# residual-GEMM epilogues: base loads regrouped to 8 rows x full 128-byte lines as well (on top of the f32 store regrouping)
# baseline (speedup 1.0000x reference)
; __device__ __forceinline__ unsigned cvt_pk_bf16(float lo, float hi) { const f32x2_t v = {lo, hi}; const bf16x2_t b = __builtin_convertvector(v, bf16x2_t); return __builtin_bit_cast(unsigned, b); }
;     __device__ __forceinline__ void operator()(const f32x4 (&acc)[2][2][4][2], const Unit& u, int wr, int wc, int fr, int fq, const PG8_LAS float*) const {
;     ...
;             for (int m = 0; m < 4; ++m) { const int row = row0 + ai * HALF + m * 16; const size_t off = (size_t)row * ldc + col0; float ss = 0.f;
; #pragma unroll
;                 for (int bj = 0; bj < 2; ++bj) {
;                     const f32x4 b0 = *(const f32x4*)(base + off + bj * HALF), b1 = *(const f32x4*)(base + off + bj * HALF + 4);
;                     const f32x4 v0 = b0 + acc[ai][bj][m][0], v1 = b1 + acc[ai][bj][m][1];
;                     *(f32x4*)(out + off + bj * HALF) = v0; *(f32x4*)(out + off + bj * HALF + 4) = v1;
;                     if (xb) { u32x4 w; w.x = cvt_pk_bf16(v0[0], v0[1]); w.y = cvt_pk_bf16(v0[2], v0[3]); w.z = cvt_pk_bf16(v1[0], v1[1]); w.w = cvt_pk_bf16(v1[2], v1[3]);
;                         *(u32x4*)(xb + off + bj * HALF) = w;
;                         ss += ((v0[0] * v0[0] + v0[1] * v0[1]) + (v0[2] * v0[2] + v0[3] * v0[3])) + ((v1[0] * v1[0] + v1[1] * v1[1]) + (v1[2] * v1[2] + v1[3] * v1[3])); } }
;                 if (xb) { ss += __shfl_xor(ss, 16); ss += __shfl_xor(ss, 32); if (fq == 0) ssq[(size_t)row * 16 + u.pn * 4 + wc] = ss; } }
.LBB0_661:
	v_lshl_add_u32 v146, s22, 8, v148
	v_lshl_or_b32 v144, s6, 8, v150
	v_ashrrev_i32_e32 v147, 31, v146
	v_ashrrev_i32_e32 v145, 31, v144
	v_lshlrev_b64 v[156:157], 10, v[146:147]
	v_lshl_add_u64 v[164:165], v[156:157], 0, v[144:145]
	v_readlane_b32 s48, v254, 3
	v_lshlrev_b64 v[168:169], 2, v[164:165]
	v_readlane_b32 s49, v254, 4
	v_readlane_b32 s22, v254, 39
	v_readlane_b32 s23, v254, 40
	v_lshl_add_u64 v[170:171], s[48:49], 0, v[168:169]
	v_lshl_add_u64 v[228:229], v[170:171], 0, v[230:231]
	v_lshl_add_u64 v[232:233], v[170:171], 0, v[244:245]
	global_load_dwordx4 v[246:249], v[228:229], off
	global_load_dwordx4 v[236:239], v[232:233], off
	v_lshl_add_u64 v[164:165], v[164:165], 1, s[22:23]
	v_lshl_add_u64 v[172:173], s[68:69], 0, v[168:169]
	v_xor_b32_e32 v155, 32, v154
	s_lshl_b32 s22, s6, 2
	s_ashr_i32 s23, s22, 31
	v_readlane_b32 s50, v254, 5
	v_readlane_b32 s51, v254, 6
	v_readlane_b32 s52, v254, 7
	v_readlane_b32 s53, v254, 8
	v_readlane_b32 s54, v254, 9
	v_readlane_b32 s55, v254, 10
	v_readlane_b32 s56, v254, 11
	v_readlane_b32 s57, v254, 12
	v_readlane_b32 s58, v254, 13
	v_readlane_b32 s59, v254, 14
	v_readlane_b32 s60, v254, 15
	v_readlane_b32 s61, v254, 16
	v_readlane_b32 s62, v254, 17
	v_readlane_b32 s63, v254, 18
	s_waitcnt vmcnt(0)
	ds_swizzle_b32 v160, v246 offset:swizzle(SWAP,8)
	ds_swizzle_b32 v161, v247 offset:swizzle(SWAP,8)
	ds_swizzle_b32 v162, v248 offset:swizzle(SWAP,8)
	ds_swizzle_b32 v163, v249 offset:swizzle(SWAP,8)
	ds_swizzle_b32 v156, v236 offset:swizzle(SWAP,8)
	ds_swizzle_b32 v157, v237 offset:swizzle(SWAP,8)
	ds_swizzle_b32 v158, v238 offset:swizzle(SWAP,8)
	ds_swizzle_b32 v159, v239 offset:swizzle(SWAP,8)
	s_waitcnt lgkmcnt(0)
	v_cndmask_b32_e64 v156, v156, v246, s[98:99]
	v_cndmask_b32_e64 v157, v157, v247, s[98:99]
	v_cndmask_b32_e64 v158, v158, v248, s[98:99]
	v_cndmask_b32_e64 v159, v159, v249, s[98:99]
	v_cndmask_b32_e64 v160, v236, v160, s[98:99]
	v_cndmask_b32_e64 v161, v237, v161, s[98:99]
	v_cndmask_b32_e64 v162, v238, v162, s[98:99]
	v_cndmask_b32_e64 v163, v239, v163, s[98:99]
	v_pk_add_f32 v[126:127], v[126:127], v[158:159]
	v_pk_add_f32 v[124:125], v[124:125], v[156:157]
	v_pk_add_f32 v[158:159], v[122:123], v[162:163]
	v_pk_add_f32 v[156:157], v[120:121], v[160:161]
	v_cvt_pk_bf16_f32 v120, v124, v125
	v_cvt_pk_bf16_f32 v121, v126, v127
	v_cvt_pk_bf16_f32 v122, v156, v157
	v_cvt_pk_bf16_f32 v123, v158, v159
	v_lshl_add_u64 v[228:229], v[172:173], 0, v[230:231]
	v_lshl_add_u64 v[232:233], v[172:173], 0, v[244:245]
	ds_swizzle_b32 v236, v156 offset:swizzle(SWAP,8)
	ds_swizzle_b32 v237, v157 offset:swizzle(SWAP,8)
	ds_swizzle_b32 v238, v158 offset:swizzle(SWAP,8)
	ds_swizzle_b32 v239, v159 offset:swizzle(SWAP,8)
	ds_swizzle_b32 v240, v124 offset:swizzle(SWAP,8)
	ds_swizzle_b32 v241, v125 offset:swizzle(SWAP,8)
	ds_swizzle_b32 v242, v126 offset:swizzle(SWAP,8)
	ds_swizzle_b32 v243, v127 offset:swizzle(SWAP,8)
	s_waitcnt lgkmcnt(0)
	v_cndmask_b32_e64 v236, v236, v124, s[98:99]
	v_cndmask_b32_e64 v237, v237, v125, s[98:99]
	v_cndmask_b32_e64 v238, v238, v126, s[98:99]
	v_cndmask_b32_e64 v239, v239, v127, s[98:99]
	v_cndmask_b32_e64 v240, v156, v240, s[98:99]
	v_cndmask_b32_e64 v241, v157, v241, s[98:99]
	v_cndmask_b32_e64 v242, v158, v242, s[98:99]
	v_cndmask_b32_e64 v243, v159, v243, s[98:99]
	global_store_dwordx4 v[228:229], v[236:239], off
	global_store_dwordx4 v[232:233], v[240:243], off
	global_store_dwordx4 v[164:165], v[120:123], off
	v_lshl_add_u64 v[228:229], v[170:171], 0, v[230:231]
	v_lshl_add_u64 v[232:233], v[170:171], 0, v[244:245]
	global_load_dwordx4 v[246:249], v[228:229], off offset:512
	global_load_dwordx4 v[236:239], v[232:233], off offset:512
	s_nop 0
	v_mul_f32_e32 v122, v125, v125
	v_mul_f32_e32 v123, v127, v127
	v_mul_f32_e32 v125, v157, v157
	v_mul_f32_e32 v127, v159, v159
	v_fmac_f32_e32 v122, v124, v124
	v_fmac_f32_e32 v123, v126, v126
	v_fmac_f32_e32 v125, v156, v156
	v_fmac_f32_e32 v127, v158, v158
	v_add_f32_e32 v122, v122, v123
	v_add_f32_e32 v123, v125, v127
	v_add_f32_e32 v126, v122, v123
	v_and_b32_e32 v121, 64, v154
	v_xor_b32_e32 v120, 16, v154
	v_add_u32_e32 v121, 64, v121
	v_cmp_lt_i32_e32 vcc, v120, v121
	s_waitcnt vmcnt(0)
	ds_swizzle_b32 v168, v246 offset:swizzle(SWAP,8)
	ds_swizzle_b32 v169, v247 offset:swizzle(SWAP,8)
	ds_swizzle_b32 v170, v248 offset:swizzle(SWAP,8)
	ds_swizzle_b32 v171, v249 offset:swizzle(SWAP,8)
	ds_swizzle_b32 v160, v236 offset:swizzle(SWAP,8)
	ds_swizzle_b32 v161, v237 offset:swizzle(SWAP,8)
	ds_swizzle_b32 v162, v238 offset:swizzle(SWAP,8)
	ds_swizzle_b32 v163, v239 offset:swizzle(SWAP,8)
	s_waitcnt lgkmcnt(0)
	v_cndmask_b32_e64 v160, v160, v246, s[98:99]
	v_cndmask_b32_e64 v161, v161, v247, s[98:99]
	v_cndmask_b32_e64 v162, v162, v248, s[98:99]
	v_cndmask_b32_e64 v163, v163, v249, s[98:99]
	v_cndmask_b32_e64 v168, v236, v168, s[98:99]
	v_cndmask_b32_e64 v169, v237, v169, s[98:99]
	v_cndmask_b32_e64 v170, v238, v170, s[98:99]
	v_cndmask_b32_e64 v171, v239, v171, s[98:99]
	v_pk_add_f32 v[118:119], v[118:119], v[162:163]
	v_pk_add_f32 v[116:117], v[116:117], v[160:161]
	s_waitcnt vmcnt(0)
; __device__ __forceinline__ unsigned cvt_pk_bf16(float lo, float hi) { const f32x2_t v = {lo, hi}; const bf16x2_t b = __builtin_convertvector(v, bf16x2_t); return __builtin_bit_cast(unsigned, b); }
;     __device__ __forceinline__ void operator()(const f32x4 (&acc)[2][2][4][2], const Unit& u, int wr, int wc, int fr, int fq, const PG8_LAS float*) const {
;     ...
;                     const f32x4 b0 = *(const f32x4*)(base + off + bj * HALF), b1 = *(const f32x4*)(base + off + bj * HALF + 4);
;                     const f32x4 v0 = b0 + acc[ai][bj][m][0], v1 = b1 + acc[ai][bj][m][1];
;                     *(f32x4*)(out + off + bj * HALF) = v0; *(f32x4*)(out + off + bj * HALF + 4) = v1;
;                     if (xb) { u32x4 w; w.x = cvt_pk_bf16(v0[0], v0[1]); w.y = cvt_pk_bf16(v0[2], v0[3]); w.z = cvt_pk_bf16(v1[0], v1[1]); w.w = cvt_pk_bf16(v1[2], v1[3]);
;                         *(u32x4*)(xb + off + bj * HALF) = w;
;                         ss += ((v0[0] * v0[0] + v0[1] * v0[1]) + (v0[2] * v0[2] + v0[3] * v0[3])) + ((v1[0] * v1[0] + v1[1] * v1[1]) + (v1[2] * v1[2] + v1[3] * v1[3])); } }
;                 if (xb) { ss += __shfl_xor(ss, 16); ss += __shfl_xor(ss, 32); if (fq == 0) ssq[(size_t)row * 16 + u.pn * 4 + wc] = ss; } }
	v_pk_add_f32 v[124:125], v[114:115], v[170:171]
	v_pk_add_f32 v[122:123], v[112:113], v[168:169]
	v_mul_f32_e32 v112, v117, v117
	v_mul_f32_e32 v113, v119, v119
	v_mul_f32_e32 v114, v123, v123
	v_mul_f32_e32 v115, v125, v125
	v_fmac_f32_e32 v112, v116, v116
	v_fmac_f32_e32 v113, v118, v118
	v_fmac_f32_e32 v114, v122, v122
	v_fmac_f32_e32 v115, v124, v124
	v_add_f32_e32 v112, v112, v113
	v_add_f32_e32 v113, v114, v115
	v_cndmask_b32_e32 v120, v154, v120, vcc
	v_add_f32_e32 v112, v112, v113
	v_lshlrev_b32_e32 v120, 2, v120
	v_add_f32_e32 v112, v126, v112
	ds_bpermute_b32 v113, v120, v112
	v_cmp_lt_i32_e32 vcc, v155, v121
	v_lshl_add_u64 v[228:229], v[172:173], 0, v[230:231]
	v_lshl_add_u64 v[232:233], v[172:173], 0, v[244:245]
	ds_swizzle_b32 v236, v122 offset:swizzle(SWAP,8)
	ds_swizzle_b32 v237, v123 offset:swizzle(SWAP,8)
	ds_swizzle_b32 v238, v124 offset:swizzle(SWAP,8)
	ds_swizzle_b32 v239, v125 offset:swizzle(SWAP,8)
	ds_swizzle_b32 v240, v116 offset:swizzle(SWAP,8)
	ds_swizzle_b32 v241, v117 offset:swizzle(SWAP,8)
	ds_swizzle_b32 v242, v118 offset:swizzle(SWAP,8)
	ds_swizzle_b32 v243, v119 offset:swizzle(SWAP,8)
	s_waitcnt lgkmcnt(0)
	v_cndmask_b32_e64 v236, v236, v116, s[98:99]
	v_cndmask_b32_e64 v237, v237, v117, s[98:99]
	v_cndmask_b32_e64 v238, v238, v118, s[98:99]
	v_cndmask_b32_e64 v239, v239, v119, s[98:99]
	v_cndmask_b32_e64 v240, v122, v240, s[98:99]
	v_cndmask_b32_e64 v241, v123, v241, s[98:99]
	v_cndmask_b32_e64 v242, v124, v242, s[98:99]
	v_cndmask_b32_e64 v243, v125, v243, s[98:99]
	global_store_dwordx4 v[228:229], v[236:239], off offset:512
	global_store_dwordx4 v[232:233], v[240:243], off offset:512
	v_cndmask_b32_e32 v114, v154, v155, vcc
	v_lshlrev_b32_e32 v114, 2, v114
	s_waitcnt lgkmcnt(0)
	v_add_f32_e32 v112, v112, v113
	ds_bpermute_b32 v113, v114, v112
	v_cvt_pk_bf16_f32 v116, v116, v117
	v_cvt_pk_bf16_f32 v117, v118, v119
	v_cvt_pk_bf16_f32 v118, v122, v123
	v_cvt_pk_bf16_f32 v119, v124, v125
	global_store_dwordx4 v[164:165], v[116:119], off offset:256
	s_and_saveexec_b64 s[24:25], s[2:3]
	s_cbranch_execz .LBB0_663
	v_readlane_b32 s26, v254, 41
	s_waitcnt lgkmcnt(0)
	v_add_f32_e32 v115, v112, v113
	v_lshlrev_b64 v[112:113], 6, v[146:147]
	v_readlane_b32 s27, v254, 42
	s_lshl_b32 s6, s38, 2
	s_nop 0
	v_lshl_add_u64 v[112:113], s[26:27], 0, v[112:113]
	v_lshl_add_u64 v[112:113], s[22:23], 2, v[112:113]
	v_lshl_add_u64 v[112:113], v[112:113], 0, s[6:7]
	global_store_dword v[112:113], v115, off
.LBB0_663:
	s_or_b64 exec, exec, s[24:25]
	v_or_b32_e32 v112, 16, v146
	s_waitcnt lgkmcnt(0)
	v_ashrrev_i32_e32 v113, 31, v112
	v_lshlrev_b64 v[116:117], 10, v[112:113]
	v_lshl_add_u64 v[126:127], v[116:117], 0, v[144:145]
	v_readlane_b32 s48, v254, 3
	v_lshlrev_b64 v[156:157], 2, v[126:127]
	v_readlane_b32 s49, v254, 4
	v_readlane_b32 s24, v254, 39
	v_readlane_b32 s25, v254, 40
	v_lshl_add_u64 v[158:159], s[48:49], 0, v[156:157]
	v_lshl_add_u64 v[228:229], v[158:159], 0, v[230:231]
	v_lshl_add_u64 v[232:233], v[158:159], 0, v[244:245]
	global_load_dwordx4 v[246:249], v[228:229], off
	global_load_dwordx4 v[236:239], v[232:233], off
	v_lshl_add_u64 v[126:127], v[126:127], 1, s[24:25]
	v_lshl_add_u64 v[156:157], s[68:69], 0, v[156:157]
	v_readlane_b32 s50, v254, 5
	v_readlane_b32 s51, v254, 6
	v_readlane_b32 s52, v254, 7
	v_readlane_b32 s53, v254, 8
	v_readlane_b32 s54, v254, 9
	v_readlane_b32 s55, v254, 10
	v_readlane_b32 s56, v254, 11
	v_readlane_b32 s57, v254, 12
	v_readlane_b32 s58, v254, 13
	v_readlane_b32 s59, v254, 14
	v_readlane_b32 s60, v254, 15
	v_readlane_b32 s61, v254, 16
	v_readlane_b32 s62, v254, 17
	v_readlane_b32 s63, v254, 18
	s_waitcnt vmcnt(0)
	ds_swizzle_b32 v122, v246 offset:swizzle(SWAP,8)
	ds_swizzle_b32 v123, v247 offset:swizzle(SWAP,8)
	ds_swizzle_b32 v124, v248 offset:swizzle(SWAP,8)
	ds_swizzle_b32 v125, v249 offset:swizzle(SWAP,8)
	ds_swizzle_b32 v116, v236 offset:swizzle(SWAP,8)
	ds_swizzle_b32 v117, v237 offset:swizzle(SWAP,8)
	ds_swizzle_b32 v118, v238 offset:swizzle(SWAP,8)
	ds_swizzle_b32 v119, v239 offset:swizzle(SWAP,8)
	s_waitcnt lgkmcnt(0)
	v_cndmask_b32_e64 v116, v116, v246, s[98:99]
	v_cndmask_b32_e64 v117, v117, v247, s[98:99]
	v_cndmask_b32_e64 v118, v118, v248, s[98:99]
	v_cndmask_b32_e64 v119, v119, v249, s[98:99]
	v_cndmask_b32_e64 v122, v236, v122, s[98:99]
	v_cndmask_b32_e64 v123, v237, v123, s[98:99]
	v_cndmask_b32_e64 v124, v238, v124, s[98:99]
	v_cndmask_b32_e64 v125, v239, v125, s[98:99]
	v_pk_add_f32 v[110:111], v[110:111], v[118:119]
	v_pk_add_f32 v[108:109], v[108:109], v[116:117]
	s_waitcnt vmcnt(0)
	v_pk_add_f32 v[106:107], v[106:107], v[124:125]
	v_pk_add_f32 v[104:105], v[104:105], v[122:123]
	v_cvt_pk_bf16_f32 v116, v108, v109
	v_cvt_pk_bf16_f32 v117, v110, v111
	v_cvt_pk_bf16_f32 v118, v104, v105
	v_cvt_pk_bf16_f32 v119, v106, v107
	v_lshl_add_u64 v[228:229], v[156:157], 0, v[230:231]
	v_lshl_add_u64 v[232:233], v[156:157], 0, v[244:245]
	ds_swizzle_b32 v236, v104 offset:swizzle(SWAP,8)
	ds_swizzle_b32 v237, v105 offset:swizzle(SWAP,8)
	ds_swizzle_b32 v238, v106 offset:swizzle(SWAP,8)
	ds_swizzle_b32 v239, v107 offset:swizzle(SWAP,8)
	ds_swizzle_b32 v240, v108 offset:swizzle(SWAP,8)
	ds_swizzle_b32 v241, v109 offset:swizzle(SWAP,8)
	ds_swizzle_b32 v242, v110 offset:swizzle(SWAP,8)
	ds_swizzle_b32 v243, v111 offset:swizzle(SWAP,8)
	s_waitcnt lgkmcnt(0)
; __device__ __forceinline__ unsigned cvt_pk_bf16(float lo, float hi) { const f32x2_t v = {lo, hi}; const bf16x2_t b = __builtin_convertvector(v, bf16x2_t); return __builtin_bit_cast(unsigned, b); }
;     __device__ __forceinline__ void operator()(const f32x4 (&acc)[2][2][4][2], const Unit& u, int wr, int wc, int fr, int fq, const PG8_LAS float*) const {
;     ...
;                     const f32x4 b0 = *(const f32x4*)(base + off + bj * HALF), b1 = *(const f32x4*)(base + off + bj * HALF + 4);
;                     const f32x4 v0 = b0 + acc[ai][bj][m][0], v1 = b1 + acc[ai][bj][m][1];
;                     *(f32x4*)(out + off + bj * HALF) = v0; *(f32x4*)(out + off + bj * HALF + 4) = v1;
;                     if (xb) { u32x4 w; w.x = cvt_pk_bf16(v0[0], v0[1]); w.y = cvt_pk_bf16(v0[2], v0[3]); w.z = cvt_pk_bf16(v1[0], v1[1]); w.w = cvt_pk_bf16(v1[2], v1[3]);
;                         *(u32x4*)(xb + off + bj * HALF) = w;
;                         ss += ((v0[0] * v0[0] + v0[1] * v0[1]) + (v0[2] * v0[2] + v0[3] * v0[3])) + ((v1[0] * v1[0] + v1[1] * v1[1]) + (v1[2] * v1[2] + v1[3] * v1[3])); } }
;                 if (xb) { ss += __shfl_xor(ss, 16); ss += __shfl_xor(ss, 32); if (fq == 0) ssq[(size_t)row * 16 + u.pn * 4 + wc] = ss; } }
	v_cndmask_b32_e64 v236, v236, v108, s[98:99]
	v_cndmask_b32_e64 v237, v237, v109, s[98:99]
	v_cndmask_b32_e64 v238, v238, v110, s[98:99]
	v_cndmask_b32_e64 v239, v239, v111, s[98:99]
	v_cndmask_b32_e64 v240, v104, v240, s[98:99]
	v_cndmask_b32_e64 v241, v105, v241, s[98:99]
	v_cndmask_b32_e64 v242, v106, v242, s[98:99]
	v_cndmask_b32_e64 v243, v107, v243, s[98:99]
	global_store_dwordx4 v[228:229], v[236:239], off
	global_store_dwordx4 v[232:233], v[240:243], off
	global_store_dwordx4 v[126:127], v[116:119], off
	v_lshl_add_u64 v[228:229], v[158:159], 0, v[230:231]
	v_lshl_add_u64 v[232:233], v[158:159], 0, v[244:245]
	global_load_dwordx4 v[246:249], v[228:229], off offset:512
	global_load_dwordx4 v[236:239], v[232:233], off offset:512
	s_nop 0
	v_mul_f32_e32 v109, v109, v109
	v_mul_f32_e32 v111, v111, v111
	v_mul_f32_e32 v105, v105, v105
	v_mul_f32_e32 v107, v107, v107
	v_fmac_f32_e32 v109, v108, v108
	v_fmac_f32_e32 v111, v110, v110
	v_fmac_f32_e32 v105, v104, v104
	v_fmac_f32_e32 v107, v106, v106
	v_add_f32_e32 v104, v109, v111
	v_add_f32_e32 v105, v105, v107
	v_add_f32_e32 v108, v104, v105
	s_waitcnt vmcnt(0)
	ds_swizzle_b32 v122, v246 offset:swizzle(SWAP,8)
	ds_swizzle_b32 v123, v247 offset:swizzle(SWAP,8)
	ds_swizzle_b32 v124, v248 offset:swizzle(SWAP,8)
	ds_swizzle_b32 v125, v249 offset:swizzle(SWAP,8)
	ds_swizzle_b32 v116, v236 offset:swizzle(SWAP,8)
	ds_swizzle_b32 v117, v237 offset:swizzle(SWAP,8)
	ds_swizzle_b32 v118, v238 offset:swizzle(SWAP,8)
	ds_swizzle_b32 v119, v239 offset:swizzle(SWAP,8)
	s_waitcnt lgkmcnt(0)
	v_cndmask_b32_e64 v116, v116, v246, s[98:99]
	v_cndmask_b32_e64 v117, v117, v247, s[98:99]
	v_cndmask_b32_e64 v118, v118, v248, s[98:99]
	v_cndmask_b32_e64 v119, v119, v249, s[98:99]
	v_cndmask_b32_e64 v122, v236, v122, s[98:99]
	v_cndmask_b32_e64 v123, v237, v123, s[98:99]
	v_cndmask_b32_e64 v124, v238, v124, s[98:99]
	v_cndmask_b32_e64 v125, v239, v125, s[98:99]
	v_pk_add_f32 v[102:103], v[102:103], v[118:119]
	v_pk_add_f32 v[100:101], v[100:101], v[116:117]
	s_waitcnt vmcnt(0)
	v_pk_add_f32 v[106:107], v[98:99], v[124:125]
	v_pk_add_f32 v[104:105], v[96:97], v[122:123]
	v_mul_f32_e32 v96, v101, v101
	v_mul_f32_e32 v97, v103, v103
	v_mul_f32_e32 v98, v105, v105
	v_mul_f32_e32 v99, v107, v107
	v_fmac_f32_e32 v96, v100, v100
	v_fmac_f32_e32 v97, v102, v102
	v_fmac_f32_e32 v98, v104, v104
	v_fmac_f32_e32 v99, v106, v106
	v_add_f32_e32 v96, v96, v97
	v_add_f32_e32 v97, v98, v99
	v_add_f32_e32 v96, v96, v97
	v_add_f32_e32 v96, v108, v96
	ds_bpermute_b32 v97, v120, v96
	v_lshl_add_u64 v[228:229], v[156:157], 0, v[230:231]
	v_lshl_add_u64 v[232:233], v[156:157], 0, v[244:245]
	ds_swizzle_b32 v236, v104 offset:swizzle(SWAP,8)
	ds_swizzle_b32 v237, v105 offset:swizzle(SWAP,8)
	ds_swizzle_b32 v238, v106 offset:swizzle(SWAP,8)
	ds_swizzle_b32 v239, v107 offset:swizzle(SWAP,8)
	ds_swizzle_b32 v240, v100 offset:swizzle(SWAP,8)
	ds_swizzle_b32 v241, v101 offset:swizzle(SWAP,8)
	ds_swizzle_b32 v242, v102 offset:swizzle(SWAP,8)
	ds_swizzle_b32 v243, v103 offset:swizzle(SWAP,8)
	s_waitcnt lgkmcnt(0)
	v_cndmask_b32_e64 v236, v236, v100, s[98:99]
	v_cndmask_b32_e64 v237, v237, v101, s[98:99]
	v_cndmask_b32_e64 v238, v238, v102, s[98:99]
	v_cndmask_b32_e64 v239, v239, v103, s[98:99]
	v_cndmask_b32_e64 v240, v104, v240, s[98:99]
	v_cndmask_b32_e64 v241, v105, v241, s[98:99]
	v_cndmask_b32_e64 v242, v106, v242, s[98:99]
	v_cndmask_b32_e64 v243, v107, v243, s[98:99]
	global_store_dwordx4 v[228:229], v[236:239], off offset:512
	global_store_dwordx4 v[232:233], v[240:243], off offset:512
	v_cvt_pk_bf16_f32 v98, v100, v101
	v_cvt_pk_bf16_f32 v99, v102, v103
	v_cvt_pk_bf16_f32 v100, v104, v105
	s_waitcnt lgkmcnt(0)
	v_add_f32_e32 v96, v96, v97
	ds_bpermute_b32 v97, v114, v96
	v_cvt_pk_bf16_f32 v101, v106, v107
	global_store_dwordx4 v[126:127], v[98:101], off offset:256
	s_and_saveexec_b64 s[24:25], s[2:3]
	s_cbranch_execz .LBB0_665
	v_readlane_b32 s26, v254, 41
	s_waitcnt lgkmcnt(0)
	v_add_f32_e32 v98, v96, v97
	v_lshlrev_b64 v[96:97], 6, v[112:113]
	v_readlane_b32 s27, v254, 42
	s_lshl_b32 s6, s38, 2
	s_nop 0
	v_lshl_add_u64 v[96:97], s[26:27], 0, v[96:97]
	v_lshl_add_u64 v[96:97], s[22:23], 2, v[96:97]
	v_lshl_add_u64 v[96:97], v[96:97], 0, s[6:7]
	global_store_dword v[96:97], v98, off
; __device__ __forceinline__ unsigned cvt_pk_bf16(float lo, float hi) { const f32x2_t v = {lo, hi}; const bf16x2_t b = __builtin_convertvector(v, bf16x2_t); return __builtin_bit_cast(unsigned, b); }
;     __device__ __forceinline__ void operator()(const f32x4 (&acc)[2][2][4][2], const Unit& u, int wr, int wc, int fr, int fq, const PG8_LAS float*) const {
;     ...
;             for (int m = 0; m < 4; ++m) { const int row = row0 + ai * HALF + m * 16; const size_t off = (size_t)row * ldc + col0; float ss = 0.f;
; #pragma unroll
;                 for (int bj = 0; bj < 2; ++bj) {
;                     const f32x4 b0 = *(const f32x4*)(base + off + bj * HALF), b1 = *(const f32x4*)(base + off + bj * HALF + 4);
;                     const f32x4 v0 = b0 + acc[ai][bj][m][0], v1 = b1 + acc[ai][bj][m][1];
;                     *(f32x4*)(out + off + bj * HALF) = v0; *(f32x4*)(out + off + bj * HALF + 4) = v1;
;                     if (xb) { u32x4 w; w.x = cvt_pk_bf16(v0[0], v0[1]); w.y = cvt_pk_bf16(v0[2], v0[3]); w.z = cvt_pk_bf16(v1[0], v1[1]); w.w = cvt_pk_bf16(v1[2], v1[3]);
;                         *(u32x4*)(xb + off + bj * HALF) = w;
;                         ss += ((v0[0] * v0[0] + v0[1] * v0[1]) + (v0[2] * v0[2] + v0[3] * v0[3])) + ((v1[0] * v1[0] + v1[1] * v1[1]) + (v1[2] * v1[2] + v1[3] * v1[3])); } }
;                 if (xb) { ss += __shfl_xor(ss, 16); ss += __shfl_xor(ss, 32); if (fq == 0) ssq[(size_t)row * 16 + u.pn * 4 + wc] = ss; } }
.LBB0_665:
	s_or_b64 exec, exec, s[24:25]
	v_or_b32_e32 v96, 32, v146
	s_waitcnt lgkmcnt(0)
	v_ashrrev_i32_e32 v97, 31, v96
	v_lshlrev_b64 v[98:99], 10, v[96:97]
	v_lshl_add_u64 v[106:107], v[98:99], 0, v[144:145]
	v_readlane_b32 s48, v254, 3
	v_lshlrev_b64 v[108:109], 2, v[106:107]
	v_readlane_b32 s49, v254, 4
	v_readlane_b32 s24, v254, 39
	v_readlane_b32 s25, v254, 40
	v_lshl_add_u64 v[110:111], s[48:49], 0, v[108:109]
	v_lshl_add_u64 v[228:229], v[110:111], 0, v[230:231]
	v_lshl_add_u64 v[232:233], v[110:111], 0, v[244:245]
	global_load_dwordx4 v[246:249], v[228:229], off
	global_load_dwordx4 v[236:239], v[232:233], off
	v_lshl_add_u64 v[106:107], v[106:107], 1, s[24:25]
	v_lshl_add_u64 v[108:109], s[68:69], 0, v[108:109]
	v_readlane_b32 s50, v254, 5
	v_readlane_b32 s51, v254, 6
	v_readlane_b32 s52, v254, 7
	v_readlane_b32 s53, v254, 8
	v_readlane_b32 s54, v254, 9
	v_readlane_b32 s55, v254, 10
	v_readlane_b32 s56, v254, 11
	v_readlane_b32 s57, v254, 12
	v_readlane_b32 s58, v254, 13
	v_readlane_b32 s59, v254, 14
	v_readlane_b32 s60, v254, 15
	v_readlane_b32 s61, v254, 16
	v_readlane_b32 s62, v254, 17
	v_readlane_b32 s63, v254, 18
	s_waitcnt vmcnt(0)
	ds_swizzle_b32 v102, v246 offset:swizzle(SWAP,8)
	ds_swizzle_b32 v103, v247 offset:swizzle(SWAP,8)
	ds_swizzle_b32 v104, v248 offset:swizzle(SWAP,8)
	ds_swizzle_b32 v105, v249 offset:swizzle(SWAP,8)
	ds_swizzle_b32 v98, v236 offset:swizzle(SWAP,8)
	ds_swizzle_b32 v99, v237 offset:swizzle(SWAP,8)
	ds_swizzle_b32 v100, v238 offset:swizzle(SWAP,8)
	ds_swizzle_b32 v101, v239 offset:swizzle(SWAP,8)
	s_waitcnt lgkmcnt(0)
	v_cndmask_b32_e64 v98, v98, v246, s[98:99]
	v_cndmask_b32_e64 v99, v99, v247, s[98:99]
	v_cndmask_b32_e64 v100, v100, v248, s[98:99]
	v_cndmask_b32_e64 v101, v101, v249, s[98:99]
	v_cndmask_b32_e64 v102, v236, v102, s[98:99]
	v_cndmask_b32_e64 v103, v237, v103, s[98:99]
	v_cndmask_b32_e64 v104, v238, v104, s[98:99]
	v_cndmask_b32_e64 v105, v239, v105, s[98:99]
	v_pk_add_f32 v[94:95], v[94:95], v[100:101]
	v_pk_add_f32 v[92:93], v[92:93], v[98:99]
	s_waitcnt vmcnt(0)
	v_pk_add_f32 v[90:91], v[90:91], v[104:105]
	v_pk_add_f32 v[88:89], v[88:89], v[102:103]
	v_cvt_pk_bf16_f32 v98, v92, v93
	v_cvt_pk_bf16_f32 v99, v94, v95
	v_cvt_pk_bf16_f32 v100, v88, v89
	v_cvt_pk_bf16_f32 v101, v90, v91
	v_lshl_add_u64 v[228:229], v[108:109], 0, v[230:231]
	v_lshl_add_u64 v[232:233], v[108:109], 0, v[244:245]
	ds_swizzle_b32 v236, v88 offset:swizzle(SWAP,8)
	ds_swizzle_b32 v237, v89 offset:swizzle(SWAP,8)
	ds_swizzle_b32 v238, v90 offset:swizzle(SWAP,8)
	ds_swizzle_b32 v239, v91 offset:swizzle(SWAP,8)
	ds_swizzle_b32 v240, v92 offset:swizzle(SWAP,8)
	ds_swizzle_b32 v241, v93 offset:swizzle(SWAP,8)
	ds_swizzle_b32 v242, v94 offset:swizzle(SWAP,8)
	ds_swizzle_b32 v243, v95 offset:swizzle(SWAP,8)
	s_waitcnt lgkmcnt(0)
	v_cndmask_b32_e64 v236, v236, v92, s[98:99]
	v_cndmask_b32_e64 v237, v237, v93, s[98:99]
	v_cndmask_b32_e64 v238, v238, v94, s[98:99]
	v_cndmask_b32_e64 v239, v239, v95, s[98:99]
	v_cndmask_b32_e64 v240, v88, v240, s[98:99]
	v_cndmask_b32_e64 v241, v89, v241, s[98:99]
	v_cndmask_b32_e64 v242, v90, v242, s[98:99]
	v_cndmask_b32_e64 v243, v91, v243, s[98:99]
	global_store_dwordx4 v[228:229], v[236:239], off
	global_store_dwordx4 v[232:233], v[240:243], off
	global_store_dwordx4 v[106:107], v[98:101], off
	v_lshl_add_u64 v[228:229], v[110:111], 0, v[230:231]
	v_lshl_add_u64 v[232:233], v[110:111], 0, v[244:245]
	global_load_dwordx4 v[246:249], v[228:229], off offset:512
	global_load_dwordx4 v[236:239], v[232:233], off offset:512
	s_nop 0
	v_mul_f32_e32 v93, v93, v93
	v_mul_f32_e32 v95, v95, v95
	v_mul_f32_e32 v89, v89, v89
	v_mul_f32_e32 v91, v91, v91
	v_fmac_f32_e32 v93, v92, v92
	v_fmac_f32_e32 v95, v94, v94
	v_fmac_f32_e32 v89, v88, v88
	v_fmac_f32_e32 v91, v90, v90
	v_add_f32_e32 v88, v93, v95
	v_add_f32_e32 v89, v89, v91
	v_add_f32_e32 v92, v88, v89
	s_waitcnt vmcnt(0)
	ds_swizzle_b32 v102, v246 offset:swizzle(SWAP,8)
	ds_swizzle_b32 v103, v247 offset:swizzle(SWAP,8)
	ds_swizzle_b32 v104, v248 offset:swizzle(SWAP,8)
	ds_swizzle_b32 v105, v249 offset:swizzle(SWAP,8)
	ds_swizzle_b32 v98, v236 offset:swizzle(SWAP,8)
	ds_swizzle_b32 v99, v237 offset:swizzle(SWAP,8)
	ds_swizzle_b32 v100, v238 offset:swizzle(SWAP,8)
	ds_swizzle_b32 v101, v239 offset:swizzle(SWAP,8)
	s_waitcnt lgkmcnt(0)
	v_cndmask_b32_e64 v98, v98, v246, s[98:99]
	v_cndmask_b32_e64 v99, v99, v247, s[98:99]
	v_cndmask_b32_e64 v100, v100, v248, s[98:99]
	v_cndmask_b32_e64 v101, v101, v249, s[98:99]
	v_cndmask_b32_e64 v102, v236, v102, s[98:99]
	v_cndmask_b32_e64 v103, v237, v103, s[98:99]
	v_cndmask_b32_e64 v104, v238, v104, s[98:99]
	v_cndmask_b32_e64 v105, v239, v105, s[98:99]
	v_pk_add_f32 v[86:87], v[86:87], v[100:101]
	v_pk_add_f32 v[84:85], v[84:85], v[98:99]
	s_waitcnt vmcnt(0)
	v_pk_add_f32 v[90:91], v[82:83], v[104:105]
	v_pk_add_f32 v[88:89], v[80:81], v[102:103]
	v_mul_f32_e32 v80, v85, v85
	v_mul_f32_e32 v81, v87, v87
	v_mul_f32_e32 v82, v89, v89
	v_mul_f32_e32 v83, v91, v91
	v_fmac_f32_e32 v80, v84, v84
	v_fmac_f32_e32 v81, v86, v86
	v_fmac_f32_e32 v82, v88, v88
	v_fmac_f32_e32 v83, v90, v90
	v_add_f32_e32 v80, v80, v81
	v_add_f32_e32 v81, v82, v83
	v_add_f32_e32 v80, v80, v81
	v_add_f32_e32 v80, v92, v80
	ds_bpermute_b32 v81, v120, v80
	v_lshl_add_u64 v[228:229], v[108:109], 0, v[230:231]
	v_lshl_add_u64 v[232:233], v[108:109], 0, v[244:245]
	ds_swizzle_b32 v236, v88 offset:swizzle(SWAP,8)
	ds_swizzle_b32 v237, v89 offset:swizzle(SWAP,8)
	ds_swizzle_b32 v238, v90 offset:swizzle(SWAP,8)
	ds_swizzle_b32 v239, v91 offset:swizzle(SWAP,8)
	ds_swizzle_b32 v240, v84 offset:swizzle(SWAP,8)
	ds_swizzle_b32 v241, v85 offset:swizzle(SWAP,8)
	ds_swizzle_b32 v242, v86 offset:swizzle(SWAP,8)
	ds_swizzle_b32 v243, v87 offset:swizzle(SWAP,8)
	s_waitcnt lgkmcnt(0)
	v_cndmask_b32_e64 v236, v236, v84, s[98:99]
	v_cndmask_b32_e64 v237, v237, v85, s[98:99]
	v_cndmask_b32_e64 v238, v238, v86, s[98:99]
	v_cndmask_b32_e64 v239, v239, v87, s[98:99]
	v_cndmask_b32_e64 v240, v88, v240, s[98:99]
	v_cndmask_b32_e64 v241, v89, v241, s[98:99]
	v_cndmask_b32_e64 v242, v90, v242, s[98:99]
	v_cndmask_b32_e64 v243, v91, v243, s[98:99]
	global_store_dwordx4 v[228:229], v[236:239], off offset:512
	global_store_dwordx4 v[232:233], v[240:243], off offset:512
	v_cvt_pk_bf16_f32 v82, v84, v85
	v_cvt_pk_bf16_f32 v83, v86, v87
	v_cvt_pk_bf16_f32 v84, v88, v89
	s_waitcnt lgkmcnt(0)
	v_add_f32_e32 v80, v80, v81
	ds_bpermute_b32 v81, v114, v80
	v_cvt_pk_bf16_f32 v85, v90, v91
	global_store_dwordx4 v[106:107], v[82:85], off offset:256
	s_and_saveexec_b64 s[24:25], s[2:3]
	s_cbranch_execz .LBB0_667
	v_readlane_b32 s26, v254, 41
	s_waitcnt lgkmcnt(0)
	v_add_f32_e32 v82, v80, v81
	v_lshlrev_b64 v[80:81], 6, v[96:97]
	v_readlane_b32 s27, v254, 42
	s_lshl_b32 s6, s38, 2
	s_nop 0
	v_lshl_add_u64 v[80:81], s[26:27], 0, v[80:81]
	v_lshl_add_u64 v[80:81], s[22:23], 2, v[80:81]
	v_lshl_add_u64 v[80:81], v[80:81], 0, s[6:7]
	global_store_dword v[80:81], v82, off
; __device__ __forceinline__ unsigned cvt_pk_bf16(float lo, float hi) { const f32x2_t v = {lo, hi}; const bf16x2_t b = __builtin_convertvector(v, bf16x2_t); return __builtin_bit_cast(unsigned, b); }
;     __device__ __forceinline__ void operator()(const f32x4 (&acc)[2][2][4][2], const Unit& u, int wr, int wc, int fr, int fq, const PG8_LAS float*) const {
;     ...
;             for (int m = 0; m < 4; ++m) { const int row = row0 + ai * HALF + m * 16; const size_t off = (size_t)row * ldc + col0; float ss = 0.f;
; #pragma unroll
;                 for (int bj = 0; bj < 2; ++bj) {
;                     const f32x4 b0 = *(const f32x4*)(base + off + bj * HALF), b1 = *(const f32x4*)(base + off + bj * HALF + 4);
;                     const f32x4 v0 = b0 + acc[ai][bj][m][0], v1 = b1 + acc[ai][bj][m][1];
;                     *(f32x4*)(out + off + bj * HALF) = v0; *(f32x4*)(out + off + bj * HALF + 4) = v1;
;                     if (xb) { u32x4 w; w.x = cvt_pk_bf16(v0[0], v0[1]); w.y = cvt_pk_bf16(v0[2], v0[3]); w.z = cvt_pk_bf16(v1[0], v1[1]); w.w = cvt_pk_bf16(v1[2], v1[3]);
;                         *(u32x4*)(xb + off + bj * HALF) = w;
;                         ss += ((v0[0] * v0[0] + v0[1] * v0[1]) + (v0[2] * v0[2] + v0[3] * v0[3])) + ((v1[0] * v1[0] + v1[1] * v1[1]) + (v1[2] * v1[2] + v1[3] * v1[3])); } }
;                 if (xb) { ss += __shfl_xor(ss, 16); ss += __shfl_xor(ss, 32); if (fq == 0) ssq[(size_t)row * 16 + u.pn * 4 + wc] = ss; } }
.LBB0_667:
	s_or_b64 exec, exec, s[24:25]
	v_or_b32_e32 v80, 48, v146
	s_waitcnt lgkmcnt(0)
	v_ashrrev_i32_e32 v81, 31, v80
	v_lshlrev_b64 v[82:83], 10, v[80:81]
	v_lshl_add_u64 v[90:91], v[82:83], 0, v[144:145]
	v_readlane_b32 s48, v254, 3
	v_lshlrev_b64 v[92:93], 2, v[90:91]
	v_readlane_b32 s49, v254, 4
	v_readlane_b32 s24, v254, 39
	v_readlane_b32 s25, v254, 40
	v_lshl_add_u64 v[94:95], s[48:49], 0, v[92:93]
	v_lshl_add_u64 v[228:229], v[94:95], 0, v[230:231]
	v_lshl_add_u64 v[232:233], v[94:95], 0, v[244:245]
	global_load_dwordx4 v[246:249], v[228:229], off
	global_load_dwordx4 v[236:239], v[232:233], off
	v_lshl_add_u64 v[90:91], v[90:91], 1, s[24:25]
	v_lshl_add_u64 v[92:93], s[68:69], 0, v[92:93]
	v_readlane_b32 s50, v254, 5
	v_readlane_b32 s51, v254, 6
	v_readlane_b32 s52, v254, 7
	v_readlane_b32 s53, v254, 8
	v_readlane_b32 s54, v254, 9
	v_readlane_b32 s55, v254, 10
	v_readlane_b32 s56, v254, 11
	v_readlane_b32 s57, v254, 12
	v_readlane_b32 s58, v254, 13
	v_readlane_b32 s59, v254, 14
	v_readlane_b32 s60, v254, 15
	v_readlane_b32 s61, v254, 16
	v_readlane_b32 s62, v254, 17
	v_readlane_b32 s63, v254, 18
	s_waitcnt vmcnt(0)
	ds_swizzle_b32 v86, v246 offset:swizzle(SWAP,8)
	ds_swizzle_b32 v87, v247 offset:swizzle(SWAP,8)
	ds_swizzle_b32 v88, v248 offset:swizzle(SWAP,8)
	ds_swizzle_b32 v89, v249 offset:swizzle(SWAP,8)
	ds_swizzle_b32 v82, v236 offset:swizzle(SWAP,8)
	ds_swizzle_b32 v83, v237 offset:swizzle(SWAP,8)
	ds_swizzle_b32 v84, v238 offset:swizzle(SWAP,8)
	ds_swizzle_b32 v85, v239 offset:swizzle(SWAP,8)
	s_waitcnt lgkmcnt(0)
	v_cndmask_b32_e64 v82, v82, v246, s[98:99]
	v_cndmask_b32_e64 v83, v83, v247, s[98:99]
	v_cndmask_b32_e64 v84, v84, v248, s[98:99]
	v_cndmask_b32_e64 v85, v85, v249, s[98:99]
	v_cndmask_b32_e64 v86, v236, v86, s[98:99]
	v_cndmask_b32_e64 v87, v237, v87, s[98:99]
	v_cndmask_b32_e64 v88, v238, v88, s[98:99]
	v_cndmask_b32_e64 v89, v239, v89, s[98:99]
	v_pk_add_f32 v[78:79], v[78:79], v[84:85]
	v_pk_add_f32 v[76:77], v[76:77], v[82:83]
	s_waitcnt vmcnt(0)
	v_pk_add_f32 v[74:75], v[74:75], v[88:89]
	v_pk_add_f32 v[72:73], v[72:73], v[86:87]
	v_cvt_pk_bf16_f32 v82, v76, v77
	v_cvt_pk_bf16_f32 v83, v78, v79
	v_cvt_pk_bf16_f32 v84, v72, v73
	v_cvt_pk_bf16_f32 v85, v74, v75
	v_lshl_add_u64 v[228:229], v[92:93], 0, v[230:231]
	v_lshl_add_u64 v[232:233], v[92:93], 0, v[244:245]
	ds_swizzle_b32 v236, v72 offset:swizzle(SWAP,8)
	ds_swizzle_b32 v237, v73 offset:swizzle(SWAP,8)
	ds_swizzle_b32 v238, v74 offset:swizzle(SWAP,8)
	ds_swizzle_b32 v239, v75 offset:swizzle(SWAP,8)
	ds_swizzle_b32 v240, v76 offset:swizzle(SWAP,8)
	ds_swizzle_b32 v241, v77 offset:swizzle(SWAP,8)
	ds_swizzle_b32 v242, v78 offset:swizzle(SWAP,8)
	ds_swizzle_b32 v243, v79 offset:swizzle(SWAP,8)
	s_waitcnt lgkmcnt(0)
	v_cndmask_b32_e64 v236, v236, v76, s[98:99]
	v_cndmask_b32_e64 v237, v237, v77, s[98:99]
	v_cndmask_b32_e64 v238, v238, v78, s[98:99]
	v_cndmask_b32_e64 v239, v239, v79, s[98:99]
	v_cndmask_b32_e64 v240, v72, v240, s[98:99]
	v_cndmask_b32_e64 v241, v73, v241, s[98:99]
	v_cndmask_b32_e64 v242, v74, v242, s[98:99]
	v_cndmask_b32_e64 v243, v75, v243, s[98:99]
	global_store_dwordx4 v[228:229], v[236:239], off
	global_store_dwordx4 v[232:233], v[240:243], off
	global_store_dwordx4 v[90:91], v[82:85], off
	v_lshl_add_u64 v[228:229], v[94:95], 0, v[230:231]
	v_lshl_add_u64 v[232:233], v[94:95], 0, v[244:245]
	global_load_dwordx4 v[246:249], v[228:229], off offset:512
	global_load_dwordx4 v[236:239], v[232:233], off offset:512
	s_nop 0
	v_mul_f32_e32 v77, v77, v77
	v_mul_f32_e32 v79, v79, v79
	v_mul_f32_e32 v73, v73, v73
	v_mul_f32_e32 v75, v75, v75
	v_fmac_f32_e32 v77, v76, v76
	v_fmac_f32_e32 v79, v78, v78
	v_fmac_f32_e32 v73, v72, v72
	v_fmac_f32_e32 v75, v74, v74
	v_add_f32_e32 v72, v77, v79
	v_add_f32_e32 v73, v73, v75
	v_add_f32_e32 v76, v72, v73
	s_waitcnt vmcnt(0)
	ds_swizzle_b32 v86, v246 offset:swizzle(SWAP,8)
	ds_swizzle_b32 v87, v247 offset:swizzle(SWAP,8)
	ds_swizzle_b32 v88, v248 offset:swizzle(SWAP,8)
	ds_swizzle_b32 v89, v249 offset:swizzle(SWAP,8)
	ds_swizzle_b32 v82, v236 offset:swizzle(SWAP,8)
	ds_swizzle_b32 v83, v237 offset:swizzle(SWAP,8)
	ds_swizzle_b32 v84, v238 offset:swizzle(SWAP,8)
	ds_swizzle_b32 v85, v239 offset:swizzle(SWAP,8)
	s_waitcnt lgkmcnt(0)
	v_cndmask_b32_e64 v82, v82, v246, s[98:99]
	v_cndmask_b32_e64 v83, v83, v247, s[98:99]
	v_cndmask_b32_e64 v84, v84, v248, s[98:99]
	v_cndmask_b32_e64 v85, v85, v249, s[98:99]
	v_cndmask_b32_e64 v86, v236, v86, s[98:99]
	v_cndmask_b32_e64 v87, v237, v87, s[98:99]
	v_cndmask_b32_e64 v88, v238, v88, s[98:99]
	v_cndmask_b32_e64 v89, v239, v89, s[98:99]
	v_pk_add_f32 v[70:71], v[70:71], v[84:85]
	v_pk_add_f32 v[68:69], v[68:69], v[82:83]
	s_waitcnt vmcnt(0)
	v_pk_add_f32 v[74:75], v[66:67], v[88:89]
	v_pk_add_f32 v[72:73], v[64:65], v[86:87]
	v_mul_f32_e32 v64, v69, v69
	v_mul_f32_e32 v65, v71, v71
	v_mul_f32_e32 v66, v73, v73
	v_mul_f32_e32 v67, v75, v75
	v_fmac_f32_e32 v64, v68, v68
	v_fmac_f32_e32 v65, v70, v70
	v_fmac_f32_e32 v66, v72, v72
	v_fmac_f32_e32 v67, v74, v74
	v_add_f32_e32 v64, v64, v65
	v_add_f32_e32 v65, v66, v67
	v_add_f32_e32 v64, v64, v65
	v_add_f32_e32 v64, v76, v64
	ds_bpermute_b32 v65, v120, v64
	v_lshl_add_u64 v[228:229], v[92:93], 0, v[230:231]
	v_lshl_add_u64 v[232:233], v[92:93], 0, v[244:245]
	ds_swizzle_b32 v236, v72 offset:swizzle(SWAP,8)
	ds_swizzle_b32 v237, v73 offset:swizzle(SWAP,8)
	ds_swizzle_b32 v238, v74 offset:swizzle(SWAP,8)
	ds_swizzle_b32 v239, v75 offset:swizzle(SWAP,8)
	ds_swizzle_b32 v240, v68 offset:swizzle(SWAP,8)
	ds_swizzle_b32 v241, v69 offset:swizzle(SWAP,8)
	ds_swizzle_b32 v242, v70 offset:swizzle(SWAP,8)
	ds_swizzle_b32 v243, v71 offset:swizzle(SWAP,8)
	s_waitcnt lgkmcnt(0)
	v_cndmask_b32_e64 v236, v236, v68, s[98:99]
	v_cndmask_b32_e64 v237, v237, v69, s[98:99]
	v_cndmask_b32_e64 v238, v238, v70, s[98:99]
	v_cndmask_b32_e64 v239, v239, v71, s[98:99]
	v_cndmask_b32_e64 v240, v72, v240, s[98:99]
	v_cndmask_b32_e64 v241, v73, v241, s[98:99]
	v_cndmask_b32_e64 v242, v74, v242, s[98:99]
	v_cndmask_b32_e64 v243, v75, v243, s[98:99]
	global_store_dwordx4 v[228:229], v[236:239], off offset:512
	global_store_dwordx4 v[232:233], v[240:243], off offset:512
	v_cvt_pk_bf16_f32 v66, v68, v69
	v_cvt_pk_bf16_f32 v67, v70, v71
	v_cvt_pk_bf16_f32 v68, v72, v73
	s_waitcnt lgkmcnt(0)
	v_add_f32_e32 v64, v64, v65
	ds_bpermute_b32 v65, v114, v64
	v_cvt_pk_bf16_f32 v69, v74, v75
	global_store_dwordx4 v[90:91], v[66:69], off offset:256
	s_and_saveexec_b64 s[24:25], s[2:3]
	s_cbranch_execz .LBB0_669
	v_readlane_b32 s26, v254, 41
	s_waitcnt lgkmcnt(0)
	v_add_f32_e32 v66, v64, v65
	v_lshlrev_b64 v[64:65], 6, v[80:81]
	v_readlane_b32 s27, v254, 42
	s_lshl_b32 s6, s38, 2
	s_nop 0
	v_lshl_add_u64 v[64:65], s[26:27], 0, v[64:65]
	v_lshl_add_u64 v[64:65], s[22:23], 2, v[64:65]
	v_lshl_add_u64 v[64:65], v[64:65], 0, s[6:7]
	global_store_dword v[64:65], v66, off
; __device__ __forceinline__ unsigned cvt_pk_bf16(float lo, float hi) { const f32x2_t v = {lo, hi}; const bf16x2_t b = __builtin_convertvector(v, bf16x2_t); return __builtin_bit_cast(unsigned, b); }
;     __device__ __forceinline__ void operator()(const f32x4 (&acc)[2][2][4][2], const Unit& u, int wr, int wc, int fr, int fq, const PG8_LAS float*) const {
;     ...
;             for (int m = 0; m < 4; ++m) { const int row = row0 + ai * HALF + m * 16; const size_t off = (size_t)row * ldc + col0; float ss = 0.f;
; #pragma unroll
;                 for (int bj = 0; bj < 2; ++bj) {
;                     const f32x4 b0 = *(const f32x4*)(base + off + bj * HALF), b1 = *(const f32x4*)(base + off + bj * HALF + 4);
;                     const f32x4 v0 = b0 + acc[ai][bj][m][0], v1 = b1 + acc[ai][bj][m][1];
;                     *(f32x4*)(out + off + bj * HALF) = v0; *(f32x4*)(out + off + bj * HALF + 4) = v1;
;                     if (xb) { u32x4 w; w.x = cvt_pk_bf16(v0[0], v0[1]); w.y = cvt_pk_bf16(v0[2], v0[3]); w.z = cvt_pk_bf16(v1[0], v1[1]); w.w = cvt_pk_bf16(v1[2], v1[3]);
;                         *(u32x4*)(xb + off + bj * HALF) = w;
;                         ss += ((v0[0] * v0[0] + v0[1] * v0[1]) + (v0[2] * v0[2] + v0[3] * v0[3])) + ((v1[0] * v1[0] + v1[1] * v1[1]) + (v1[2] * v1[2] + v1[3] * v1[3])); } }
;                 if (xb) { ss += __shfl_xor(ss, 16); ss += __shfl_xor(ss, 32); if (fq == 0) ssq[(size_t)row * 16 + u.pn * 4 + wc] = ss; } }
.LBB0_669:
	s_or_b64 exec, exec, s[24:25]
	v_add_u32_e32 v64, 0x80, v146
	s_waitcnt lgkmcnt(0)
	v_ashrrev_i32_e32 v65, 31, v64
	v_lshlrev_b64 v[66:67], 10, v[64:65]
	v_lshl_add_u64 v[74:75], v[66:67], 0, v[144:145]
	v_readlane_b32 s48, v254, 3
	v_lshlrev_b64 v[76:77], 2, v[74:75]
	v_readlane_b32 s49, v254, 4
	v_readlane_b32 s24, v254, 39
	v_readlane_b32 s25, v254, 40
	v_lshl_add_u64 v[78:79], s[48:49], 0, v[76:77]
	v_lshl_add_u64 v[228:229], v[78:79], 0, v[230:231]
	v_lshl_add_u64 v[232:233], v[78:79], 0, v[244:245]
	global_load_dwordx4 v[246:249], v[228:229], off
	global_load_dwordx4 v[236:239], v[232:233], off
	v_lshl_add_u64 v[74:75], v[74:75], 1, s[24:25]
	v_lshl_add_u64 v[76:77], s[68:69], 0, v[76:77]
	v_readlane_b32 s50, v254, 5
	v_readlane_b32 s51, v254, 6
	v_readlane_b32 s52, v254, 7
	v_readlane_b32 s53, v254, 8
	v_readlane_b32 s54, v254, 9
	v_readlane_b32 s55, v254, 10
	v_readlane_b32 s56, v254, 11
	v_readlane_b32 s57, v254, 12
	v_readlane_b32 s58, v254, 13
	v_readlane_b32 s59, v254, 14
	v_readlane_b32 s60, v254, 15
	v_readlane_b32 s61, v254, 16
	v_readlane_b32 s62, v254, 17
	v_readlane_b32 s63, v254, 18
	s_waitcnt vmcnt(0)
	ds_swizzle_b32 v70, v246 offset:swizzle(SWAP,8)
	ds_swizzle_b32 v71, v247 offset:swizzle(SWAP,8)
	ds_swizzle_b32 v72, v248 offset:swizzle(SWAP,8)
	ds_swizzle_b32 v73, v249 offset:swizzle(SWAP,8)
	ds_swizzle_b32 v66, v236 offset:swizzle(SWAP,8)
	ds_swizzle_b32 v67, v237 offset:swizzle(SWAP,8)
	ds_swizzle_b32 v68, v238 offset:swizzle(SWAP,8)
	ds_swizzle_b32 v69, v239 offset:swizzle(SWAP,8)
	s_waitcnt lgkmcnt(0)
	v_cndmask_b32_e64 v66, v66, v246, s[98:99]
	v_cndmask_b32_e64 v67, v67, v247, s[98:99]
	v_cndmask_b32_e64 v68, v68, v248, s[98:99]
	v_cndmask_b32_e64 v69, v69, v249, s[98:99]
	v_cndmask_b32_e64 v70, v236, v70, s[98:99]
	v_cndmask_b32_e64 v71, v237, v71, s[98:99]
	v_cndmask_b32_e64 v72, v238, v72, s[98:99]
	v_cndmask_b32_e64 v73, v239, v73, s[98:99]
	v_pk_add_f32 v[62:63], v[62:63], v[68:69]
	v_pk_add_f32 v[60:61], v[60:61], v[66:67]
	s_waitcnt vmcnt(0)
	v_pk_add_f32 v[58:59], v[58:59], v[72:73]
	v_pk_add_f32 v[56:57], v[56:57], v[70:71]
	v_cvt_pk_bf16_f32 v66, v60, v61
	v_cvt_pk_bf16_f32 v67, v62, v63
	v_cvt_pk_bf16_f32 v68, v56, v57
	v_cvt_pk_bf16_f32 v69, v58, v59
	v_lshl_add_u64 v[228:229], v[76:77], 0, v[230:231]
	v_lshl_add_u64 v[232:233], v[76:77], 0, v[244:245]
	ds_swizzle_b32 v236, v56 offset:swizzle(SWAP,8)
	ds_swizzle_b32 v237, v57 offset:swizzle(SWAP,8)
	ds_swizzle_b32 v238, v58 offset:swizzle(SWAP,8)
	ds_swizzle_b32 v239, v59 offset:swizzle(SWAP,8)
	ds_swizzle_b32 v240, v60 offset:swizzle(SWAP,8)
	ds_swizzle_b32 v241, v61 offset:swizzle(SWAP,8)
	ds_swizzle_b32 v242, v62 offset:swizzle(SWAP,8)
	ds_swizzle_b32 v243, v63 offset:swizzle(SWAP,8)
	s_waitcnt lgkmcnt(0)
	v_cndmask_b32_e64 v236, v236, v60, s[98:99]
	v_cndmask_b32_e64 v237, v237, v61, s[98:99]
	v_cndmask_b32_e64 v238, v238, v62, s[98:99]
	v_cndmask_b32_e64 v239, v239, v63, s[98:99]
	v_cndmask_b32_e64 v240, v56, v240, s[98:99]
	v_cndmask_b32_e64 v241, v57, v241, s[98:99]
	v_cndmask_b32_e64 v242, v58, v242, s[98:99]
	v_cndmask_b32_e64 v243, v59, v243, s[98:99]
	global_store_dwordx4 v[228:229], v[236:239], off
	global_store_dwordx4 v[232:233], v[240:243], off
	global_store_dwordx4 v[74:75], v[66:69], off
	v_lshl_add_u64 v[228:229], v[78:79], 0, v[230:231]
	v_lshl_add_u64 v[232:233], v[78:79], 0, v[244:245]
	global_load_dwordx4 v[246:249], v[228:229], off offset:512
	global_load_dwordx4 v[236:239], v[232:233], off offset:512
	s_nop 0
	v_mul_f32_e32 v61, v61, v61
	v_mul_f32_e32 v63, v63, v63
	v_mul_f32_e32 v57, v57, v57
	v_mul_f32_e32 v59, v59, v59
	v_fmac_f32_e32 v61, v60, v60
	v_fmac_f32_e32 v63, v62, v62
	v_fmac_f32_e32 v57, v56, v56
	v_fmac_f32_e32 v59, v58, v58
	v_add_f32_e32 v56, v61, v63
	v_add_f32_e32 v57, v57, v59
	v_add_f32_e32 v60, v56, v57
	s_waitcnt vmcnt(0)
	ds_swizzle_b32 v70, v246 offset:swizzle(SWAP,8)
	ds_swizzle_b32 v71, v247 offset:swizzle(SWAP,8)
	ds_swizzle_b32 v72, v248 offset:swizzle(SWAP,8)
	ds_swizzle_b32 v73, v249 offset:swizzle(SWAP,8)
	ds_swizzle_b32 v66, v236 offset:swizzle(SWAP,8)
	ds_swizzle_b32 v67, v237 offset:swizzle(SWAP,8)
	ds_swizzle_b32 v68, v238 offset:swizzle(SWAP,8)
	ds_swizzle_b32 v69, v239 offset:swizzle(SWAP,8)
	s_waitcnt lgkmcnt(0)
	v_cndmask_b32_e64 v66, v66, v246, s[98:99]
	v_cndmask_b32_e64 v67, v67, v247, s[98:99]
	v_cndmask_b32_e64 v68, v68, v248, s[98:99]
	v_cndmask_b32_e64 v69, v69, v249, s[98:99]
	v_cndmask_b32_e64 v70, v236, v70, s[98:99]
	v_cndmask_b32_e64 v71, v237, v71, s[98:99]
	v_cndmask_b32_e64 v72, v238, v72, s[98:99]
	v_cndmask_b32_e64 v73, v239, v73, s[98:99]
	v_pk_add_f32 v[54:55], v[54:55], v[68:69]
	v_pk_add_f32 v[52:53], v[52:53], v[66:67]
	s_waitcnt vmcnt(0)
	v_pk_add_f32 v[58:59], v[50:51], v[72:73]
	v_pk_add_f32 v[56:57], v[48:49], v[70:71]
	v_mul_f32_e32 v48, v53, v53
	v_mul_f32_e32 v49, v55, v55
	v_mul_f32_e32 v50, v57, v57
	v_mul_f32_e32 v51, v59, v59
	v_fmac_f32_e32 v48, v52, v52
	v_fmac_f32_e32 v49, v54, v54
	v_fmac_f32_e32 v50, v56, v56
	v_fmac_f32_e32 v51, v58, v58
	v_add_f32_e32 v48, v48, v49
	v_add_f32_e32 v49, v50, v51
	v_add_f32_e32 v48, v48, v49
	v_add_f32_e32 v48, v60, v48
	ds_bpermute_b32 v49, v120, v48
	v_lshl_add_u64 v[228:229], v[76:77], 0, v[230:231]
	v_lshl_add_u64 v[232:233], v[76:77], 0, v[244:245]
	ds_swizzle_b32 v236, v56 offset:swizzle(SWAP,8)
	ds_swizzle_b32 v237, v57 offset:swizzle(SWAP,8)
	ds_swizzle_b32 v238, v58 offset:swizzle(SWAP,8)
	ds_swizzle_b32 v239, v59 offset:swizzle(SWAP,8)
	ds_swizzle_b32 v240, v52 offset:swizzle(SWAP,8)
	ds_swizzle_b32 v241, v53 offset:swizzle(SWAP,8)
	ds_swizzle_b32 v242, v54 offset:swizzle(SWAP,8)
	ds_swizzle_b32 v243, v55 offset:swizzle(SWAP,8)
	s_waitcnt lgkmcnt(0)
	v_cndmask_b32_e64 v236, v236, v52, s[98:99]
	v_cndmask_b32_e64 v237, v237, v53, s[98:99]
	v_cndmask_b32_e64 v238, v238, v54, s[98:99]
	v_cndmask_b32_e64 v239, v239, v55, s[98:99]
	v_cndmask_b32_e64 v240, v56, v240, s[98:99]
	v_cndmask_b32_e64 v241, v57, v241, s[98:99]
	v_cndmask_b32_e64 v242, v58, v242, s[98:99]
	v_cndmask_b32_e64 v243, v59, v243, s[98:99]
	global_store_dwordx4 v[228:229], v[236:239], off offset:512
	global_store_dwordx4 v[232:233], v[240:243], off offset:512
	v_cvt_pk_bf16_f32 v50, v52, v53
	v_cvt_pk_bf16_f32 v51, v54, v55
	v_cvt_pk_bf16_f32 v52, v56, v57
	s_waitcnt lgkmcnt(0)
	v_add_f32_e32 v48, v48, v49
	ds_bpermute_b32 v49, v114, v48
	v_cvt_pk_bf16_f32 v53, v58, v59
	global_store_dwordx4 v[74:75], v[50:53], off offset:256
	s_and_saveexec_b64 s[24:25], s[2:3]
	s_cbranch_execz .LBB0_671
	v_readlane_b32 s26, v254, 41
	s_waitcnt lgkmcnt(0)
	v_add_f32_e32 v50, v48, v49
	v_lshlrev_b64 v[48:49], 6, v[64:65]
	v_readlane_b32 s27, v254, 42
	s_lshl_b32 s6, s38, 2
	s_nop 0
	v_lshl_add_u64 v[48:49], s[26:27], 0, v[48:49]
	v_lshl_add_u64 v[48:49], s[22:23], 2, v[48:49]
	v_lshl_add_u64 v[48:49], v[48:49], 0, s[6:7]
	global_store_dword v[48:49], v50, off
; __device__ __forceinline__ unsigned cvt_pk_bf16(float lo, float hi) { const f32x2_t v = {lo, hi}; const bf16x2_t b = __builtin_convertvector(v, bf16x2_t); return __builtin_bit_cast(unsigned, b); }
;     __device__ __forceinline__ void operator()(const f32x4 (&acc)[2][2][4][2], const Unit& u, int wr, int wc, int fr, int fq, const PG8_LAS float*) const {
;     ...
;             for (int m = 0; m < 4; ++m) { const int row = row0 + ai * HALF + m * 16; const size_t off = (size_t)row * ldc + col0; float ss = 0.f;
; #pragma unroll
;                 for (int bj = 0; bj < 2; ++bj) {
;                     const f32x4 b0 = *(const f32x4*)(base + off + bj * HALF), b1 = *(const f32x4*)(base + off + bj * HALF + 4);
;                     const f32x4 v0 = b0 + acc[ai][bj][m][0], v1 = b1 + acc[ai][bj][m][1];
;                     *(f32x4*)(out + off + bj * HALF) = v0; *(f32x4*)(out + off + bj * HALF + 4) = v1;
;                     if (xb) { u32x4 w; w.x = cvt_pk_bf16(v0[0], v0[1]); w.y = cvt_pk_bf16(v0[2], v0[3]); w.z = cvt_pk_bf16(v1[0], v1[1]); w.w = cvt_pk_bf16(v1[2], v1[3]);
;                         *(u32x4*)(xb + off + bj * HALF) = w;
;                         ss += ((v0[0] * v0[0] + v0[1] * v0[1]) + (v0[2] * v0[2] + v0[3] * v0[3])) + ((v1[0] * v1[0] + v1[1] * v1[1]) + (v1[2] * v1[2] + v1[3] * v1[3])); } }
;                 if (xb) { ss += __shfl_xor(ss, 16); ss += __shfl_xor(ss, 32); if (fq == 0) ssq[(size_t)row * 16 + u.pn * 4 + wc] = ss; } }
.LBB0_671:
	s_or_b64 exec, exec, s[24:25]
	v_add_u32_e32 v48, 0x90, v146
	s_waitcnt lgkmcnt(0)
	v_ashrrev_i32_e32 v49, 31, v48
	v_lshlrev_b64 v[50:51], 10, v[48:49]
	v_lshl_add_u64 v[58:59], v[50:51], 0, v[144:145]
	v_readlane_b32 s48, v254, 3
	v_lshlrev_b64 v[60:61], 2, v[58:59]
	v_readlane_b32 s49, v254, 4
	v_readlane_b32 s24, v254, 39
	v_readlane_b32 s25, v254, 40
	v_lshl_add_u64 v[62:63], s[48:49], 0, v[60:61]
	v_lshl_add_u64 v[228:229], v[62:63], 0, v[230:231]
	v_lshl_add_u64 v[232:233], v[62:63], 0, v[244:245]
	global_load_dwordx4 v[246:249], v[228:229], off
	global_load_dwordx4 v[236:239], v[232:233], off
	v_lshl_add_u64 v[58:59], v[58:59], 1, s[24:25]
	v_lshl_add_u64 v[60:61], s[68:69], 0, v[60:61]
	v_readlane_b32 s50, v254, 5
	v_readlane_b32 s51, v254, 6
	v_readlane_b32 s52, v254, 7
	v_readlane_b32 s53, v254, 8
	v_readlane_b32 s54, v254, 9
	v_readlane_b32 s55, v254, 10
	v_readlane_b32 s56, v254, 11
	v_readlane_b32 s57, v254, 12
	v_readlane_b32 s58, v254, 13
	v_readlane_b32 s59, v254, 14
	v_readlane_b32 s60, v254, 15
	v_readlane_b32 s61, v254, 16
	v_readlane_b32 s62, v254, 17
	v_readlane_b32 s63, v254, 18
	s_waitcnt vmcnt(0)
	ds_swizzle_b32 v54, v246 offset:swizzle(SWAP,8)
	ds_swizzle_b32 v55, v247 offset:swizzle(SWAP,8)
	ds_swizzle_b32 v56, v248 offset:swizzle(SWAP,8)
	ds_swizzle_b32 v57, v249 offset:swizzle(SWAP,8)
	ds_swizzle_b32 v50, v236 offset:swizzle(SWAP,8)
	ds_swizzle_b32 v51, v237 offset:swizzle(SWAP,8)
	ds_swizzle_b32 v52, v238 offset:swizzle(SWAP,8)
	ds_swizzle_b32 v53, v239 offset:swizzle(SWAP,8)
	s_waitcnt lgkmcnt(0)
	v_cndmask_b32_e64 v50, v50, v246, s[98:99]
	v_cndmask_b32_e64 v51, v51, v247, s[98:99]
	v_cndmask_b32_e64 v52, v52, v248, s[98:99]
	v_cndmask_b32_e64 v53, v53, v249, s[98:99]
	v_cndmask_b32_e64 v54, v236, v54, s[98:99]
	v_cndmask_b32_e64 v55, v237, v55, s[98:99]
	v_cndmask_b32_e64 v56, v238, v56, s[98:99]
	v_cndmask_b32_e64 v57, v239, v57, s[98:99]
	v_pk_add_f32 v[46:47], v[46:47], v[52:53]
	v_pk_add_f32 v[44:45], v[44:45], v[50:51]
	s_waitcnt vmcnt(0)
	v_pk_add_f32 v[42:43], v[42:43], v[56:57]
	v_pk_add_f32 v[40:41], v[40:41], v[54:55]
	v_cvt_pk_bf16_f32 v50, v44, v45
	v_cvt_pk_bf16_f32 v51, v46, v47
	v_cvt_pk_bf16_f32 v52, v40, v41
	v_cvt_pk_bf16_f32 v53, v42, v43
	v_lshl_add_u64 v[228:229], v[60:61], 0, v[230:231]
	v_lshl_add_u64 v[232:233], v[60:61], 0, v[244:245]
	ds_swizzle_b32 v236, v40 offset:swizzle(SWAP,8)
	ds_swizzle_b32 v237, v41 offset:swizzle(SWAP,8)
	ds_swizzle_b32 v238, v42 offset:swizzle(SWAP,8)
	ds_swizzle_b32 v239, v43 offset:swizzle(SWAP,8)
	ds_swizzle_b32 v240, v44 offset:swizzle(SWAP,8)
	ds_swizzle_b32 v241, v45 offset:swizzle(SWAP,8)
	ds_swizzle_b32 v242, v46 offset:swizzle(SWAP,8)
	ds_swizzle_b32 v243, v47 offset:swizzle(SWAP,8)
	s_waitcnt lgkmcnt(0)
	v_cndmask_b32_e64 v236, v236, v44, s[98:99]
	v_cndmask_b32_e64 v237, v237, v45, s[98:99]
	v_cndmask_b32_e64 v238, v238, v46, s[98:99]
	v_cndmask_b32_e64 v239, v239, v47, s[98:99]
	v_cndmask_b32_e64 v240, v40, v240, s[98:99]
	v_cndmask_b32_e64 v241, v41, v241, s[98:99]
	v_cndmask_b32_e64 v242, v42, v242, s[98:99]
	v_cndmask_b32_e64 v243, v43, v243, s[98:99]
	global_store_dwordx4 v[228:229], v[236:239], off
	global_store_dwordx4 v[232:233], v[240:243], off
	global_store_dwordx4 v[58:59], v[50:53], off
	v_lshl_add_u64 v[228:229], v[62:63], 0, v[230:231]
	v_lshl_add_u64 v[232:233], v[62:63], 0, v[244:245]
	global_load_dwordx4 v[246:249], v[228:229], off offset:512
	global_load_dwordx4 v[236:239], v[232:233], off offset:512
	s_nop 0
	v_mul_f32_e32 v45, v45, v45
	v_mul_f32_e32 v47, v47, v47
	v_mul_f32_e32 v41, v41, v41
	v_mul_f32_e32 v43, v43, v43
	v_fmac_f32_e32 v45, v44, v44
	v_fmac_f32_e32 v47, v46, v46
	v_fmac_f32_e32 v41, v40, v40
	v_fmac_f32_e32 v43, v42, v42
	v_add_f32_e32 v40, v45, v47
	v_add_f32_e32 v41, v41, v43
	v_add_f32_e32 v44, v40, v41
	s_waitcnt vmcnt(0)
	ds_swizzle_b32 v54, v246 offset:swizzle(SWAP,8)
	ds_swizzle_b32 v55, v247 offset:swizzle(SWAP,8)
	ds_swizzle_b32 v56, v248 offset:swizzle(SWAP,8)
	ds_swizzle_b32 v57, v249 offset:swizzle(SWAP,8)
	ds_swizzle_b32 v50, v236 offset:swizzle(SWAP,8)
	ds_swizzle_b32 v51, v237 offset:swizzle(SWAP,8)
	ds_swizzle_b32 v52, v238 offset:swizzle(SWAP,8)
	ds_swizzle_b32 v53, v239 offset:swizzle(SWAP,8)
	s_waitcnt lgkmcnt(0)
	v_cndmask_b32_e64 v50, v50, v246, s[98:99]
	v_cndmask_b32_e64 v51, v51, v247, s[98:99]
	v_cndmask_b32_e64 v52, v52, v248, s[98:99]
	v_cndmask_b32_e64 v53, v53, v249, s[98:99]
	v_cndmask_b32_e64 v54, v236, v54, s[98:99]
	v_cndmask_b32_e64 v55, v237, v55, s[98:99]
	v_cndmask_b32_e64 v56, v238, v56, s[98:99]
	v_cndmask_b32_e64 v57, v239, v57, s[98:99]
	v_pk_add_f32 v[38:39], v[38:39], v[52:53]
	v_pk_add_f32 v[36:37], v[36:37], v[50:51]
	s_waitcnt vmcnt(0)
	v_pk_add_f32 v[42:43], v[34:35], v[56:57]
	v_pk_add_f32 v[40:41], v[32:33], v[54:55]
	v_mul_f32_e32 v32, v37, v37
	v_mul_f32_e32 v33, v39, v39
	v_mul_f32_e32 v34, v41, v41
	v_mul_f32_e32 v35, v43, v43
	v_fmac_f32_e32 v32, v36, v36
	v_fmac_f32_e32 v33, v38, v38
	v_fmac_f32_e32 v34, v40, v40
	v_fmac_f32_e32 v35, v42, v42
	v_add_f32_e32 v32, v32, v33
	v_add_f32_e32 v33, v34, v35
	v_add_f32_e32 v32, v32, v33
	v_add_f32_e32 v32, v44, v32
	ds_bpermute_b32 v33, v120, v32
	v_lshl_add_u64 v[228:229], v[60:61], 0, v[230:231]
	v_lshl_add_u64 v[232:233], v[60:61], 0, v[244:245]
	ds_swizzle_b32 v236, v40 offset:swizzle(SWAP,8)
	ds_swizzle_b32 v237, v41 offset:swizzle(SWAP,8)
	ds_swizzle_b32 v238, v42 offset:swizzle(SWAP,8)
	ds_swizzle_b32 v239, v43 offset:swizzle(SWAP,8)
	ds_swizzle_b32 v240, v36 offset:swizzle(SWAP,8)
	ds_swizzle_b32 v241, v37 offset:swizzle(SWAP,8)
	ds_swizzle_b32 v242, v38 offset:swizzle(SWAP,8)
	ds_swizzle_b32 v243, v39 offset:swizzle(SWAP,8)
	s_waitcnt lgkmcnt(0)
	v_cndmask_b32_e64 v236, v236, v36, s[98:99]
	v_cndmask_b32_e64 v237, v237, v37, s[98:99]
	v_cndmask_b32_e64 v238, v238, v38, s[98:99]
	v_cndmask_b32_e64 v239, v239, v39, s[98:99]
	v_cndmask_b32_e64 v240, v40, v240, s[98:99]
	v_cndmask_b32_e64 v241, v41, v241, s[98:99]
	v_cndmask_b32_e64 v242, v42, v242, s[98:99]
	v_cndmask_b32_e64 v243, v43, v243, s[98:99]
	global_store_dwordx4 v[228:229], v[236:239], off offset:512
	global_store_dwordx4 v[232:233], v[240:243], off offset:512
	v_cvt_pk_bf16_f32 v34, v36, v37
	v_cvt_pk_bf16_f32 v35, v38, v39
	v_cvt_pk_bf16_f32 v36, v40, v41
	s_waitcnt lgkmcnt(0)
	v_add_f32_e32 v32, v32, v33
	ds_bpermute_b32 v33, v114, v32
	v_cvt_pk_bf16_f32 v37, v42, v43
	global_store_dwordx4 v[58:59], v[34:37], off offset:256
	s_and_saveexec_b64 s[24:25], s[2:3]
	s_cbranch_execz .LBB0_673
	v_readlane_b32 s26, v254, 41
	s_waitcnt lgkmcnt(0)
	v_add_f32_e32 v34, v32, v33
	v_lshlrev_b64 v[32:33], 6, v[48:49]
	v_readlane_b32 s27, v254, 42
	s_lshl_b32 s6, s38, 2
	s_nop 0
	v_lshl_add_u64 v[32:33], s[26:27], 0, v[32:33]
	v_lshl_add_u64 v[32:33], s[22:23], 2, v[32:33]
	v_lshl_add_u64 v[32:33], v[32:33], 0, s[6:7]
	global_store_dword v[32:33], v34, off
; __device__ __forceinline__ unsigned cvt_pk_bf16(float lo, float hi) { const f32x2_t v = {lo, hi}; const bf16x2_t b = __builtin_convertvector(v, bf16x2_t); return __builtin_bit_cast(unsigned, b); }
;     __device__ __forceinline__ void operator()(const f32x4 (&acc)[2][2][4][2], const Unit& u, int wr, int wc, int fr, int fq, const PG8_LAS float*) const {
;     ...
;             for (int m = 0; m < 4; ++m) { const int row = row0 + ai * HALF + m * 16; const size_t off = (size_t)row * ldc + col0; float ss = 0.f;
; #pragma unroll
;                 for (int bj = 0; bj < 2; ++bj) {
;                     const f32x4 b0 = *(const f32x4*)(base + off + bj * HALF), b1 = *(const f32x4*)(base + off + bj * HALF + 4);
;                     const f32x4 v0 = b0 + acc[ai][bj][m][0], v1 = b1 + acc[ai][bj][m][1];
;                     *(f32x4*)(out + off + bj * HALF) = v0; *(f32x4*)(out + off + bj * HALF + 4) = v1;
;                     if (xb) { u32x4 w; w.x = cvt_pk_bf16(v0[0], v0[1]); w.y = cvt_pk_bf16(v0[2], v0[3]); w.z = cvt_pk_bf16(v1[0], v1[1]); w.w = cvt_pk_bf16(v1[2], v1[3]);
;                         *(u32x4*)(xb + off + bj * HALF) = w;
;                         ss += ((v0[0] * v0[0] + v0[1] * v0[1]) + (v0[2] * v0[2] + v0[3] * v0[3])) + ((v1[0] * v1[0] + v1[1] * v1[1]) + (v1[2] * v1[2] + v1[3] * v1[3])); } }
;                 if (xb) { ss += __shfl_xor(ss, 16); ss += __shfl_xor(ss, 32); if (fq == 0) ssq[(size_t)row * 16 + u.pn * 4 + wc] = ss; } }
.LBB0_673:
	s_or_b64 exec, exec, s[24:25]
	v_add_u32_e32 v32, 0xa0, v146
	s_waitcnt lgkmcnt(0)
	v_ashrrev_i32_e32 v33, 31, v32
	v_lshlrev_b64 v[34:35], 10, v[32:33]
	v_lshl_add_u64 v[42:43], v[34:35], 0, v[144:145]
	v_readlane_b32 s48, v254, 3
	v_lshlrev_b64 v[44:45], 2, v[42:43]
	v_readlane_b32 s49, v254, 4
	v_readlane_b32 s24, v254, 39
	v_readlane_b32 s25, v254, 40
	v_lshl_add_u64 v[46:47], s[48:49], 0, v[44:45]
	v_lshl_add_u64 v[228:229], v[46:47], 0, v[230:231]
	v_lshl_add_u64 v[232:233], v[46:47], 0, v[244:245]
	global_load_dwordx4 v[246:249], v[228:229], off
	global_load_dwordx4 v[236:239], v[232:233], off
	v_lshl_add_u64 v[42:43], v[42:43], 1, s[24:25]
	v_lshl_add_u64 v[44:45], s[68:69], 0, v[44:45]
	v_readlane_b32 s50, v254, 5
	v_readlane_b32 s51, v254, 6
	v_readlane_b32 s52, v254, 7
	v_readlane_b32 s53, v254, 8
	v_readlane_b32 s54, v254, 9
	v_readlane_b32 s55, v254, 10
	v_readlane_b32 s56, v254, 11
	v_readlane_b32 s57, v254, 12
	v_readlane_b32 s58, v254, 13
	v_readlane_b32 s59, v254, 14
	v_readlane_b32 s60, v254, 15
	v_readlane_b32 s61, v254, 16
	v_readlane_b32 s62, v254, 17
	v_readlane_b32 s63, v254, 18
	s_waitcnt vmcnt(0)
	ds_swizzle_b32 v38, v246 offset:swizzle(SWAP,8)
	ds_swizzle_b32 v39, v247 offset:swizzle(SWAP,8)
	ds_swizzle_b32 v40, v248 offset:swizzle(SWAP,8)
	ds_swizzle_b32 v41, v249 offset:swizzle(SWAP,8)
	ds_swizzle_b32 v34, v236 offset:swizzle(SWAP,8)
	ds_swizzle_b32 v35, v237 offset:swizzle(SWAP,8)
	ds_swizzle_b32 v36, v238 offset:swizzle(SWAP,8)
	ds_swizzle_b32 v37, v239 offset:swizzle(SWAP,8)
	s_waitcnt lgkmcnt(0)
	v_cndmask_b32_e64 v34, v34, v246, s[98:99]
	v_cndmask_b32_e64 v35, v35, v247, s[98:99]
	v_cndmask_b32_e64 v36, v36, v248, s[98:99]
	v_cndmask_b32_e64 v37, v37, v249, s[98:99]
	v_cndmask_b32_e64 v38, v236, v38, s[98:99]
	v_cndmask_b32_e64 v39, v237, v39, s[98:99]
	v_cndmask_b32_e64 v40, v238, v40, s[98:99]
	v_cndmask_b32_e64 v41, v239, v41, s[98:99]
	v_pk_add_f32 v[30:31], v[30:31], v[36:37]
	v_pk_add_f32 v[28:29], v[28:29], v[34:35]
	s_waitcnt vmcnt(0)
	v_pk_add_f32 v[26:27], v[26:27], v[40:41]
	v_pk_add_f32 v[24:25], v[24:25], v[38:39]
	v_cvt_pk_bf16_f32 v34, v28, v29
	v_cvt_pk_bf16_f32 v35, v30, v31
	v_cvt_pk_bf16_f32 v36, v24, v25
	v_cvt_pk_bf16_f32 v37, v26, v27
	v_lshl_add_u64 v[228:229], v[44:45], 0, v[230:231]
	v_lshl_add_u64 v[232:233], v[44:45], 0, v[244:245]
	ds_swizzle_b32 v236, v24 offset:swizzle(SWAP,8)
	ds_swizzle_b32 v237, v25 offset:swizzle(SWAP,8)
	ds_swizzle_b32 v238, v26 offset:swizzle(SWAP,8)
	ds_swizzle_b32 v239, v27 offset:swizzle(SWAP,8)
	ds_swizzle_b32 v240, v28 offset:swizzle(SWAP,8)
	ds_swizzle_b32 v241, v29 offset:swizzle(SWAP,8)
	ds_swizzle_b32 v242, v30 offset:swizzle(SWAP,8)
	ds_swizzle_b32 v243, v31 offset:swizzle(SWAP,8)
	s_waitcnt lgkmcnt(0)
	v_cndmask_b32_e64 v236, v236, v28, s[98:99]
	v_cndmask_b32_e64 v237, v237, v29, s[98:99]
	v_cndmask_b32_e64 v238, v238, v30, s[98:99]
	v_cndmask_b32_e64 v239, v239, v31, s[98:99]
	v_cndmask_b32_e64 v240, v24, v240, s[98:99]
	v_cndmask_b32_e64 v241, v25, v241, s[98:99]
	v_cndmask_b32_e64 v242, v26, v242, s[98:99]
	v_cndmask_b32_e64 v243, v27, v243, s[98:99]
	global_store_dwordx4 v[228:229], v[236:239], off
	global_store_dwordx4 v[232:233], v[240:243], off
	global_store_dwordx4 v[42:43], v[34:37], off
	v_lshl_add_u64 v[228:229], v[46:47], 0, v[230:231]
	v_lshl_add_u64 v[232:233], v[46:47], 0, v[244:245]
	global_load_dwordx4 v[246:249], v[228:229], off offset:512
	global_load_dwordx4 v[236:239], v[232:233], off offset:512
	s_nop 0
	v_mul_f32_e32 v29, v29, v29
	v_mul_f32_e32 v31, v31, v31
	v_mul_f32_e32 v25, v25, v25
	v_mul_f32_e32 v27, v27, v27
	v_fmac_f32_e32 v29, v28, v28
	v_fmac_f32_e32 v31, v30, v30
	v_fmac_f32_e32 v25, v24, v24
	v_fmac_f32_e32 v27, v26, v26
	v_add_f32_e32 v24, v29, v31
	v_add_f32_e32 v25, v25, v27
	v_add_f32_e32 v28, v24, v25
	s_waitcnt vmcnt(0)
	ds_swizzle_b32 v38, v246 offset:swizzle(SWAP,8)
	ds_swizzle_b32 v39, v247 offset:swizzle(SWAP,8)
	ds_swizzle_b32 v40, v248 offset:swizzle(SWAP,8)
	ds_swizzle_b32 v41, v249 offset:swizzle(SWAP,8)
	ds_swizzle_b32 v34, v236 offset:swizzle(SWAP,8)
	ds_swizzle_b32 v35, v237 offset:swizzle(SWAP,8)
	ds_swizzle_b32 v36, v238 offset:swizzle(SWAP,8)
	ds_swizzle_b32 v37, v239 offset:swizzle(SWAP,8)
	s_waitcnt lgkmcnt(0)
	v_cndmask_b32_e64 v34, v34, v246, s[98:99]
	v_cndmask_b32_e64 v35, v35, v247, s[98:99]
	v_cndmask_b32_e64 v36, v36, v248, s[98:99]
	v_cndmask_b32_e64 v37, v37, v249, s[98:99]
	v_cndmask_b32_e64 v38, v236, v38, s[98:99]
	v_cndmask_b32_e64 v39, v237, v39, s[98:99]
	v_cndmask_b32_e64 v40, v238, v40, s[98:99]
	v_cndmask_b32_e64 v41, v239, v41, s[98:99]
	v_pk_add_f32 v[22:23], v[22:23], v[36:37]
	v_pk_add_f32 v[20:21], v[20:21], v[34:35]
	s_waitcnt vmcnt(0)
	v_pk_add_f32 v[26:27], v[18:19], v[40:41]
	v_pk_add_f32 v[24:25], v[16:17], v[38:39]
	v_mul_f32_e32 v16, v21, v21
	v_mul_f32_e32 v17, v23, v23
	v_mul_f32_e32 v18, v25, v25
	v_mul_f32_e32 v19, v27, v27
	v_fmac_f32_e32 v16, v20, v20
	v_fmac_f32_e32 v17, v22, v22
	v_fmac_f32_e32 v18, v24, v24
	v_fmac_f32_e32 v19, v26, v26
	v_add_f32_e32 v16, v16, v17
	v_add_f32_e32 v17, v18, v19
	v_add_f32_e32 v16, v16, v17
	v_add_f32_e32 v16, v28, v16
	ds_bpermute_b32 v17, v120, v16
	v_lshl_add_u64 v[228:229], v[44:45], 0, v[230:231]
	v_lshl_add_u64 v[232:233], v[44:45], 0, v[244:245]
	ds_swizzle_b32 v236, v24 offset:swizzle(SWAP,8)
	ds_swizzle_b32 v237, v25 offset:swizzle(SWAP,8)
	ds_swizzle_b32 v238, v26 offset:swizzle(SWAP,8)
	ds_swizzle_b32 v239, v27 offset:swizzle(SWAP,8)
	ds_swizzle_b32 v240, v20 offset:swizzle(SWAP,8)
	ds_swizzle_b32 v241, v21 offset:swizzle(SWAP,8)
	ds_swizzle_b32 v242, v22 offset:swizzle(SWAP,8)
	ds_swizzle_b32 v243, v23 offset:swizzle(SWAP,8)
	s_waitcnt lgkmcnt(0)
	v_cndmask_b32_e64 v236, v236, v20, s[98:99]
	v_cndmask_b32_e64 v237, v237, v21, s[98:99]
	v_cndmask_b32_e64 v238, v238, v22, s[98:99]
	v_cndmask_b32_e64 v239, v239, v23, s[98:99]
	v_cndmask_b32_e64 v240, v24, v240, s[98:99]
	v_cndmask_b32_e64 v241, v25, v241, s[98:99]
	v_cndmask_b32_e64 v242, v26, v242, s[98:99]
	v_cndmask_b32_e64 v243, v27, v243, s[98:99]
	global_store_dwordx4 v[228:229], v[236:239], off offset:512
	global_store_dwordx4 v[232:233], v[240:243], off offset:512
	v_cvt_pk_bf16_f32 v18, v20, v21
	v_cvt_pk_bf16_f32 v19, v22, v23
	v_cvt_pk_bf16_f32 v20, v24, v25
	s_waitcnt lgkmcnt(0)
	v_add_f32_e32 v16, v16, v17
	ds_bpermute_b32 v17, v114, v16
	v_cvt_pk_bf16_f32 v21, v26, v27
	global_store_dwordx4 v[42:43], v[18:21], off offset:256
	s_and_saveexec_b64 s[24:25], s[2:3]
	s_cbranch_execz .LBB0_675
	v_readlane_b32 s26, v254, 41
	s_waitcnt lgkmcnt(0)
	v_add_f32_e32 v18, v16, v17
	v_lshlrev_b64 v[16:17], 6, v[32:33]
	v_readlane_b32 s27, v254, 42
	s_lshl_b32 s6, s38, 2
	s_nop 0
	v_lshl_add_u64 v[16:17], s[26:27], 0, v[16:17]
	v_lshl_add_u64 v[16:17], s[22:23], 2, v[16:17]
	v_lshl_add_u64 v[16:17], v[16:17], 0, s[6:7]
	global_store_dword v[16:17], v18, off
; __device__ __forceinline__ unsigned cvt_pk_bf16(float lo, float hi) { const f32x2_t v = {lo, hi}; const bf16x2_t b = __builtin_convertvector(v, bf16x2_t); return __builtin_bit_cast(unsigned, b); }
;     __device__ __forceinline__ void operator()(const f32x4 (&acc)[2][2][4][2], const Unit& u, int wr, int wc, int fr, int fq, const PG8_LAS float*) const {
;     ...
;             for (int m = 0; m < 4; ++m) { const int row = row0 + ai * HALF + m * 16; const size_t off = (size_t)row * ldc + col0; float ss = 0.f;
; #pragma unroll
;                 for (int bj = 0; bj < 2; ++bj) {
;                     const f32x4 b0 = *(const f32x4*)(base + off + bj * HALF), b1 = *(const f32x4*)(base + off + bj * HALF + 4);
;                     const f32x4 v0 = b0 + acc[ai][bj][m][0], v1 = b1 + acc[ai][bj][m][1];
;                     *(f32x4*)(out + off + bj * HALF) = v0; *(f32x4*)(out + off + bj * HALF + 4) = v1;
;                     if (xb) { u32x4 w; w.x = cvt_pk_bf16(v0[0], v0[1]); w.y = cvt_pk_bf16(v0[2], v0[3]); w.z = cvt_pk_bf16(v1[0], v1[1]); w.w = cvt_pk_bf16(v1[2], v1[3]);
;                         *(u32x4*)(xb + off + bj * HALF) = w;
;                         ss += ((v0[0] * v0[0] + v0[1] * v0[1]) + (v0[2] * v0[2] + v0[3] * v0[3])) + ((v1[0] * v1[0] + v1[1] * v1[1]) + (v1[2] * v1[2] + v1[3] * v1[3])); } }
;                 if (xb) { ss += __shfl_xor(ss, 16); ss += __shfl_xor(ss, 32); if (fq == 0) ssq[(size_t)row * 16 + u.pn * 4 + wc] = ss; } }
.LBB0_675:
	s_or_b64 exec, exec, s[24:25]
	v_add_u32_e32 v16, 0xb0, v146
	s_waitcnt lgkmcnt(0)
	v_ashrrev_i32_e32 v17, 31, v16
	v_lshlrev_b64 v[18:19], 10, v[16:17]
	v_lshl_add_u64 v[26:27], v[18:19], 0, v[144:145]
	v_readlane_b32 s48, v254, 3
	v_lshlrev_b64 v[28:29], 2, v[26:27]
	v_readlane_b32 s49, v254, 4
	v_readlane_b32 s24, v254, 39
	v_readlane_b32 s25, v254, 40
	v_lshl_add_u64 v[30:31], s[48:49], 0, v[28:29]
	v_lshl_add_u64 v[228:229], v[30:31], 0, v[230:231]
	v_lshl_add_u64 v[232:233], v[30:31], 0, v[244:245]
	global_load_dwordx4 v[246:249], v[228:229], off
	global_load_dwordx4 v[236:239], v[232:233], off
	v_lshl_add_u64 v[26:27], v[26:27], 1, s[24:25]
	v_lshl_add_u64 v[28:29], s[68:69], 0, v[28:29]
	v_readlane_b32 s50, v254, 5
	v_readlane_b32 s51, v254, 6
	v_readlane_b32 s52, v254, 7
	v_readlane_b32 s53, v254, 8
	v_readlane_b32 s54, v254, 9
	v_readlane_b32 s55, v254, 10
	v_readlane_b32 s56, v254, 11
	v_readlane_b32 s57, v254, 12
	v_readlane_b32 s58, v254, 13
	v_readlane_b32 s59, v254, 14
	v_readlane_b32 s60, v254, 15
	v_readlane_b32 s61, v254, 16
	v_readlane_b32 s62, v254, 17
	v_readlane_b32 s63, v254, 18
	s_waitcnt vmcnt(0)
	ds_swizzle_b32 v22, v246 offset:swizzle(SWAP,8)
	ds_swizzle_b32 v23, v247 offset:swizzle(SWAP,8)
	ds_swizzle_b32 v24, v248 offset:swizzle(SWAP,8)
	ds_swizzle_b32 v25, v249 offset:swizzle(SWAP,8)
	ds_swizzle_b32 v18, v236 offset:swizzle(SWAP,8)
	ds_swizzle_b32 v19, v237 offset:swizzle(SWAP,8)
	ds_swizzle_b32 v20, v238 offset:swizzle(SWAP,8)
	ds_swizzle_b32 v21, v239 offset:swizzle(SWAP,8)
	s_waitcnt lgkmcnt(0)
	v_cndmask_b32_e64 v18, v18, v246, s[98:99]
	v_cndmask_b32_e64 v19, v19, v247, s[98:99]
	v_cndmask_b32_e64 v20, v20, v248, s[98:99]
	v_cndmask_b32_e64 v21, v21, v249, s[98:99]
	v_cndmask_b32_e64 v22, v236, v22, s[98:99]
	v_cndmask_b32_e64 v23, v237, v23, s[98:99]
	v_cndmask_b32_e64 v24, v238, v24, s[98:99]
	v_cndmask_b32_e64 v25, v239, v25, s[98:99]
	v_pk_add_f32 v[14:15], v[14:15], v[20:21]
	v_pk_add_f32 v[12:13], v[12:13], v[18:19]
	s_waitcnt vmcnt(0)
	v_pk_add_f32 v[10:11], v[10:11], v[24:25]
	v_pk_add_f32 v[8:9], v[8:9], v[22:23]
	v_cvt_pk_bf16_f32 v18, v12, v13
	v_cvt_pk_bf16_f32 v19, v14, v15
	v_cvt_pk_bf16_f32 v20, v8, v9
	v_cvt_pk_bf16_f32 v21, v10, v11
	v_lshl_add_u64 v[228:229], v[28:29], 0, v[230:231]
	v_lshl_add_u64 v[232:233], v[28:29], 0, v[244:245]
	ds_swizzle_b32 v236, v8 offset:swizzle(SWAP,8)
	ds_swizzle_b32 v237, v9 offset:swizzle(SWAP,8)
	ds_swizzle_b32 v238, v10 offset:swizzle(SWAP,8)
	ds_swizzle_b32 v239, v11 offset:swizzle(SWAP,8)
	ds_swizzle_b32 v240, v12 offset:swizzle(SWAP,8)
	ds_swizzle_b32 v241, v13 offset:swizzle(SWAP,8)
	ds_swizzle_b32 v242, v14 offset:swizzle(SWAP,8)
	ds_swizzle_b32 v243, v15 offset:swizzle(SWAP,8)
	s_waitcnt lgkmcnt(0)
	v_cndmask_b32_e64 v236, v236, v12, s[98:99]
	v_cndmask_b32_e64 v237, v237, v13, s[98:99]
	v_cndmask_b32_e64 v238, v238, v14, s[98:99]
	v_cndmask_b32_e64 v239, v239, v15, s[98:99]
	v_cndmask_b32_e64 v240, v8, v240, s[98:99]
	v_cndmask_b32_e64 v241, v9, v241, s[98:99]
	v_cndmask_b32_e64 v242, v10, v242, s[98:99]
	v_cndmask_b32_e64 v243, v11, v243, s[98:99]
	global_store_dwordx4 v[228:229], v[236:239], off
	global_store_dwordx4 v[232:233], v[240:243], off
	global_store_dwordx4 v[26:27], v[18:21], off
	v_lshl_add_u64 v[228:229], v[30:31], 0, v[230:231]
	v_lshl_add_u64 v[232:233], v[30:31], 0, v[244:245]
	global_load_dwordx4 v[246:249], v[228:229], off offset:512
	global_load_dwordx4 v[236:239], v[232:233], off offset:512
	s_nop 0
	v_mul_f32_e32 v13, v13, v13
	v_mul_f32_e32 v15, v15, v15
	v_mul_f32_e32 v9, v9, v9
	v_mul_f32_e32 v11, v11, v11
	v_fmac_f32_e32 v13, v12, v12
	v_fmac_f32_e32 v15, v14, v14
	v_fmac_f32_e32 v9, v8, v8
	v_fmac_f32_e32 v11, v10, v10
	v_add_f32_e32 v8, v13, v15
	v_add_f32_e32 v9, v9, v11
	v_add_f32_e32 v12, v8, v9
	s_waitcnt vmcnt(0)
	ds_swizzle_b32 v22, v246 offset:swizzle(SWAP,8)
	ds_swizzle_b32 v23, v247 offset:swizzle(SWAP,8)
	ds_swizzle_b32 v24, v248 offset:swizzle(SWAP,8)
	ds_swizzle_b32 v25, v249 offset:swizzle(SWAP,8)
	ds_swizzle_b32 v18, v236 offset:swizzle(SWAP,8)
	ds_swizzle_b32 v19, v237 offset:swizzle(SWAP,8)
	ds_swizzle_b32 v20, v238 offset:swizzle(SWAP,8)
	ds_swizzle_b32 v21, v239 offset:swizzle(SWAP,8)
	s_waitcnt lgkmcnt(0)
	v_cndmask_b32_e64 v18, v18, v246, s[98:99]
	v_cndmask_b32_e64 v19, v19, v247, s[98:99]
	v_cndmask_b32_e64 v20, v20, v248, s[98:99]
	v_cndmask_b32_e64 v21, v21, v249, s[98:99]
	v_cndmask_b32_e64 v22, v236, v22, s[98:99]
	v_cndmask_b32_e64 v23, v237, v23, s[98:99]
	v_cndmask_b32_e64 v24, v238, v24, s[98:99]
	v_cndmask_b32_e64 v25, v239, v25, s[98:99]
	v_pk_add_f32 v[6:7], v[6:7], v[20:21]
	v_pk_add_f32 v[4:5], v[4:5], v[18:19]
	s_waitcnt vmcnt(0)
	v_pk_add_f32 v[10:11], v[2:3], v[24:25]
	v_pk_add_f32 v[8:9], v[0:1], v[22:23]
	v_mul_f32_e32 v0, v5, v5
	v_mul_f32_e32 v1, v7, v7
	v_mul_f32_e32 v2, v9, v9
	v_mul_f32_e32 v3, v11, v11
	v_fmac_f32_e32 v0, v4, v4
	v_fmac_f32_e32 v1, v6, v6
	v_fmac_f32_e32 v2, v8, v8
	v_fmac_f32_e32 v3, v10, v10
	v_add_f32_e32 v0, v0, v1
	v_add_f32_e32 v1, v2, v3
	v_add_f32_e32 v0, v0, v1
	v_add_f32_e32 v0, v12, v0
	ds_bpermute_b32 v1, v120, v0
	v_lshl_add_u64 v[228:229], v[28:29], 0, v[230:231]
	v_lshl_add_u64 v[232:233], v[28:29], 0, v[244:245]
	ds_swizzle_b32 v236, v8 offset:swizzle(SWAP,8)
	ds_swizzle_b32 v237, v9 offset:swizzle(SWAP,8)
	ds_swizzle_b32 v238, v10 offset:swizzle(SWAP,8)
	ds_swizzle_b32 v239, v11 offset:swizzle(SWAP,8)
	ds_swizzle_b32 v240, v4 offset:swizzle(SWAP,8)
	ds_swizzle_b32 v241, v5 offset:swizzle(SWAP,8)
	ds_swizzle_b32 v242, v6 offset:swizzle(SWAP,8)
	ds_swizzle_b32 v243, v7 offset:swizzle(SWAP,8)
	s_waitcnt lgkmcnt(0)
	v_cndmask_b32_e64 v236, v236, v4, s[98:99]
	v_cndmask_b32_e64 v237, v237, v5, s[98:99]
	v_cndmask_b32_e64 v238, v238, v6, s[98:99]
	v_cndmask_b32_e64 v239, v239, v7, s[98:99]
	v_cndmask_b32_e64 v240, v8, v240, s[98:99]
	v_cndmask_b32_e64 v241, v9, v241, s[98:99]
	v_cndmask_b32_e64 v242, v10, v242, s[98:99]
	v_cndmask_b32_e64 v243, v11, v243, s[98:99]
	global_store_dwordx4 v[228:229], v[236:239], off offset:512
	global_store_dwordx4 v[232:233], v[240:243], off offset:512
	v_cvt_pk_bf16_f32 v2, v4, v5
	v_cvt_pk_bf16_f32 v3, v6, v7
	v_cvt_pk_bf16_f32 v4, v8, v9
	s_waitcnt lgkmcnt(0)
	v_add_f32_e32 v0, v0, v1
	ds_bpermute_b32 v1, v114, v0
	v_cvt_pk_bf16_f32 v5, v10, v11
	global_store_dwordx4 v[26:27], v[2:5], off offset:256
	s_and_saveexec_b64 s[24:25], s[2:3]
	s_cbranch_execz .LBB0_677
	v_readlane_b32 s26, v254, 41
	s_waitcnt lgkmcnt(0)
	v_add_f32_e32 v2, v0, v1
	v_lshlrev_b64 v[0:1], 6, v[16:17]
	v_readlane_b32 s27, v254, 42
	s_lshl_b32 s6, s38, 2
	s_nop 0
	v_lshl_add_u64 v[0:1], s[26:27], 0, v[0:1]
	v_lshl_add_u64 v[0:1], s[22:23], 2, v[0:1]
	v_lshl_add_u64 v[0:1], v[0:1], 0, s[6:7]
	global_store_dword v[0:1], v2, off

; __device__ __forceinline__ unsigned cvt_pk_bf16(float lo, float hi) { const f32x2_t v = {lo, hi}; const bf16x2_t b = __builtin_convertvector(v, bf16x2_t); return __builtin_bit_cast(unsigned, b); }
;     __device__ __forceinline__ void operator()(const f32x4 (&acc)[2][2][4][2], const Unit& u, int wr, int wc, int fr, int fq, const PG8_LAS float*) const {
;     ...
;             for (int m = 0; m < 4; ++m) { const int row = row0 + ai * HALF + m * 16; const size_t off = (size_t)row * ldc + col0; float ss = 0.f;
; #pragma unroll
;                 for (int bj = 0; bj < 2; ++bj) {
;                     const f32x4 b0 = *(const f32x4*)(base + off + bj * HALF), b1 = *(const f32x4*)(base + off + bj * HALF + 4);
;                     const f32x4 v0 = b0 + acc[ai][bj][m][0], v1 = b1 + acc[ai][bj][m][1];
;                     *(f32x4*)(out + off + bj * HALF) = v0; *(f32x4*)(out + off + bj * HALF + 4) = v1;
;                     if (xb) { u32x4 w; w.x = cvt_pk_bf16(v0[0], v0[1]); w.y = cvt_pk_bf16(v0[2], v0[3]); w.z = cvt_pk_bf16(v1[0], v1[1]); w.w = cvt_pk_bf16(v1[2], v1[3]);
;                         *(u32x4*)(xb + off + bj * HALF) = w;
;                         ss += ((v0[0] * v0[0] + v0[1] * v0[1]) + (v0[2] * v0[2] + v0[3] * v0[3])) + ((v1[0] * v1[0] + v1[1] * v1[1]) + (v1[2] * v1[2] + v1[3] * v1[3])); } }
;                 if (xb) { ss += __shfl_xor(ss, 16); ss += __shfl_xor(ss, 32); if (fq == 0) ssq[(size_t)row * 16 + u.pn * 4 + wc] = ss; } }
.LBB0_845:
	v_lshl_add_u32 v146, s22, 8, v148
	v_lshl_or_b32 v144, s6, 8, v150
	v_ashrrev_i32_e32 v147, 31, v146
	v_ashrrev_i32_e32 v145, 31, v144
	v_lshlrev_b64 v[156:157], 10, v[146:147]
	v_lshl_add_u64 v[164:165], v[156:157], 0, v[144:145]
	v_lshl_add_u64 v[172:173], v[164:165], 2, s[68:69]
	v_lshl_add_u64 v[228:229], v[172:173], 0, v[230:231]
	v_lshl_add_u64 v[232:233], v[172:173], 0, v[244:245]
	global_load_dwordx4 v[246:249], v[228:229], off
	global_load_dwordx4 v[236:239], v[232:233], off
	v_readlane_b32 s22, v254, 39
	v_readlane_b32 s23, v254, 40
	v_xor_b32_e32 v155, 32, v154
	s_waitcnt vmcnt(0)
	ds_swizzle_b32 v160, v246 offset:swizzle(SWAP,8)
	ds_swizzle_b32 v161, v247 offset:swizzle(SWAP,8)
	ds_swizzle_b32 v162, v248 offset:swizzle(SWAP,8)
	ds_swizzle_b32 v163, v249 offset:swizzle(SWAP,8)
	ds_swizzle_b32 v156, v236 offset:swizzle(SWAP,8)
	ds_swizzle_b32 v157, v237 offset:swizzle(SWAP,8)
	ds_swizzle_b32 v158, v238 offset:swizzle(SWAP,8)
	ds_swizzle_b32 v159, v239 offset:swizzle(SWAP,8)
	s_waitcnt lgkmcnt(0)
	v_cndmask_b32_e64 v156, v156, v246, s[98:99]
	v_cndmask_b32_e64 v157, v157, v247, s[98:99]
	v_cndmask_b32_e64 v158, v158, v248, s[98:99]
	v_cndmask_b32_e64 v159, v159, v249, s[98:99]
	v_cndmask_b32_e64 v160, v236, v160, s[98:99]
	v_cndmask_b32_e64 v161, v237, v161, s[98:99]
	v_cndmask_b32_e64 v162, v238, v162, s[98:99]
	v_cndmask_b32_e64 v163, v239, v163, s[98:99]
	v_pk_add_f32 v[126:127], v[126:127], v[158:159]
	v_pk_add_f32 v[124:125], v[124:125], v[156:157]
	v_pk_add_f32 v[158:159], v[122:123], v[162:163]
	v_pk_add_f32 v[156:157], v[120:121], v[160:161]
	v_lshl_add_u64 v[164:165], v[164:165], 1, s[22:23]
	v_cvt_pk_bf16_f32 v120, v124, v125
	v_cvt_pk_bf16_f32 v121, v126, v127
	v_cvt_pk_bf16_f32 v122, v156, v157
	v_cvt_pk_bf16_f32 v123, v158, v159
	v_lshl_add_u64 v[228:229], v[172:173], 0, v[230:231]
	v_lshl_add_u64 v[232:233], v[172:173], 0, v[244:245]
	ds_swizzle_b32 v236, v156 offset:swizzle(SWAP,8)
	ds_swizzle_b32 v237, v157 offset:swizzle(SWAP,8)
	ds_swizzle_b32 v238, v158 offset:swizzle(SWAP,8)
	ds_swizzle_b32 v239, v159 offset:swizzle(SWAP,8)
	ds_swizzle_b32 v240, v124 offset:swizzle(SWAP,8)
	ds_swizzle_b32 v241, v125 offset:swizzle(SWAP,8)
	ds_swizzle_b32 v242, v126 offset:swizzle(SWAP,8)
	ds_swizzle_b32 v243, v127 offset:swizzle(SWAP,8)
	s_waitcnt lgkmcnt(0)
	v_cndmask_b32_e64 v236, v236, v124, s[98:99]
	v_cndmask_b32_e64 v237, v237, v125, s[98:99]
	v_cndmask_b32_e64 v238, v238, v126, s[98:99]
	v_cndmask_b32_e64 v239, v239, v127, s[98:99]
	v_cndmask_b32_e64 v240, v156, v240, s[98:99]
	v_cndmask_b32_e64 v241, v157, v241, s[98:99]
	v_cndmask_b32_e64 v242, v158, v242, s[98:99]
	v_cndmask_b32_e64 v243, v159, v243, s[98:99]
	global_store_dwordx4 v[228:229], v[236:239], off
	global_store_dwordx4 v[232:233], v[240:243], off
	global_store_dwordx4 v[164:165], v[120:123], off
	v_lshl_add_u64 v[228:229], v[172:173], 0, v[230:231]
	v_lshl_add_u64 v[232:233], v[172:173], 0, v[244:245]
	global_load_dwordx4 v[246:249], v[228:229], off offset:512
	global_load_dwordx4 v[236:239], v[232:233], off offset:512
	v_mul_f32_e32 v122, v125, v125
	v_mul_f32_e32 v123, v127, v127
	v_mul_f32_e32 v125, v157, v157
	v_mul_f32_e32 v127, v159, v159
	v_fmac_f32_e32 v122, v124, v124
	v_fmac_f32_e32 v123, v126, v126
	v_fmac_f32_e32 v125, v156, v156
	v_fmac_f32_e32 v127, v158, v158
	v_add_f32_e32 v122, v122, v123
	v_add_f32_e32 v123, v125, v127
	v_add_f32_e32 v126, v122, v123
	v_and_b32_e32 v121, 64, v154
	v_xor_b32_e32 v120, 16, v154
	v_add_u32_e32 v121, 64, v121
	v_cmp_lt_i32_e32 vcc, v120, v121
	s_lshl_b32 s22, s6, 2
	s_ashr_i32 s23, s22, 31
	v_cndmask_b32_e32 v120, v154, v120, vcc
	v_lshlrev_b32_e32 v120, 2, v120
	v_cmp_lt_i32_e32 vcc, v155, v121
	s_waitcnt vmcnt(0)
	ds_swizzle_b32 v168, v246 offset:swizzle(SWAP,8)
	ds_swizzle_b32 v169, v247 offset:swizzle(SWAP,8)
	ds_swizzle_b32 v170, v248 offset:swizzle(SWAP,8)
	ds_swizzle_b32 v171, v249 offset:swizzle(SWAP,8)
	ds_swizzle_b32 v160, v236 offset:swizzle(SWAP,8)
	ds_swizzle_b32 v161, v237 offset:swizzle(SWAP,8)
	ds_swizzle_b32 v162, v238 offset:swizzle(SWAP,8)
	ds_swizzle_b32 v163, v239 offset:swizzle(SWAP,8)
	s_waitcnt lgkmcnt(0)
	v_cndmask_b32_e64 v160, v160, v246, s[98:99]
	v_cndmask_b32_e64 v161, v161, v247, s[98:99]
	v_cndmask_b32_e64 v162, v162, v248, s[98:99]
	v_cndmask_b32_e64 v163, v163, v249, s[98:99]
	v_cndmask_b32_e64 v168, v236, v168, s[98:99]
	v_cndmask_b32_e64 v169, v237, v169, s[98:99]
	v_cndmask_b32_e64 v170, v238, v170, s[98:99]
	v_cndmask_b32_e64 v171, v239, v171, s[98:99]
	v_pk_add_f32 v[118:119], v[118:119], v[162:163]
	v_pk_add_f32 v[116:117], v[116:117], v[160:161]
	s_waitcnt vmcnt(0)
	v_pk_add_f32 v[124:125], v[114:115], v[170:171]
	v_pk_add_f32 v[122:123], v[112:113], v[168:169]
	v_mul_f32_e32 v112, v117, v117
	v_mul_f32_e32 v113, v119, v119
	v_mul_f32_e32 v114, v123, v123
	v_mul_f32_e32 v115, v125, v125
	v_fmac_f32_e32 v112, v116, v116
	v_fmac_f32_e32 v113, v118, v118
	v_fmac_f32_e32 v114, v122, v122
	v_fmac_f32_e32 v115, v124, v124
	v_add_f32_e32 v112, v112, v113
	v_add_f32_e32 v113, v114, v115
	v_add_f32_e32 v112, v112, v113
	v_add_f32_e32 v112, v126, v112
	ds_bpermute_b32 v113, v120, v112
	v_cndmask_b32_e32 v114, v154, v155, vcc
	v_lshlrev_b32_e32 v114, 2, v114
	v_lshl_add_u64 v[228:229], v[172:173], 0, v[230:231]
	v_lshl_add_u64 v[232:233], v[172:173], 0, v[244:245]
	ds_swizzle_b32 v236, v122 offset:swizzle(SWAP,8)
	ds_swizzle_b32 v237, v123 offset:swizzle(SWAP,8)
	ds_swizzle_b32 v238, v124 offset:swizzle(SWAP,8)
	ds_swizzle_b32 v239, v125 offset:swizzle(SWAP,8)
	ds_swizzle_b32 v240, v116 offset:swizzle(SWAP,8)
	ds_swizzle_b32 v241, v117 offset:swizzle(SWAP,8)
	ds_swizzle_b32 v242, v118 offset:swizzle(SWAP,8)
	ds_swizzle_b32 v243, v119 offset:swizzle(SWAP,8)
	s_waitcnt lgkmcnt(0)
	v_cndmask_b32_e64 v236, v236, v116, s[98:99]
	v_cndmask_b32_e64 v237, v237, v117, s[98:99]
	v_cndmask_b32_e64 v238, v238, v118, s[98:99]
	v_cndmask_b32_e64 v239, v239, v119, s[98:99]
	v_cndmask_b32_e64 v240, v122, v240, s[98:99]
	v_cndmask_b32_e64 v241, v123, v241, s[98:99]
	v_cndmask_b32_e64 v242, v124, v242, s[98:99]
	v_cndmask_b32_e64 v243, v125, v243, s[98:99]
	global_store_dwordx4 v[228:229], v[236:239], off offset:512
	global_store_dwordx4 v[232:233], v[240:243], off offset:512
	s_waitcnt lgkmcnt(0)
	v_add_f32_e32 v112, v112, v113
	ds_bpermute_b32 v113, v114, v112
	v_cvt_pk_bf16_f32 v116, v116, v117
	v_cvt_pk_bf16_f32 v117, v118, v119
	v_cvt_pk_bf16_f32 v118, v122, v123
	v_cvt_pk_bf16_f32 v119, v124, v125
	global_store_dwordx4 v[164:165], v[116:119], off offset:256
	s_and_saveexec_b64 s[24:25], s[2:3]
	s_cbranch_execz .LBB0_847
	v_readlane_b32 s26, v254, 41
	s_waitcnt lgkmcnt(0)
	v_add_f32_e32 v115, v112, v113
	v_lshlrev_b64 v[112:113], 6, v[146:147]
	v_readlane_b32 s27, v254, 42
	s_lshl_b32 s6, s38, 2
	s_nop 0
	v_lshl_add_u64 v[112:113], s[26:27], 0, v[112:113]
	v_lshl_add_u64 v[112:113], s[22:23], 2, v[112:113]
	v_lshl_add_u64 v[112:113], v[112:113], 0, s[6:7]
	global_store_dword v[112:113], v115, off
; __device__ __forceinline__ unsigned cvt_pk_bf16(float lo, float hi) { const f32x2_t v = {lo, hi}; const bf16x2_t b = __builtin_convertvector(v, bf16x2_t); return __builtin_bit_cast(unsigned, b); }
;     __device__ __forceinline__ void operator()(const f32x4 (&acc)[2][2][4][2], const Unit& u, int wr, int wc, int fr, int fq, const PG8_LAS float*) const {
;     ...
;             for (int m = 0; m < 4; ++m) { const int row = row0 + ai * HALF + m * 16; const size_t off = (size_t)row * ldc + col0; float ss = 0.f;
; #pragma unroll
;                 for (int bj = 0; bj < 2; ++bj) {
;                     const f32x4 b0 = *(const f32x4*)(base + off + bj * HALF), b1 = *(const f32x4*)(base + off + bj * HALF + 4);
;                     const f32x4 v0 = b0 + acc[ai][bj][m][0], v1 = b1 + acc[ai][bj][m][1];
;                     *(f32x4*)(out + off + bj * HALF) = v0; *(f32x4*)(out + off + bj * HALF + 4) = v1;
;                     if (xb) { u32x4 w; w.x = cvt_pk_bf16(v0[0], v0[1]); w.y = cvt_pk_bf16(v0[2], v0[3]); w.z = cvt_pk_bf16(v1[0], v1[1]); w.w = cvt_pk_bf16(v1[2], v1[3]);
;                         *(u32x4*)(xb + off + bj * HALF) = w;
;                         ss += ((v0[0] * v0[0] + v0[1] * v0[1]) + (v0[2] * v0[2] + v0[3] * v0[3])) + ((v1[0] * v1[0] + v1[1] * v1[1]) + (v1[2] * v1[2] + v1[3] * v1[3])); } }
;                 if (xb) { ss += __shfl_xor(ss, 16); ss += __shfl_xor(ss, 32); if (fq == 0) ssq[(size_t)row * 16 + u.pn * 4 + wc] = ss; } }
.LBB0_847:
	s_or_b64 exec, exec, s[24:25]
	v_or_b32_e32 v112, 16, v146
	s_waitcnt lgkmcnt(0)
	v_ashrrev_i32_e32 v113, 31, v112
	v_lshlrev_b64 v[116:117], 10, v[112:113]
	v_lshl_add_u64 v[126:127], v[116:117], 0, v[144:145]
	v_lshl_add_u64 v[156:157], v[126:127], 2, s[68:69]
	v_lshl_add_u64 v[228:229], v[156:157], 0, v[230:231]
	v_lshl_add_u64 v[232:233], v[156:157], 0, v[244:245]
	global_load_dwordx4 v[246:249], v[228:229], off
	global_load_dwordx4 v[236:239], v[232:233], off
	v_readlane_b32 s24, v254, 39
	v_readlane_b32 s25, v254, 40
	s_waitcnt vmcnt(0)
	ds_swizzle_b32 v122, v246 offset:swizzle(SWAP,8)
	ds_swizzle_b32 v123, v247 offset:swizzle(SWAP,8)
	ds_swizzle_b32 v124, v248 offset:swizzle(SWAP,8)
	ds_swizzle_b32 v125, v249 offset:swizzle(SWAP,8)
	ds_swizzle_b32 v116, v236 offset:swizzle(SWAP,8)
	ds_swizzle_b32 v117, v237 offset:swizzle(SWAP,8)
	ds_swizzle_b32 v118, v238 offset:swizzle(SWAP,8)
	ds_swizzle_b32 v119, v239 offset:swizzle(SWAP,8)
	s_waitcnt lgkmcnt(0)
	v_cndmask_b32_e64 v116, v116, v246, s[98:99]
	v_cndmask_b32_e64 v117, v117, v247, s[98:99]
	v_cndmask_b32_e64 v118, v118, v248, s[98:99]
	v_cndmask_b32_e64 v119, v119, v249, s[98:99]
	v_cndmask_b32_e64 v122, v236, v122, s[98:99]
	v_cndmask_b32_e64 v123, v237, v123, s[98:99]
	v_cndmask_b32_e64 v124, v238, v124, s[98:99]
	v_cndmask_b32_e64 v125, v239, v125, s[98:99]
	v_pk_add_f32 v[110:111], v[110:111], v[118:119]
	v_pk_add_f32 v[108:109], v[108:109], v[116:117]
	s_waitcnt vmcnt(0)
	v_pk_add_f32 v[106:107], v[106:107], v[124:125]
	v_pk_add_f32 v[104:105], v[104:105], v[122:123]
	v_lshl_add_u64 v[126:127], v[126:127], 1, s[24:25]
	v_cvt_pk_bf16_f32 v116, v108, v109
	v_cvt_pk_bf16_f32 v117, v110, v111
	v_cvt_pk_bf16_f32 v118, v104, v105
	v_cvt_pk_bf16_f32 v119, v106, v107
	v_lshl_add_u64 v[228:229], v[156:157], 0, v[230:231]
	v_lshl_add_u64 v[232:233], v[156:157], 0, v[244:245]
	ds_swizzle_b32 v236, v104 offset:swizzle(SWAP,8)
	ds_swizzle_b32 v237, v105 offset:swizzle(SWAP,8)
	ds_swizzle_b32 v238, v106 offset:swizzle(SWAP,8)
	ds_swizzle_b32 v239, v107 offset:swizzle(SWAP,8)
	ds_swizzle_b32 v240, v108 offset:swizzle(SWAP,8)
	ds_swizzle_b32 v241, v109 offset:swizzle(SWAP,8)
	ds_swizzle_b32 v242, v110 offset:swizzle(SWAP,8)
	ds_swizzle_b32 v243, v111 offset:swizzle(SWAP,8)
	s_waitcnt lgkmcnt(0)
	v_cndmask_b32_e64 v236, v236, v108, s[98:99]
	v_cndmask_b32_e64 v237, v237, v109, s[98:99]
	v_cndmask_b32_e64 v238, v238, v110, s[98:99]
	v_cndmask_b32_e64 v239, v239, v111, s[98:99]
	v_cndmask_b32_e64 v240, v104, v240, s[98:99]
	v_cndmask_b32_e64 v241, v105, v241, s[98:99]
	v_cndmask_b32_e64 v242, v106, v242, s[98:99]
	v_cndmask_b32_e64 v243, v107, v243, s[98:99]
	global_store_dwordx4 v[228:229], v[236:239], off
	global_store_dwordx4 v[232:233], v[240:243], off
	global_store_dwordx4 v[126:127], v[116:119], off
	v_lshl_add_u64 v[228:229], v[156:157], 0, v[230:231]
	v_lshl_add_u64 v[232:233], v[156:157], 0, v[244:245]
	global_load_dwordx4 v[246:249], v[228:229], off offset:512
	global_load_dwordx4 v[236:239], v[232:233], off offset:512
	s_nop 0
	v_mul_f32_e32 v109, v109, v109
	v_mul_f32_e32 v111, v111, v111
	v_mul_f32_e32 v105, v105, v105
	v_mul_f32_e32 v107, v107, v107
	v_fmac_f32_e32 v109, v108, v108
	v_fmac_f32_e32 v111, v110, v110
	v_fmac_f32_e32 v105, v104, v104
	v_fmac_f32_e32 v107, v106, v106
	v_add_f32_e32 v104, v109, v111
	v_add_f32_e32 v105, v105, v107
	v_add_f32_e32 v108, v104, v105
	s_waitcnt vmcnt(0)
	ds_swizzle_b32 v122, v246 offset:swizzle(SWAP,8)
	ds_swizzle_b32 v123, v247 offset:swizzle(SWAP,8)
	ds_swizzle_b32 v124, v248 offset:swizzle(SWAP,8)
	ds_swizzle_b32 v125, v249 offset:swizzle(SWAP,8)
	ds_swizzle_b32 v116, v236 offset:swizzle(SWAP,8)
	ds_swizzle_b32 v117, v237 offset:swizzle(SWAP,8)
	ds_swizzle_b32 v118, v238 offset:swizzle(SWAP,8)
	ds_swizzle_b32 v119, v239 offset:swizzle(SWAP,8)
	s_waitcnt lgkmcnt(0)
	v_cndmask_b32_e64 v116, v116, v246, s[98:99]
	v_cndmask_b32_e64 v117, v117, v247, s[98:99]
	v_cndmask_b32_e64 v118, v118, v248, s[98:99]
	v_cndmask_b32_e64 v119, v119, v249, s[98:99]
	v_cndmask_b32_e64 v122, v236, v122, s[98:99]
	v_cndmask_b32_e64 v123, v237, v123, s[98:99]
	v_cndmask_b32_e64 v124, v238, v124, s[98:99]
	v_cndmask_b32_e64 v125, v239, v125, s[98:99]
	v_pk_add_f32 v[102:103], v[102:103], v[118:119]
	v_pk_add_f32 v[100:101], v[100:101], v[116:117]
	s_waitcnt vmcnt(0)
	v_pk_add_f32 v[106:107], v[98:99], v[124:125]
	v_pk_add_f32 v[104:105], v[96:97], v[122:123]
	v_mul_f32_e32 v96, v101, v101
	v_mul_f32_e32 v97, v103, v103
	v_mul_f32_e32 v98, v105, v105
	v_mul_f32_e32 v99, v107, v107
	v_fmac_f32_e32 v96, v100, v100
	v_fmac_f32_e32 v97, v102, v102
	v_fmac_f32_e32 v98, v104, v104
	v_fmac_f32_e32 v99, v106, v106
	v_add_f32_e32 v96, v96, v97
	v_add_f32_e32 v97, v98, v99
	v_add_f32_e32 v96, v96, v97
	v_add_f32_e32 v96, v108, v96
	ds_bpermute_b32 v97, v120, v96
	v_lshl_add_u64 v[228:229], v[156:157], 0, v[230:231]
	v_lshl_add_u64 v[232:233], v[156:157], 0, v[244:245]
	ds_swizzle_b32 v236, v104 offset:swizzle(SWAP,8)
	ds_swizzle_b32 v237, v105 offset:swizzle(SWAP,8)
	ds_swizzle_b32 v238, v106 offset:swizzle(SWAP,8)
	ds_swizzle_b32 v239, v107 offset:swizzle(SWAP,8)
	ds_swizzle_b32 v240, v100 offset:swizzle(SWAP,8)
	ds_swizzle_b32 v241, v101 offset:swizzle(SWAP,8)
	ds_swizzle_b32 v242, v102 offset:swizzle(SWAP,8)
	ds_swizzle_b32 v243, v103 offset:swizzle(SWAP,8)
	s_waitcnt lgkmcnt(0)
	v_cndmask_b32_e64 v236, v236, v100, s[98:99]
	v_cndmask_b32_e64 v237, v237, v101, s[98:99]
	v_cndmask_b32_e64 v238, v238, v102, s[98:99]
	v_cndmask_b32_e64 v239, v239, v103, s[98:99]
	v_cndmask_b32_e64 v240, v104, v240, s[98:99]
	v_cndmask_b32_e64 v241, v105, v241, s[98:99]
	v_cndmask_b32_e64 v242, v106, v242, s[98:99]
	v_cndmask_b32_e64 v243, v107, v243, s[98:99]
	global_store_dwordx4 v[228:229], v[236:239], off offset:512
	global_store_dwordx4 v[232:233], v[240:243], off offset:512
	v_cvt_pk_bf16_f32 v98, v100, v101
	v_cvt_pk_bf16_f32 v99, v102, v103
	v_cvt_pk_bf16_f32 v100, v104, v105
	s_waitcnt lgkmcnt(0)
	v_add_f32_e32 v96, v96, v97
	ds_bpermute_b32 v97, v114, v96
	v_cvt_pk_bf16_f32 v101, v106, v107
	global_store_dwordx4 v[126:127], v[98:101], off offset:256
	s_and_saveexec_b64 s[24:25], s[2:3]
	s_cbranch_execz .LBB0_849
	v_readlane_b32 s26, v254, 41
	s_waitcnt lgkmcnt(0)
	v_add_f32_e32 v98, v96, v97
	v_lshlrev_b64 v[96:97], 6, v[112:113]
	v_readlane_b32 s27, v254, 42
	s_lshl_b32 s6, s38, 2
	s_nop 0
	v_lshl_add_u64 v[96:97], s[26:27], 0, v[96:97]
	v_lshl_add_u64 v[96:97], s[22:23], 2, v[96:97]
	v_lshl_add_u64 v[96:97], v[96:97], 0, s[6:7]
	global_store_dword v[96:97], v98, off
; __device__ __forceinline__ unsigned cvt_pk_bf16(float lo, float hi) { const f32x2_t v = {lo, hi}; const bf16x2_t b = __builtin_convertvector(v, bf16x2_t); return __builtin_bit_cast(unsigned, b); }
;     __device__ __forceinline__ void operator()(const f32x4 (&acc)[2][2][4][2], const Unit& u, int wr, int wc, int fr, int fq, const PG8_LAS float*) const {
;     ...
;             for (int m = 0; m < 4; ++m) { const int row = row0 + ai * HALF + m * 16; const size_t off = (size_t)row * ldc + col0; float ss = 0.f;
; #pragma unroll
;                 for (int bj = 0; bj < 2; ++bj) {
;                     const f32x4 b0 = *(const f32x4*)(base + off + bj * HALF), b1 = *(const f32x4*)(base + off + bj * HALF + 4);
;                     const f32x4 v0 = b0 + acc[ai][bj][m][0], v1 = b1 + acc[ai][bj][m][1];
;                     *(f32x4*)(out + off + bj * HALF) = v0; *(f32x4*)(out + off + bj * HALF + 4) = v1;
;                     if (xb) { u32x4 w; w.x = cvt_pk_bf16(v0[0], v0[1]); w.y = cvt_pk_bf16(v0[2], v0[3]); w.z = cvt_pk_bf16(v1[0], v1[1]); w.w = cvt_pk_bf16(v1[2], v1[3]);
;                         *(u32x4*)(xb + off + bj * HALF) = w;
;                         ss += ((v0[0] * v0[0] + v0[1] * v0[1]) + (v0[2] * v0[2] + v0[3] * v0[3])) + ((v1[0] * v1[0] + v1[1] * v1[1]) + (v1[2] * v1[2] + v1[3] * v1[3])); } }
;                 if (xb) { ss += __shfl_xor(ss, 16); ss += __shfl_xor(ss, 32); if (fq == 0) ssq[(size_t)row * 16 + u.pn * 4 + wc] = ss; } }
.LBB0_849:
	s_or_b64 exec, exec, s[24:25]
	v_or_b32_e32 v96, 32, v146
	s_waitcnt lgkmcnt(0)
	v_ashrrev_i32_e32 v97, 31, v96
	v_lshlrev_b64 v[98:99], 10, v[96:97]
	v_lshl_add_u64 v[106:107], v[98:99], 0, v[144:145]
	v_lshl_add_u64 v[108:109], v[106:107], 2, s[68:69]
	v_lshl_add_u64 v[228:229], v[108:109], 0, v[230:231]
	v_lshl_add_u64 v[232:233], v[108:109], 0, v[244:245]
	global_load_dwordx4 v[246:249], v[228:229], off
	global_load_dwordx4 v[236:239], v[232:233], off
	v_readlane_b32 s24, v254, 39
	v_readlane_b32 s25, v254, 40
	s_waitcnt vmcnt(0)
	ds_swizzle_b32 v102, v246 offset:swizzle(SWAP,8)
	ds_swizzle_b32 v103, v247 offset:swizzle(SWAP,8)
	ds_swizzle_b32 v104, v248 offset:swizzle(SWAP,8)
	ds_swizzle_b32 v105, v249 offset:swizzle(SWAP,8)
	ds_swizzle_b32 v98, v236 offset:swizzle(SWAP,8)
	ds_swizzle_b32 v99, v237 offset:swizzle(SWAP,8)
	ds_swizzle_b32 v100, v238 offset:swizzle(SWAP,8)
	ds_swizzle_b32 v101, v239 offset:swizzle(SWAP,8)
	s_waitcnt lgkmcnt(0)
	v_cndmask_b32_e64 v98, v98, v246, s[98:99]
	v_cndmask_b32_e64 v99, v99, v247, s[98:99]
	v_cndmask_b32_e64 v100, v100, v248, s[98:99]
	v_cndmask_b32_e64 v101, v101, v249, s[98:99]
	v_cndmask_b32_e64 v102, v236, v102, s[98:99]
	v_cndmask_b32_e64 v103, v237, v103, s[98:99]
	v_cndmask_b32_e64 v104, v238, v104, s[98:99]
	v_cndmask_b32_e64 v105, v239, v105, s[98:99]
	v_pk_add_f32 v[94:95], v[94:95], v[100:101]
	v_pk_add_f32 v[92:93], v[92:93], v[98:99]
	s_waitcnt vmcnt(0)
	v_pk_add_f32 v[90:91], v[90:91], v[104:105]
	v_pk_add_f32 v[88:89], v[88:89], v[102:103]
	v_lshl_add_u64 v[106:107], v[106:107], 1, s[24:25]
	v_cvt_pk_bf16_f32 v98, v92, v93
	v_cvt_pk_bf16_f32 v99, v94, v95
	v_cvt_pk_bf16_f32 v100, v88, v89
	v_cvt_pk_bf16_f32 v101, v90, v91
	v_lshl_add_u64 v[228:229], v[108:109], 0, v[230:231]
	v_lshl_add_u64 v[232:233], v[108:109], 0, v[244:245]
	ds_swizzle_b32 v236, v88 offset:swizzle(SWAP,8)
	ds_swizzle_b32 v237, v89 offset:swizzle(SWAP,8)
	ds_swizzle_b32 v238, v90 offset:swizzle(SWAP,8)
	ds_swizzle_b32 v239, v91 offset:swizzle(SWAP,8)
	ds_swizzle_b32 v240, v92 offset:swizzle(SWAP,8)
	ds_swizzle_b32 v241, v93 offset:swizzle(SWAP,8)
	ds_swizzle_b32 v242, v94 offset:swizzle(SWAP,8)
	ds_swizzle_b32 v243, v95 offset:swizzle(SWAP,8)
	s_waitcnt lgkmcnt(0)
	v_cndmask_b32_e64 v236, v236, v92, s[98:99]
	v_cndmask_b32_e64 v237, v237, v93, s[98:99]
	v_cndmask_b32_e64 v238, v238, v94, s[98:99]
	v_cndmask_b32_e64 v239, v239, v95, s[98:99]
	v_cndmask_b32_e64 v240, v88, v240, s[98:99]
	v_cndmask_b32_e64 v241, v89, v241, s[98:99]
	v_cndmask_b32_e64 v242, v90, v242, s[98:99]
	v_cndmask_b32_e64 v243, v91, v243, s[98:99]
	global_store_dwordx4 v[228:229], v[236:239], off
	global_store_dwordx4 v[232:233], v[240:243], off
	global_store_dwordx4 v[106:107], v[98:101], off
	v_lshl_add_u64 v[228:229], v[108:109], 0, v[230:231]
	v_lshl_add_u64 v[232:233], v[108:109], 0, v[244:245]
	global_load_dwordx4 v[246:249], v[228:229], off offset:512
	global_load_dwordx4 v[236:239], v[232:233], off offset:512
	s_nop 0
	v_mul_f32_e32 v93, v93, v93
	v_mul_f32_e32 v95, v95, v95
	v_mul_f32_e32 v89, v89, v89
	v_mul_f32_e32 v91, v91, v91
	v_fmac_f32_e32 v93, v92, v92
	v_fmac_f32_e32 v95, v94, v94
	v_fmac_f32_e32 v89, v88, v88
	v_fmac_f32_e32 v91, v90, v90
	v_add_f32_e32 v88, v93, v95
	v_add_f32_e32 v89, v89, v91
	v_add_f32_e32 v92, v88, v89
	s_waitcnt vmcnt(0)
	ds_swizzle_b32 v102, v246 offset:swizzle(SWAP,8)
	ds_swizzle_b32 v103, v247 offset:swizzle(SWAP,8)
	ds_swizzle_b32 v104, v248 offset:swizzle(SWAP,8)
	ds_swizzle_b32 v105, v249 offset:swizzle(SWAP,8)
	ds_swizzle_b32 v98, v236 offset:swizzle(SWAP,8)
	ds_swizzle_b32 v99, v237 offset:swizzle(SWAP,8)
	ds_swizzle_b32 v100, v238 offset:swizzle(SWAP,8)
	ds_swizzle_b32 v101, v239 offset:swizzle(SWAP,8)
	s_waitcnt lgkmcnt(0)
	v_cndmask_b32_e64 v98, v98, v246, s[98:99]
	v_cndmask_b32_e64 v99, v99, v247, s[98:99]
	v_cndmask_b32_e64 v100, v100, v248, s[98:99]
	v_cndmask_b32_e64 v101, v101, v249, s[98:99]
	v_cndmask_b32_e64 v102, v236, v102, s[98:99]
	v_cndmask_b32_e64 v103, v237, v103, s[98:99]
	v_cndmask_b32_e64 v104, v238, v104, s[98:99]
	v_cndmask_b32_e64 v105, v239, v105, s[98:99]
	v_pk_add_f32 v[86:87], v[86:87], v[100:101]
	v_pk_add_f32 v[84:85], v[84:85], v[98:99]
	s_waitcnt vmcnt(0)
	v_pk_add_f32 v[90:91], v[82:83], v[104:105]
	v_pk_add_f32 v[88:89], v[80:81], v[102:103]
	v_mul_f32_e32 v80, v85, v85
	v_mul_f32_e32 v81, v87, v87
	v_mul_f32_e32 v82, v89, v89
	v_mul_f32_e32 v83, v91, v91
	v_fmac_f32_e32 v80, v84, v84
	v_fmac_f32_e32 v81, v86, v86
	v_fmac_f32_e32 v82, v88, v88
	v_fmac_f32_e32 v83, v90, v90
	v_add_f32_e32 v80, v80, v81
	v_add_f32_e32 v81, v82, v83
	v_add_f32_e32 v80, v80, v81
	v_add_f32_e32 v80, v92, v80
	ds_bpermute_b32 v81, v120, v80
	v_lshl_add_u64 v[228:229], v[108:109], 0, v[230:231]
	v_lshl_add_u64 v[232:233], v[108:109], 0, v[244:245]
	ds_swizzle_b32 v236, v88 offset:swizzle(SWAP,8)
	ds_swizzle_b32 v237, v89 offset:swizzle(SWAP,8)
	ds_swizzle_b32 v238, v90 offset:swizzle(SWAP,8)
	ds_swizzle_b32 v239, v91 offset:swizzle(SWAP,8)
	ds_swizzle_b32 v240, v84 offset:swizzle(SWAP,8)
	ds_swizzle_b32 v241, v85 offset:swizzle(SWAP,8)
	ds_swizzle_b32 v242, v86 offset:swizzle(SWAP,8)
	ds_swizzle_b32 v243, v87 offset:swizzle(SWAP,8)
	s_waitcnt lgkmcnt(0)
	v_cndmask_b32_e64 v236, v236, v84, s[98:99]
	v_cndmask_b32_e64 v237, v237, v85, s[98:99]
	v_cndmask_b32_e64 v238, v238, v86, s[98:99]
	v_cndmask_b32_e64 v239, v239, v87, s[98:99]
	v_cndmask_b32_e64 v240, v88, v240, s[98:99]
	v_cndmask_b32_e64 v241, v89, v241, s[98:99]
	v_cndmask_b32_e64 v242, v90, v242, s[98:99]
	v_cndmask_b32_e64 v243, v91, v243, s[98:99]
	global_store_dwordx4 v[228:229], v[236:239], off offset:512
	global_store_dwordx4 v[232:233], v[240:243], off offset:512
	v_cvt_pk_bf16_f32 v82, v84, v85
	v_cvt_pk_bf16_f32 v83, v86, v87
	v_cvt_pk_bf16_f32 v84, v88, v89
	s_waitcnt lgkmcnt(0)
	v_add_f32_e32 v80, v80, v81
	ds_bpermute_b32 v81, v114, v80
	v_cvt_pk_bf16_f32 v85, v90, v91
	global_store_dwordx4 v[106:107], v[82:85], off offset:256
	s_and_saveexec_b64 s[24:25], s[2:3]
	s_cbranch_execz .LBB0_851
	v_readlane_b32 s26, v254, 41
	s_waitcnt lgkmcnt(0)
	v_add_f32_e32 v82, v80, v81
	v_lshlrev_b64 v[80:81], 6, v[96:97]
	v_readlane_b32 s27, v254, 42
	s_lshl_b32 s6, s38, 2
	s_nop 0
	v_lshl_add_u64 v[80:81], s[26:27], 0, v[80:81]
	v_lshl_add_u64 v[80:81], s[22:23], 2, v[80:81]
	v_lshl_add_u64 v[80:81], v[80:81], 0, s[6:7]
	global_store_dword v[80:81], v82, off
; __device__ __forceinline__ unsigned cvt_pk_bf16(float lo, float hi) { const f32x2_t v = {lo, hi}; const bf16x2_t b = __builtin_convertvector(v, bf16x2_t); return __builtin_bit_cast(unsigned, b); }
;     __device__ __forceinline__ void operator()(const f32x4 (&acc)[2][2][4][2], const Unit& u, int wr, int wc, int fr, int fq, const PG8_LAS float*) const {
;     ...
;             for (int m = 0; m < 4; ++m) { const int row = row0 + ai * HALF + m * 16; const size_t off = (size_t)row * ldc + col0; float ss = 0.f;
; #pragma unroll
;                 for (int bj = 0; bj < 2; ++bj) {
;                     const f32x4 b0 = *(const f32x4*)(base + off + bj * HALF), b1 = *(const f32x4*)(base + off + bj * HALF + 4);
;                     const f32x4 v0 = b0 + acc[ai][bj][m][0], v1 = b1 + acc[ai][bj][m][1];
;                     *(f32x4*)(out + off + bj * HALF) = v0; *(f32x4*)(out + off + bj * HALF + 4) = v1;
;                     if (xb) { u32x4 w; w.x = cvt_pk_bf16(v0[0], v0[1]); w.y = cvt_pk_bf16(v0[2], v0[3]); w.z = cvt_pk_bf16(v1[0], v1[1]); w.w = cvt_pk_bf16(v1[2], v1[3]);
;                         *(u32x4*)(xb + off + bj * HALF) = w;
;                         ss += ((v0[0] * v0[0] + v0[1] * v0[1]) + (v0[2] * v0[2] + v0[3] * v0[3])) + ((v1[0] * v1[0] + v1[1] * v1[1]) + (v1[2] * v1[2] + v1[3] * v1[3])); } }
;                 if (xb) { ss += __shfl_xor(ss, 16); ss += __shfl_xor(ss, 32); if (fq == 0) ssq[(size_t)row * 16 + u.pn * 4 + wc] = ss; } }
.LBB0_851:
	s_or_b64 exec, exec, s[24:25]
	v_or_b32_e32 v80, 48, v146
	s_waitcnt lgkmcnt(0)
	v_ashrrev_i32_e32 v81, 31, v80
	v_lshlrev_b64 v[82:83], 10, v[80:81]
	v_lshl_add_u64 v[90:91], v[82:83], 0, v[144:145]
	v_lshl_add_u64 v[92:93], v[90:91], 2, s[68:69]
	v_lshl_add_u64 v[228:229], v[92:93], 0, v[230:231]
	v_lshl_add_u64 v[232:233], v[92:93], 0, v[244:245]
	global_load_dwordx4 v[246:249], v[228:229], off
	global_load_dwordx4 v[236:239], v[232:233], off
	v_readlane_b32 s24, v254, 39
	v_readlane_b32 s25, v254, 40
	s_waitcnt vmcnt(0)
	ds_swizzle_b32 v86, v246 offset:swizzle(SWAP,8)
	ds_swizzle_b32 v87, v247 offset:swizzle(SWAP,8)
	ds_swizzle_b32 v88, v248 offset:swizzle(SWAP,8)
	ds_swizzle_b32 v89, v249 offset:swizzle(SWAP,8)
	ds_swizzle_b32 v82, v236 offset:swizzle(SWAP,8)
	ds_swizzle_b32 v83, v237 offset:swizzle(SWAP,8)
	ds_swizzle_b32 v84, v238 offset:swizzle(SWAP,8)
	ds_swizzle_b32 v85, v239 offset:swizzle(SWAP,8)
	s_waitcnt lgkmcnt(0)
	v_cndmask_b32_e64 v82, v82, v246, s[98:99]
	v_cndmask_b32_e64 v83, v83, v247, s[98:99]
	v_cndmask_b32_e64 v84, v84, v248, s[98:99]
	v_cndmask_b32_e64 v85, v85, v249, s[98:99]
	v_cndmask_b32_e64 v86, v236, v86, s[98:99]
	v_cndmask_b32_e64 v87, v237, v87, s[98:99]
	v_cndmask_b32_e64 v88, v238, v88, s[98:99]
	v_cndmask_b32_e64 v89, v239, v89, s[98:99]
	v_pk_add_f32 v[78:79], v[78:79], v[84:85]
	v_pk_add_f32 v[76:77], v[76:77], v[82:83]
	s_waitcnt vmcnt(0)
	v_pk_add_f32 v[74:75], v[74:75], v[88:89]
	v_pk_add_f32 v[72:73], v[72:73], v[86:87]
	v_lshl_add_u64 v[90:91], v[90:91], 1, s[24:25]
	v_cvt_pk_bf16_f32 v82, v76, v77
	v_cvt_pk_bf16_f32 v83, v78, v79
	v_cvt_pk_bf16_f32 v84, v72, v73
	v_cvt_pk_bf16_f32 v85, v74, v75
	v_lshl_add_u64 v[228:229], v[92:93], 0, v[230:231]
	v_lshl_add_u64 v[232:233], v[92:93], 0, v[244:245]
	ds_swizzle_b32 v236, v72 offset:swizzle(SWAP,8)
	ds_swizzle_b32 v237, v73 offset:swizzle(SWAP,8)
	ds_swizzle_b32 v238, v74 offset:swizzle(SWAP,8)
	ds_swizzle_b32 v239, v75 offset:swizzle(SWAP,8)
	ds_swizzle_b32 v240, v76 offset:swizzle(SWAP,8)
	ds_swizzle_b32 v241, v77 offset:swizzle(SWAP,8)
	ds_swizzle_b32 v242, v78 offset:swizzle(SWAP,8)
	ds_swizzle_b32 v243, v79 offset:swizzle(SWAP,8)
	s_waitcnt lgkmcnt(0)
	v_cndmask_b32_e64 v236, v236, v76, s[98:99]
	v_cndmask_b32_e64 v237, v237, v77, s[98:99]
	v_cndmask_b32_e64 v238, v238, v78, s[98:99]
	v_cndmask_b32_e64 v239, v239, v79, s[98:99]
	v_cndmask_b32_e64 v240, v72, v240, s[98:99]
	v_cndmask_b32_e64 v241, v73, v241, s[98:99]
	v_cndmask_b32_e64 v242, v74, v242, s[98:99]
	v_cndmask_b32_e64 v243, v75, v243, s[98:99]
	global_store_dwordx4 v[228:229], v[236:239], off
	global_store_dwordx4 v[232:233], v[240:243], off
	global_store_dwordx4 v[90:91], v[82:85], off
	v_lshl_add_u64 v[228:229], v[92:93], 0, v[230:231]
	v_lshl_add_u64 v[232:233], v[92:93], 0, v[244:245]
	global_load_dwordx4 v[246:249], v[228:229], off offset:512
	global_load_dwordx4 v[236:239], v[232:233], off offset:512
	s_nop 0
	v_mul_f32_e32 v77, v77, v77
	v_mul_f32_e32 v79, v79, v79
	v_mul_f32_e32 v73, v73, v73
	v_mul_f32_e32 v75, v75, v75
	v_fmac_f32_e32 v77, v76, v76
	v_fmac_f32_e32 v79, v78, v78
	v_fmac_f32_e32 v73, v72, v72
	v_fmac_f32_e32 v75, v74, v74
	v_add_f32_e32 v72, v77, v79
	v_add_f32_e32 v73, v73, v75
	v_add_f32_e32 v76, v72, v73
	s_waitcnt vmcnt(0)
	ds_swizzle_b32 v86, v246 offset:swizzle(SWAP,8)
	ds_swizzle_b32 v87, v247 offset:swizzle(SWAP,8)
	ds_swizzle_b32 v88, v248 offset:swizzle(SWAP,8)
	ds_swizzle_b32 v89, v249 offset:swizzle(SWAP,8)
	ds_swizzle_b32 v82, v236 offset:swizzle(SWAP,8)
	ds_swizzle_b32 v83, v237 offset:swizzle(SWAP,8)
	ds_swizzle_b32 v84, v238 offset:swizzle(SWAP,8)
	ds_swizzle_b32 v85, v239 offset:swizzle(SWAP,8)
	s_waitcnt lgkmcnt(0)
	v_cndmask_b32_e64 v82, v82, v246, s[98:99]
	v_cndmask_b32_e64 v83, v83, v247, s[98:99]
	v_cndmask_b32_e64 v84, v84, v248, s[98:99]
	v_cndmask_b32_e64 v85, v85, v249, s[98:99]
	v_cndmask_b32_e64 v86, v236, v86, s[98:99]
	v_cndmask_b32_e64 v87, v237, v87, s[98:99]
	v_cndmask_b32_e64 v88, v238, v88, s[98:99]
	v_cndmask_b32_e64 v89, v239, v89, s[98:99]
	v_pk_add_f32 v[70:71], v[70:71], v[84:85]
	v_pk_add_f32 v[68:69], v[68:69], v[82:83]
	s_waitcnt vmcnt(0)
	v_pk_add_f32 v[74:75], v[66:67], v[88:89]
	v_pk_add_f32 v[72:73], v[64:65], v[86:87]
	v_mul_f32_e32 v64, v69, v69
	v_mul_f32_e32 v65, v71, v71
	v_mul_f32_e32 v66, v73, v73
	v_mul_f32_e32 v67, v75, v75
	v_fmac_f32_e32 v64, v68, v68
	v_fmac_f32_e32 v65, v70, v70
	v_fmac_f32_e32 v66, v72, v72
	v_fmac_f32_e32 v67, v74, v74
	v_add_f32_e32 v64, v64, v65
	v_add_f32_e32 v65, v66, v67
	v_add_f32_e32 v64, v64, v65
	v_add_f32_e32 v64, v76, v64
	ds_bpermute_b32 v65, v120, v64
	v_lshl_add_u64 v[228:229], v[92:93], 0, v[230:231]
	v_lshl_add_u64 v[232:233], v[92:93], 0, v[244:245]
	ds_swizzle_b32 v236, v72 offset:swizzle(SWAP,8)
	ds_swizzle_b32 v237, v73 offset:swizzle(SWAP,8)
	ds_swizzle_b32 v238, v74 offset:swizzle(SWAP,8)
	ds_swizzle_b32 v239, v75 offset:swizzle(SWAP,8)
	ds_swizzle_b32 v240, v68 offset:swizzle(SWAP,8)
	ds_swizzle_b32 v241, v69 offset:swizzle(SWAP,8)
	ds_swizzle_b32 v242, v70 offset:swizzle(SWAP,8)
	ds_swizzle_b32 v243, v71 offset:swizzle(SWAP,8)
	s_waitcnt lgkmcnt(0)
	v_cndmask_b32_e64 v236, v236, v68, s[98:99]
	v_cndmask_b32_e64 v237, v237, v69, s[98:99]
	v_cndmask_b32_e64 v238, v238, v70, s[98:99]
	v_cndmask_b32_e64 v239, v239, v71, s[98:99]
	v_cndmask_b32_e64 v240, v72, v240, s[98:99]
	v_cndmask_b32_e64 v241, v73, v241, s[98:99]
	v_cndmask_b32_e64 v242, v74, v242, s[98:99]
	v_cndmask_b32_e64 v243, v75, v243, s[98:99]
	global_store_dwordx4 v[228:229], v[236:239], off offset:512
	global_store_dwordx4 v[232:233], v[240:243], off offset:512
	v_cvt_pk_bf16_f32 v66, v68, v69
	v_cvt_pk_bf16_f32 v67, v70, v71
	v_cvt_pk_bf16_f32 v68, v72, v73
	s_waitcnt lgkmcnt(0)
	v_add_f32_e32 v64, v64, v65
	ds_bpermute_b32 v65, v114, v64
	v_cvt_pk_bf16_f32 v69, v74, v75
	global_store_dwordx4 v[90:91], v[66:69], off offset:256
	s_and_saveexec_b64 s[24:25], s[2:3]
	s_cbranch_execz .LBB0_853
	v_readlane_b32 s26, v254, 41
	s_waitcnt lgkmcnt(0)
	v_add_f32_e32 v66, v64, v65
	v_lshlrev_b64 v[64:65], 6, v[80:81]
	v_readlane_b32 s27, v254, 42
	s_lshl_b32 s6, s38, 2
	s_nop 0
	v_lshl_add_u64 v[64:65], s[26:27], 0, v[64:65]
	v_lshl_add_u64 v[64:65], s[22:23], 2, v[64:65]
	v_lshl_add_u64 v[64:65], v[64:65], 0, s[6:7]
	global_store_dword v[64:65], v66, off
; __device__ __forceinline__ unsigned cvt_pk_bf16(float lo, float hi) { const f32x2_t v = {lo, hi}; const bf16x2_t b = __builtin_convertvector(v, bf16x2_t); return __builtin_bit_cast(unsigned, b); }
;     __device__ __forceinline__ void operator()(const f32x4 (&acc)[2][2][4][2], const Unit& u, int wr, int wc, int fr, int fq, const PG8_LAS float*) const {
;     ...
;             for (int m = 0; m < 4; ++m) { const int row = row0 + ai * HALF + m * 16; const size_t off = (size_t)row * ldc + col0; float ss = 0.f;
; #pragma unroll
;                 for (int bj = 0; bj < 2; ++bj) {
;                     const f32x4 b0 = *(const f32x4*)(base + off + bj * HALF), b1 = *(const f32x4*)(base + off + bj * HALF + 4);
;                     const f32x4 v0 = b0 + acc[ai][bj][m][0], v1 = b1 + acc[ai][bj][m][1];
;                     *(f32x4*)(out + off + bj * HALF) = v0; *(f32x4*)(out + off + bj * HALF + 4) = v1;
;                     if (xb) { u32x4 w; w.x = cvt_pk_bf16(v0[0], v0[1]); w.y = cvt_pk_bf16(v0[2], v0[3]); w.z = cvt_pk_bf16(v1[0], v1[1]); w.w = cvt_pk_bf16(v1[2], v1[3]);
;                         *(u32x4*)(xb + off + bj * HALF) = w;
;                         ss += ((v0[0] * v0[0] + v0[1] * v0[1]) + (v0[2] * v0[2] + v0[3] * v0[3])) + ((v1[0] * v1[0] + v1[1] * v1[1]) + (v1[2] * v1[2] + v1[3] * v1[3])); } }
;                 if (xb) { ss += __shfl_xor(ss, 16); ss += __shfl_xor(ss, 32); if (fq == 0) ssq[(size_t)row * 16 + u.pn * 4 + wc] = ss; } }
.LBB0_853:
	s_or_b64 exec, exec, s[24:25]
	v_add_u32_e32 v64, 0x80, v146
	s_waitcnt lgkmcnt(0)
	v_ashrrev_i32_e32 v65, 31, v64
	v_lshlrev_b64 v[66:67], 10, v[64:65]
	v_lshl_add_u64 v[74:75], v[66:67], 0, v[144:145]
	v_lshl_add_u64 v[76:77], v[74:75], 2, s[68:69]
	v_lshl_add_u64 v[228:229], v[76:77], 0, v[230:231]
	v_lshl_add_u64 v[232:233], v[76:77], 0, v[244:245]
	global_load_dwordx4 v[246:249], v[228:229], off
	global_load_dwordx4 v[236:239], v[232:233], off
	v_readlane_b32 s24, v254, 39
	v_readlane_b32 s25, v254, 40
	s_waitcnt vmcnt(0)
	ds_swizzle_b32 v70, v246 offset:swizzle(SWAP,8)
	ds_swizzle_b32 v71, v247 offset:swizzle(SWAP,8)
	ds_swizzle_b32 v72, v248 offset:swizzle(SWAP,8)
	ds_swizzle_b32 v73, v249 offset:swizzle(SWAP,8)
	ds_swizzle_b32 v66, v236 offset:swizzle(SWAP,8)
	ds_swizzle_b32 v67, v237 offset:swizzle(SWAP,8)
	ds_swizzle_b32 v68, v238 offset:swizzle(SWAP,8)
	ds_swizzle_b32 v69, v239 offset:swizzle(SWAP,8)
	s_waitcnt lgkmcnt(0)
	v_cndmask_b32_e64 v66, v66, v246, s[98:99]
	v_cndmask_b32_e64 v67, v67, v247, s[98:99]
	v_cndmask_b32_e64 v68, v68, v248, s[98:99]
	v_cndmask_b32_e64 v69, v69, v249, s[98:99]
	v_cndmask_b32_e64 v70, v236, v70, s[98:99]
	v_cndmask_b32_e64 v71, v237, v71, s[98:99]
	v_cndmask_b32_e64 v72, v238, v72, s[98:99]
	v_cndmask_b32_e64 v73, v239, v73, s[98:99]
	v_pk_add_f32 v[62:63], v[62:63], v[68:69]
	v_pk_add_f32 v[60:61], v[60:61], v[66:67]
	s_waitcnt vmcnt(0)
	v_pk_add_f32 v[58:59], v[58:59], v[72:73]
	v_pk_add_f32 v[56:57], v[56:57], v[70:71]
	v_lshl_add_u64 v[74:75], v[74:75], 1, s[24:25]
	v_cvt_pk_bf16_f32 v66, v60, v61
	v_cvt_pk_bf16_f32 v67, v62, v63
	v_cvt_pk_bf16_f32 v68, v56, v57
	v_cvt_pk_bf16_f32 v69, v58, v59
	v_lshl_add_u64 v[228:229], v[76:77], 0, v[230:231]
	v_lshl_add_u64 v[232:233], v[76:77], 0, v[244:245]
	ds_swizzle_b32 v236, v56 offset:swizzle(SWAP,8)
	ds_swizzle_b32 v237, v57 offset:swizzle(SWAP,8)
	ds_swizzle_b32 v238, v58 offset:swizzle(SWAP,8)
	ds_swizzle_b32 v239, v59 offset:swizzle(SWAP,8)
	ds_swizzle_b32 v240, v60 offset:swizzle(SWAP,8)
	ds_swizzle_b32 v241, v61 offset:swizzle(SWAP,8)
	ds_swizzle_b32 v242, v62 offset:swizzle(SWAP,8)
	ds_swizzle_b32 v243, v63 offset:swizzle(SWAP,8)
	s_waitcnt lgkmcnt(0)
	v_cndmask_b32_e64 v236, v236, v60, s[98:99]
	v_cndmask_b32_e64 v237, v237, v61, s[98:99]
	v_cndmask_b32_e64 v238, v238, v62, s[98:99]
	v_cndmask_b32_e64 v239, v239, v63, s[98:99]
	v_cndmask_b32_e64 v240, v56, v240, s[98:99]
	v_cndmask_b32_e64 v241, v57, v241, s[98:99]
	v_cndmask_b32_e64 v242, v58, v242, s[98:99]
	v_cndmask_b32_e64 v243, v59, v243, s[98:99]
	global_store_dwordx4 v[228:229], v[236:239], off
	global_store_dwordx4 v[232:233], v[240:243], off
	global_store_dwordx4 v[74:75], v[66:69], off
	v_lshl_add_u64 v[228:229], v[76:77], 0, v[230:231]
	v_lshl_add_u64 v[232:233], v[76:77], 0, v[244:245]
	global_load_dwordx4 v[246:249], v[228:229], off offset:512
	global_load_dwordx4 v[236:239], v[232:233], off offset:512
	s_nop 0
	v_mul_f32_e32 v61, v61, v61
	v_mul_f32_e32 v63, v63, v63
	v_mul_f32_e32 v57, v57, v57
	v_mul_f32_e32 v59, v59, v59
	v_fmac_f32_e32 v61, v60, v60
	v_fmac_f32_e32 v63, v62, v62
	v_fmac_f32_e32 v57, v56, v56
	v_fmac_f32_e32 v59, v58, v58
	v_add_f32_e32 v56, v61, v63
	v_add_f32_e32 v57, v57, v59
	v_add_f32_e32 v60, v56, v57
	s_waitcnt vmcnt(0)
	ds_swizzle_b32 v70, v246 offset:swizzle(SWAP,8)
	ds_swizzle_b32 v71, v247 offset:swizzle(SWAP,8)
	ds_swizzle_b32 v72, v248 offset:swizzle(SWAP,8)
	ds_swizzle_b32 v73, v249 offset:swizzle(SWAP,8)
	ds_swizzle_b32 v66, v236 offset:swizzle(SWAP,8)
	ds_swizzle_b32 v67, v237 offset:swizzle(SWAP,8)
	ds_swizzle_b32 v68, v238 offset:swizzle(SWAP,8)
	ds_swizzle_b32 v69, v239 offset:swizzle(SWAP,8)
	s_waitcnt lgkmcnt(0)
	v_cndmask_b32_e64 v66, v66, v246, s[98:99]
	v_cndmask_b32_e64 v67, v67, v247, s[98:99]
	v_cndmask_b32_e64 v68, v68, v248, s[98:99]
	v_cndmask_b32_e64 v69, v69, v249, s[98:99]
	v_cndmask_b32_e64 v70, v236, v70, s[98:99]
	v_cndmask_b32_e64 v71, v237, v71, s[98:99]
	v_cndmask_b32_e64 v72, v238, v72, s[98:99]
	v_cndmask_b32_e64 v73, v239, v73, s[98:99]
	v_pk_add_f32 v[54:55], v[54:55], v[68:69]
	v_pk_add_f32 v[52:53], v[52:53], v[66:67]
	s_waitcnt vmcnt(0)
	v_pk_add_f32 v[58:59], v[50:51], v[72:73]
	v_pk_add_f32 v[56:57], v[48:49], v[70:71]
	v_mul_f32_e32 v48, v53, v53
	v_mul_f32_e32 v49, v55, v55
	v_mul_f32_e32 v50, v57, v57
	v_mul_f32_e32 v51, v59, v59
	v_fmac_f32_e32 v48, v52, v52
	v_fmac_f32_e32 v49, v54, v54
	v_fmac_f32_e32 v50, v56, v56
	v_fmac_f32_e32 v51, v58, v58
	v_add_f32_e32 v48, v48, v49
	v_add_f32_e32 v49, v50, v51
	v_add_f32_e32 v48, v48, v49
	v_add_f32_e32 v48, v60, v48
	ds_bpermute_b32 v49, v120, v48
	v_lshl_add_u64 v[228:229], v[76:77], 0, v[230:231]
	v_lshl_add_u64 v[232:233], v[76:77], 0, v[244:245]
	ds_swizzle_b32 v236, v56 offset:swizzle(SWAP,8)
	ds_swizzle_b32 v237, v57 offset:swizzle(SWAP,8)
	ds_swizzle_b32 v238, v58 offset:swizzle(SWAP,8)
	ds_swizzle_b32 v239, v59 offset:swizzle(SWAP,8)
	ds_swizzle_b32 v240, v52 offset:swizzle(SWAP,8)
	ds_swizzle_b32 v241, v53 offset:swizzle(SWAP,8)
	ds_swizzle_b32 v242, v54 offset:swizzle(SWAP,8)
	ds_swizzle_b32 v243, v55 offset:swizzle(SWAP,8)
	s_waitcnt lgkmcnt(0)
	v_cndmask_b32_e64 v236, v236, v52, s[98:99]
	v_cndmask_b32_e64 v237, v237, v53, s[98:99]
	v_cndmask_b32_e64 v238, v238, v54, s[98:99]
	v_cndmask_b32_e64 v239, v239, v55, s[98:99]
	v_cndmask_b32_e64 v240, v56, v240, s[98:99]
	v_cndmask_b32_e64 v241, v57, v241, s[98:99]
	v_cndmask_b32_e64 v242, v58, v242, s[98:99]
	v_cndmask_b32_e64 v243, v59, v243, s[98:99]
	global_store_dwordx4 v[228:229], v[236:239], off offset:512
	global_store_dwordx4 v[232:233], v[240:243], off offset:512
	v_cvt_pk_bf16_f32 v50, v52, v53
	v_cvt_pk_bf16_f32 v51, v54, v55
	v_cvt_pk_bf16_f32 v52, v56, v57
	s_waitcnt lgkmcnt(0)
	v_add_f32_e32 v48, v48, v49
	ds_bpermute_b32 v49, v114, v48
	v_cvt_pk_bf16_f32 v53, v58, v59
	global_store_dwordx4 v[74:75], v[50:53], off offset:256
	s_and_saveexec_b64 s[24:25], s[2:3]
	s_cbranch_execz .LBB0_855
	v_readlane_b32 s26, v254, 41
	s_waitcnt lgkmcnt(0)
	v_add_f32_e32 v50, v48, v49
	v_lshlrev_b64 v[48:49], 6, v[64:65]
	v_readlane_b32 s27, v254, 42
	s_lshl_b32 s6, s38, 2
	s_nop 0
	v_lshl_add_u64 v[48:49], s[26:27], 0, v[48:49]
	v_lshl_add_u64 v[48:49], s[22:23], 2, v[48:49]
	v_lshl_add_u64 v[48:49], v[48:49], 0, s[6:7]
	global_store_dword v[48:49], v50, off
; __device__ __forceinline__ unsigned cvt_pk_bf16(float lo, float hi) { const f32x2_t v = {lo, hi}; const bf16x2_t b = __builtin_convertvector(v, bf16x2_t); return __builtin_bit_cast(unsigned, b); }
;     __device__ __forceinline__ void operator()(const f32x4 (&acc)[2][2][4][2], const Unit& u, int wr, int wc, int fr, int fq, const PG8_LAS float*) const {
;     ...
;             for (int m = 0; m < 4; ++m) { const int row = row0 + ai * HALF + m * 16; const size_t off = (size_t)row * ldc + col0; float ss = 0.f;
; #pragma unroll
;                 for (int bj = 0; bj < 2; ++bj) {
;                     const f32x4 b0 = *(const f32x4*)(base + off + bj * HALF), b1 = *(const f32x4*)(base + off + bj * HALF + 4);
;                     const f32x4 v0 = b0 + acc[ai][bj][m][0], v1 = b1 + acc[ai][bj][m][1];
;                     *(f32x4*)(out + off + bj * HALF) = v0; *(f32x4*)(out + off + bj * HALF + 4) = v1;
;                     if (xb) { u32x4 w; w.x = cvt_pk_bf16(v0[0], v0[1]); w.y = cvt_pk_bf16(v0[2], v0[3]); w.z = cvt_pk_bf16(v1[0], v1[1]); w.w = cvt_pk_bf16(v1[2], v1[3]);
;                         *(u32x4*)(xb + off + bj * HALF) = w;
;                         ss += ((v0[0] * v0[0] + v0[1] * v0[1]) + (v0[2] * v0[2] + v0[3] * v0[3])) + ((v1[0] * v1[0] + v1[1] * v1[1]) + (v1[2] * v1[2] + v1[3] * v1[3])); } }
;                 if (xb) { ss += __shfl_xor(ss, 16); ss += __shfl_xor(ss, 32); if (fq == 0) ssq[(size_t)row * 16 + u.pn * 4 + wc] = ss; } }
.LBB0_855:
	s_or_b64 exec, exec, s[24:25]
	v_add_u32_e32 v48, 0x90, v146
	s_waitcnt lgkmcnt(0)
	v_ashrrev_i32_e32 v49, 31, v48
	v_lshlrev_b64 v[50:51], 10, v[48:49]
	v_lshl_add_u64 v[58:59], v[50:51], 0, v[144:145]
	v_lshl_add_u64 v[60:61], v[58:59], 2, s[68:69]
	v_lshl_add_u64 v[228:229], v[60:61], 0, v[230:231]
	v_lshl_add_u64 v[232:233], v[60:61], 0, v[244:245]
	global_load_dwordx4 v[246:249], v[228:229], off
	global_load_dwordx4 v[236:239], v[232:233], off
	v_readlane_b32 s24, v254, 39
	v_readlane_b32 s25, v254, 40
	s_waitcnt vmcnt(0)
	ds_swizzle_b32 v54, v246 offset:swizzle(SWAP,8)
	ds_swizzle_b32 v55, v247 offset:swizzle(SWAP,8)
	ds_swizzle_b32 v56, v248 offset:swizzle(SWAP,8)
	ds_swizzle_b32 v57, v249 offset:swizzle(SWAP,8)
	ds_swizzle_b32 v50, v236 offset:swizzle(SWAP,8)
	ds_swizzle_b32 v51, v237 offset:swizzle(SWAP,8)
	ds_swizzle_b32 v52, v238 offset:swizzle(SWAP,8)
	ds_swizzle_b32 v53, v239 offset:swizzle(SWAP,8)
	s_waitcnt lgkmcnt(0)
	v_cndmask_b32_e64 v50, v50, v246, s[98:99]
	v_cndmask_b32_e64 v51, v51, v247, s[98:99]
	v_cndmask_b32_e64 v52, v52, v248, s[98:99]
	v_cndmask_b32_e64 v53, v53, v249, s[98:99]
	v_cndmask_b32_e64 v54, v236, v54, s[98:99]
	v_cndmask_b32_e64 v55, v237, v55, s[98:99]
	v_cndmask_b32_e64 v56, v238, v56, s[98:99]
	v_cndmask_b32_e64 v57, v239, v57, s[98:99]
	v_pk_add_f32 v[46:47], v[46:47], v[52:53]
	v_pk_add_f32 v[44:45], v[44:45], v[50:51]
	s_waitcnt vmcnt(0)
	v_pk_add_f32 v[42:43], v[42:43], v[56:57]
	v_pk_add_f32 v[40:41], v[40:41], v[54:55]
	v_lshl_add_u64 v[58:59], v[58:59], 1, s[24:25]
	v_cvt_pk_bf16_f32 v50, v44, v45
	v_cvt_pk_bf16_f32 v51, v46, v47
	v_cvt_pk_bf16_f32 v52, v40, v41
	v_cvt_pk_bf16_f32 v53, v42, v43
	v_lshl_add_u64 v[228:229], v[60:61], 0, v[230:231]
	v_lshl_add_u64 v[232:233], v[60:61], 0, v[244:245]
	ds_swizzle_b32 v236, v40 offset:swizzle(SWAP,8)
	ds_swizzle_b32 v237, v41 offset:swizzle(SWAP,8)
	ds_swizzle_b32 v238, v42 offset:swizzle(SWAP,8)
	ds_swizzle_b32 v239, v43 offset:swizzle(SWAP,8)
	ds_swizzle_b32 v240, v44 offset:swizzle(SWAP,8)
	ds_swizzle_b32 v241, v45 offset:swizzle(SWAP,8)
	ds_swizzle_b32 v242, v46 offset:swizzle(SWAP,8)
	ds_swizzle_b32 v243, v47 offset:swizzle(SWAP,8)
	s_waitcnt lgkmcnt(0)
	v_cndmask_b32_e64 v236, v236, v44, s[98:99]
	v_cndmask_b32_e64 v237, v237, v45, s[98:99]
	v_cndmask_b32_e64 v238, v238, v46, s[98:99]
	v_cndmask_b32_e64 v239, v239, v47, s[98:99]
	v_cndmask_b32_e64 v240, v40, v240, s[98:99]
	v_cndmask_b32_e64 v241, v41, v241, s[98:99]
	v_cndmask_b32_e64 v242, v42, v242, s[98:99]
	v_cndmask_b32_e64 v243, v43, v243, s[98:99]
	global_store_dwordx4 v[228:229], v[236:239], off
	global_store_dwordx4 v[232:233], v[240:243], off
	global_store_dwordx4 v[58:59], v[50:53], off
	v_lshl_add_u64 v[228:229], v[60:61], 0, v[230:231]
	v_lshl_add_u64 v[232:233], v[60:61], 0, v[244:245]
	global_load_dwordx4 v[246:249], v[228:229], off offset:512
	global_load_dwordx4 v[236:239], v[232:233], off offset:512
	s_nop 0
	v_mul_f32_e32 v45, v45, v45
	v_mul_f32_e32 v47, v47, v47
	v_mul_f32_e32 v41, v41, v41
	v_mul_f32_e32 v43, v43, v43
	v_fmac_f32_e32 v45, v44, v44
	v_fmac_f32_e32 v47, v46, v46
	v_fmac_f32_e32 v41, v40, v40
	v_fmac_f32_e32 v43, v42, v42
	v_add_f32_e32 v40, v45, v47
	v_add_f32_e32 v41, v41, v43
	v_add_f32_e32 v44, v40, v41
	s_waitcnt vmcnt(0)
	ds_swizzle_b32 v54, v246 offset:swizzle(SWAP,8)
	ds_swizzle_b32 v55, v247 offset:swizzle(SWAP,8)
	ds_swizzle_b32 v56, v248 offset:swizzle(SWAP,8)
	ds_swizzle_b32 v57, v249 offset:swizzle(SWAP,8)
	ds_swizzle_b32 v50, v236 offset:swizzle(SWAP,8)
	ds_swizzle_b32 v51, v237 offset:swizzle(SWAP,8)
	ds_swizzle_b32 v52, v238 offset:swizzle(SWAP,8)
	ds_swizzle_b32 v53, v239 offset:swizzle(SWAP,8)
	s_waitcnt lgkmcnt(0)
	v_cndmask_b32_e64 v50, v50, v246, s[98:99]
	v_cndmask_b32_e64 v51, v51, v247, s[98:99]
	v_cndmask_b32_e64 v52, v52, v248, s[98:99]
	v_cndmask_b32_e64 v53, v53, v249, s[98:99]
	v_cndmask_b32_e64 v54, v236, v54, s[98:99]
	v_cndmask_b32_e64 v55, v237, v55, s[98:99]
	v_cndmask_b32_e64 v56, v238, v56, s[98:99]
	v_cndmask_b32_e64 v57, v239, v57, s[98:99]
	v_pk_add_f32 v[38:39], v[38:39], v[52:53]
	v_pk_add_f32 v[36:37], v[36:37], v[50:51]
	s_waitcnt vmcnt(0)
	v_pk_add_f32 v[42:43], v[34:35], v[56:57]
	v_pk_add_f32 v[40:41], v[32:33], v[54:55]
	v_mul_f32_e32 v32, v37, v37
	v_mul_f32_e32 v33, v39, v39
	v_mul_f32_e32 v34, v41, v41
	v_mul_f32_e32 v35, v43, v43
	v_fmac_f32_e32 v32, v36, v36
	v_fmac_f32_e32 v33, v38, v38
	v_fmac_f32_e32 v34, v40, v40
	v_fmac_f32_e32 v35, v42, v42
	v_add_f32_e32 v32, v32, v33
	v_add_f32_e32 v33, v34, v35
	v_add_f32_e32 v32, v32, v33
	v_add_f32_e32 v32, v44, v32
	ds_bpermute_b32 v33, v120, v32
	v_lshl_add_u64 v[228:229], v[60:61], 0, v[230:231]
	v_lshl_add_u64 v[232:233], v[60:61], 0, v[244:245]
	ds_swizzle_b32 v236, v40 offset:swizzle(SWAP,8)
	ds_swizzle_b32 v237, v41 offset:swizzle(SWAP,8)
	ds_swizzle_b32 v238, v42 offset:swizzle(SWAP,8)
	ds_swizzle_b32 v239, v43 offset:swizzle(SWAP,8)
	ds_swizzle_b32 v240, v36 offset:swizzle(SWAP,8)
	ds_swizzle_b32 v241, v37 offset:swizzle(SWAP,8)
	ds_swizzle_b32 v242, v38 offset:swizzle(SWAP,8)
	ds_swizzle_b32 v243, v39 offset:swizzle(SWAP,8)
	s_waitcnt lgkmcnt(0)
	v_cndmask_b32_e64 v236, v236, v36, s[98:99]
	v_cndmask_b32_e64 v237, v237, v37, s[98:99]
	v_cndmask_b32_e64 v238, v238, v38, s[98:99]
	v_cndmask_b32_e64 v239, v239, v39, s[98:99]
	v_cndmask_b32_e64 v240, v40, v240, s[98:99]
	v_cndmask_b32_e64 v241, v41, v241, s[98:99]
	v_cndmask_b32_e64 v242, v42, v242, s[98:99]
	v_cndmask_b32_e64 v243, v43, v243, s[98:99]
	global_store_dwordx4 v[228:229], v[236:239], off offset:512
	global_store_dwordx4 v[232:233], v[240:243], off offset:512
	v_cvt_pk_bf16_f32 v34, v36, v37
	v_cvt_pk_bf16_f32 v35, v38, v39
	v_cvt_pk_bf16_f32 v36, v40, v41
	s_waitcnt lgkmcnt(0)
	v_add_f32_e32 v32, v32, v33
	ds_bpermute_b32 v33, v114, v32
	v_cvt_pk_bf16_f32 v37, v42, v43
	global_store_dwordx4 v[58:59], v[34:37], off offset:256
	s_and_saveexec_b64 s[24:25], s[2:3]
	s_cbranch_execz .LBB0_857
	v_readlane_b32 s26, v254, 41
	s_waitcnt lgkmcnt(0)
	v_add_f32_e32 v34, v32, v33
	v_lshlrev_b64 v[32:33], 6, v[48:49]
	v_readlane_b32 s27, v254, 42
	s_lshl_b32 s6, s38, 2
	s_nop 0
	v_lshl_add_u64 v[32:33], s[26:27], 0, v[32:33]
	v_lshl_add_u64 v[32:33], s[22:23], 2, v[32:33]
	v_lshl_add_u64 v[32:33], v[32:33], 0, s[6:7]
	global_store_dword v[32:33], v34, off
; __device__ __forceinline__ unsigned cvt_pk_bf16(float lo, float hi) { const f32x2_t v = {lo, hi}; const bf16x2_t b = __builtin_convertvector(v, bf16x2_t); return __builtin_bit_cast(unsigned, b); }
;     __device__ __forceinline__ void operator()(const f32x4 (&acc)[2][2][4][2], const Unit& u, int wr, int wc, int fr, int fq, const PG8_LAS float*) const {
;     ...
;             for (int m = 0; m < 4; ++m) { const int row = row0 + ai * HALF + m * 16; const size_t off = (size_t)row * ldc + col0; float ss = 0.f;
; #pragma unroll
;                 for (int bj = 0; bj < 2; ++bj) {
;                     const f32x4 b0 = *(const f32x4*)(base + off + bj * HALF), b1 = *(const f32x4*)(base + off + bj * HALF + 4);
;                     const f32x4 v0 = b0 + acc[ai][bj][m][0], v1 = b1 + acc[ai][bj][m][1];
;                     *(f32x4*)(out + off + bj * HALF) = v0; *(f32x4*)(out + off + bj * HALF + 4) = v1;
;                     if (xb) { u32x4 w; w.x = cvt_pk_bf16(v0[0], v0[1]); w.y = cvt_pk_bf16(v0[2], v0[3]); w.z = cvt_pk_bf16(v1[0], v1[1]); w.w = cvt_pk_bf16(v1[2], v1[3]);
;                         *(u32x4*)(xb + off + bj * HALF) = w;
;                         ss += ((v0[0] * v0[0] + v0[1] * v0[1]) + (v0[2] * v0[2] + v0[3] * v0[3])) + ((v1[0] * v1[0] + v1[1] * v1[1]) + (v1[2] * v1[2] + v1[3] * v1[3])); } }
;                 if (xb) { ss += __shfl_xor(ss, 16); ss += __shfl_xor(ss, 32); if (fq == 0) ssq[(size_t)row * 16 + u.pn * 4 + wc] = ss; } }
.LBB0_857:
	s_or_b64 exec, exec, s[24:25]
	v_add_u32_e32 v32, 0xa0, v146
	s_waitcnt lgkmcnt(0)
	v_ashrrev_i32_e32 v33, 31, v32
	v_lshlrev_b64 v[34:35], 10, v[32:33]
	v_lshl_add_u64 v[42:43], v[34:35], 0, v[144:145]
	v_lshl_add_u64 v[44:45], v[42:43], 2, s[68:69]
	v_lshl_add_u64 v[228:229], v[44:45], 0, v[230:231]
	v_lshl_add_u64 v[232:233], v[44:45], 0, v[244:245]
	global_load_dwordx4 v[246:249], v[228:229], off
	global_load_dwordx4 v[236:239], v[232:233], off
	v_readlane_b32 s24, v254, 39
	v_readlane_b32 s25, v254, 40
	s_waitcnt vmcnt(0)
	ds_swizzle_b32 v38, v246 offset:swizzle(SWAP,8)
	ds_swizzle_b32 v39, v247 offset:swizzle(SWAP,8)
	ds_swizzle_b32 v40, v248 offset:swizzle(SWAP,8)
	ds_swizzle_b32 v41, v249 offset:swizzle(SWAP,8)
	ds_swizzle_b32 v34, v236 offset:swizzle(SWAP,8)
	ds_swizzle_b32 v35, v237 offset:swizzle(SWAP,8)
	ds_swizzle_b32 v36, v238 offset:swizzle(SWAP,8)
	ds_swizzle_b32 v37, v239 offset:swizzle(SWAP,8)
	s_waitcnt lgkmcnt(0)
	v_cndmask_b32_e64 v34, v34, v246, s[98:99]
	v_cndmask_b32_e64 v35, v35, v247, s[98:99]
	v_cndmask_b32_e64 v36, v36, v248, s[98:99]
	v_cndmask_b32_e64 v37, v37, v249, s[98:99]
	v_cndmask_b32_e64 v38, v236, v38, s[98:99]
	v_cndmask_b32_e64 v39, v237, v39, s[98:99]
	v_cndmask_b32_e64 v40, v238, v40, s[98:99]
	v_cndmask_b32_e64 v41, v239, v41, s[98:99]
	v_pk_add_f32 v[30:31], v[30:31], v[36:37]
	v_pk_add_f32 v[28:29], v[28:29], v[34:35]
	s_waitcnt vmcnt(0)
	v_pk_add_f32 v[26:27], v[26:27], v[40:41]
	v_pk_add_f32 v[24:25], v[24:25], v[38:39]
	v_lshl_add_u64 v[42:43], v[42:43], 1, s[24:25]
	v_cvt_pk_bf16_f32 v34, v28, v29
	v_cvt_pk_bf16_f32 v35, v30, v31
	v_cvt_pk_bf16_f32 v36, v24, v25
	v_cvt_pk_bf16_f32 v37, v26, v27
	v_lshl_add_u64 v[228:229], v[44:45], 0, v[230:231]
	v_lshl_add_u64 v[232:233], v[44:45], 0, v[244:245]
	ds_swizzle_b32 v236, v24 offset:swizzle(SWAP,8)
	ds_swizzle_b32 v237, v25 offset:swizzle(SWAP,8)
	ds_swizzle_b32 v238, v26 offset:swizzle(SWAP,8)
	ds_swizzle_b32 v239, v27 offset:swizzle(SWAP,8)
	ds_swizzle_b32 v240, v28 offset:swizzle(SWAP,8)
	ds_swizzle_b32 v241, v29 offset:swizzle(SWAP,8)
	ds_swizzle_b32 v242, v30 offset:swizzle(SWAP,8)
	ds_swizzle_b32 v243, v31 offset:swizzle(SWAP,8)
	s_waitcnt lgkmcnt(0)
	v_cndmask_b32_e64 v236, v236, v28, s[98:99]
	v_cndmask_b32_e64 v237, v237, v29, s[98:99]
	v_cndmask_b32_e64 v238, v238, v30, s[98:99]
	v_cndmask_b32_e64 v239, v239, v31, s[98:99]
	v_cndmask_b32_e64 v240, v24, v240, s[98:99]
	v_cndmask_b32_e64 v241, v25, v241, s[98:99]
	v_cndmask_b32_e64 v242, v26, v242, s[98:99]
	v_cndmask_b32_e64 v243, v27, v243, s[98:99]
	global_store_dwordx4 v[228:229], v[236:239], off
	global_store_dwordx4 v[232:233], v[240:243], off
	global_store_dwordx4 v[42:43], v[34:37], off
	v_lshl_add_u64 v[228:229], v[44:45], 0, v[230:231]
	v_lshl_add_u64 v[232:233], v[44:45], 0, v[244:245]
	global_load_dwordx4 v[246:249], v[228:229], off offset:512
	global_load_dwordx4 v[236:239], v[232:233], off offset:512
	s_nop 0
	v_mul_f32_e32 v29, v29, v29
	v_mul_f32_e32 v31, v31, v31
	v_mul_f32_e32 v25, v25, v25
	v_mul_f32_e32 v27, v27, v27
	v_fmac_f32_e32 v29, v28, v28
	v_fmac_f32_e32 v31, v30, v30
	v_fmac_f32_e32 v25, v24, v24
	v_fmac_f32_e32 v27, v26, v26
	v_add_f32_e32 v24, v29, v31
	v_add_f32_e32 v25, v25, v27
	v_add_f32_e32 v28, v24, v25
	s_waitcnt vmcnt(0)
	ds_swizzle_b32 v38, v246 offset:swizzle(SWAP,8)
	ds_swizzle_b32 v39, v247 offset:swizzle(SWAP,8)
	ds_swizzle_b32 v40, v248 offset:swizzle(SWAP,8)
	ds_swizzle_b32 v41, v249 offset:swizzle(SWAP,8)
	ds_swizzle_b32 v34, v236 offset:swizzle(SWAP,8)
	ds_swizzle_b32 v35, v237 offset:swizzle(SWAP,8)
	ds_swizzle_b32 v36, v238 offset:swizzle(SWAP,8)
	ds_swizzle_b32 v37, v239 offset:swizzle(SWAP,8)
	s_waitcnt lgkmcnt(0)
	v_cndmask_b32_e64 v34, v34, v246, s[98:99]
	v_cndmask_b32_e64 v35, v35, v247, s[98:99]
	v_cndmask_b32_e64 v36, v36, v248, s[98:99]
	v_cndmask_b32_e64 v37, v37, v249, s[98:99]
	v_cndmask_b32_e64 v38, v236, v38, s[98:99]
	v_cndmask_b32_e64 v39, v237, v39, s[98:99]
	v_cndmask_b32_e64 v40, v238, v40, s[98:99]
	v_cndmask_b32_e64 v41, v239, v41, s[98:99]
	v_pk_add_f32 v[22:23], v[22:23], v[36:37]
	v_pk_add_f32 v[20:21], v[20:21], v[34:35]
	s_waitcnt vmcnt(0)
	v_pk_add_f32 v[26:27], v[18:19], v[40:41]
	v_pk_add_f32 v[24:25], v[16:17], v[38:39]
	v_mul_f32_e32 v16, v21, v21
	v_mul_f32_e32 v17, v23, v23
	v_mul_f32_e32 v18, v25, v25
	v_mul_f32_e32 v19, v27, v27
	v_fmac_f32_e32 v16, v20, v20
	v_fmac_f32_e32 v17, v22, v22
	v_fmac_f32_e32 v18, v24, v24
	v_fmac_f32_e32 v19, v26, v26
	v_add_f32_e32 v16, v16, v17
	v_add_f32_e32 v17, v18, v19
	v_add_f32_e32 v16, v16, v17
	v_add_f32_e32 v16, v28, v16
	ds_bpermute_b32 v17, v120, v16
	v_lshl_add_u64 v[228:229], v[44:45], 0, v[230:231]
	v_lshl_add_u64 v[232:233], v[44:45], 0, v[244:245]
	ds_swizzle_b32 v236, v24 offset:swizzle(SWAP,8)
	ds_swizzle_b32 v237, v25 offset:swizzle(SWAP,8)
	ds_swizzle_b32 v238, v26 offset:swizzle(SWAP,8)
	ds_swizzle_b32 v239, v27 offset:swizzle(SWAP,8)
	ds_swizzle_b32 v240, v20 offset:swizzle(SWAP,8)
	ds_swizzle_b32 v241, v21 offset:swizzle(SWAP,8)
	ds_swizzle_b32 v242, v22 offset:swizzle(SWAP,8)
	ds_swizzle_b32 v243, v23 offset:swizzle(SWAP,8)
	s_waitcnt lgkmcnt(0)
	v_cndmask_b32_e64 v236, v236, v20, s[98:99]
	v_cndmask_b32_e64 v237, v237, v21, s[98:99]
	v_cndmask_b32_e64 v238, v238, v22, s[98:99]
	v_cndmask_b32_e64 v239, v239, v23, s[98:99]
	v_cndmask_b32_e64 v240, v24, v240, s[98:99]
	v_cndmask_b32_e64 v241, v25, v241, s[98:99]
	v_cndmask_b32_e64 v242, v26, v242, s[98:99]
	v_cndmask_b32_e64 v243, v27, v243, s[98:99]
	global_store_dwordx4 v[228:229], v[236:239], off offset:512
	global_store_dwordx4 v[232:233], v[240:243], off offset:512
	v_cvt_pk_bf16_f32 v18, v20, v21
	v_cvt_pk_bf16_f32 v19, v22, v23
	v_cvt_pk_bf16_f32 v20, v24, v25
	s_waitcnt lgkmcnt(0)
	v_add_f32_e32 v16, v16, v17
	ds_bpermute_b32 v17, v114, v16
	v_cvt_pk_bf16_f32 v21, v26, v27
	global_store_dwordx4 v[42:43], v[18:21], off offset:256
	s_and_saveexec_b64 s[24:25], s[2:3]
	s_cbranch_execz .LBB0_859
	v_readlane_b32 s26, v254, 41
	s_waitcnt lgkmcnt(0)
	v_add_f32_e32 v18, v16, v17
	v_lshlrev_b64 v[16:17], 6, v[32:33]
	v_readlane_b32 s27, v254, 42
	s_lshl_b32 s6, s38, 2
	s_nop 0
	v_lshl_add_u64 v[16:17], s[26:27], 0, v[16:17]
	v_lshl_add_u64 v[16:17], s[22:23], 2, v[16:17]
	v_lshl_add_u64 v[16:17], v[16:17], 0, s[6:7]
	global_store_dword v[16:17], v18, off
; __device__ __forceinline__ unsigned cvt_pk_bf16(float lo, float hi) { const f32x2_t v = {lo, hi}; const bf16x2_t b = __builtin_convertvector(v, bf16x2_t); return __builtin_bit_cast(unsigned, b); }
;     __device__ __forceinline__ void operator()(const f32x4 (&acc)[2][2][4][2], const Unit& u, int wr, int wc, int fr, int fq, const PG8_LAS float*) const {
;     ...
;             for (int m = 0; m < 4; ++m) { const int row = row0 + ai * HALF + m * 16; const size_t off = (size_t)row * ldc + col0; float ss = 0.f;
; #pragma unroll
;                 for (int bj = 0; bj < 2; ++bj) {
;                     const f32x4 b0 = *(const f32x4*)(base + off + bj * HALF), b1 = *(const f32x4*)(base + off + bj * HALF + 4);
;                     const f32x4 v0 = b0 + acc[ai][bj][m][0], v1 = b1 + acc[ai][bj][m][1];
;                     *(f32x4*)(out + off + bj * HALF) = v0; *(f32x4*)(out + off + bj * HALF + 4) = v1;
;                     if (xb) { u32x4 w; w.x = cvt_pk_bf16(v0[0], v0[1]); w.y = cvt_pk_bf16(v0[2], v0[3]); w.z = cvt_pk_bf16(v1[0], v1[1]); w.w = cvt_pk_bf16(v1[2], v1[3]);
;                         *(u32x4*)(xb + off + bj * HALF) = w;
;                         ss += ((v0[0] * v0[0] + v0[1] * v0[1]) + (v0[2] * v0[2] + v0[3] * v0[3])) + ((v1[0] * v1[0] + v1[1] * v1[1]) + (v1[2] * v1[2] + v1[3] * v1[3])); } }
;                 if (xb) { ss += __shfl_xor(ss, 16); ss += __shfl_xor(ss, 32); if (fq == 0) ssq[(size_t)row * 16 + u.pn * 4 + wc] = ss; } }
.LBB0_859:
	s_or_b64 exec, exec, s[24:25]
	v_add_u32_e32 v16, 0xb0, v146
	s_waitcnt lgkmcnt(0)
	v_ashrrev_i32_e32 v17, 31, v16
	v_lshlrev_b64 v[18:19], 10, v[16:17]
	v_lshl_add_u64 v[26:27], v[18:19], 0, v[144:145]
	v_lshl_add_u64 v[28:29], v[26:27], 2, s[68:69]
	v_lshl_add_u64 v[228:229], v[28:29], 0, v[230:231]
	v_lshl_add_u64 v[232:233], v[28:29], 0, v[244:245]
	global_load_dwordx4 v[246:249], v[228:229], off
	global_load_dwordx4 v[236:239], v[232:233], off
	v_readlane_b32 s24, v254, 39
	v_readlane_b32 s25, v254, 40
	s_waitcnt vmcnt(0)
	ds_swizzle_b32 v22, v246 offset:swizzle(SWAP,8)
	ds_swizzle_b32 v23, v247 offset:swizzle(SWAP,8)
	ds_swizzle_b32 v24, v248 offset:swizzle(SWAP,8)
	ds_swizzle_b32 v25, v249 offset:swizzle(SWAP,8)
	ds_swizzle_b32 v18, v236 offset:swizzle(SWAP,8)
	ds_swizzle_b32 v19, v237 offset:swizzle(SWAP,8)
	ds_swizzle_b32 v20, v238 offset:swizzle(SWAP,8)
	ds_swizzle_b32 v21, v239 offset:swizzle(SWAP,8)
	s_waitcnt lgkmcnt(0)
	v_cndmask_b32_e64 v18, v18, v246, s[98:99]
	v_cndmask_b32_e64 v19, v19, v247, s[98:99]
	v_cndmask_b32_e64 v20, v20, v248, s[98:99]
	v_cndmask_b32_e64 v21, v21, v249, s[98:99]
	v_cndmask_b32_e64 v22, v236, v22, s[98:99]
	v_cndmask_b32_e64 v23, v237, v23, s[98:99]
	v_cndmask_b32_e64 v24, v238, v24, s[98:99]
	v_cndmask_b32_e64 v25, v239, v25, s[98:99]
	v_pk_add_f32 v[14:15], v[14:15], v[20:21]
	v_pk_add_f32 v[12:13], v[12:13], v[18:19]
	s_waitcnt vmcnt(0)
	v_pk_add_f32 v[10:11], v[10:11], v[24:25]
	v_pk_add_f32 v[8:9], v[8:9], v[22:23]
	v_lshl_add_u64 v[26:27], v[26:27], 1, s[24:25]
	v_cvt_pk_bf16_f32 v18, v12, v13
	v_cvt_pk_bf16_f32 v19, v14, v15
	v_cvt_pk_bf16_f32 v20, v8, v9
	v_cvt_pk_bf16_f32 v21, v10, v11
	v_lshl_add_u64 v[228:229], v[28:29], 0, v[230:231]
	v_lshl_add_u64 v[232:233], v[28:29], 0, v[244:245]
	ds_swizzle_b32 v236, v8 offset:swizzle(SWAP,8)
	ds_swizzle_b32 v237, v9 offset:swizzle(SWAP,8)
	ds_swizzle_b32 v238, v10 offset:swizzle(SWAP,8)
	ds_swizzle_b32 v239, v11 offset:swizzle(SWAP,8)
	ds_swizzle_b32 v240, v12 offset:swizzle(SWAP,8)
	ds_swizzle_b32 v241, v13 offset:swizzle(SWAP,8)
	ds_swizzle_b32 v242, v14 offset:swizzle(SWAP,8)
	ds_swizzle_b32 v243, v15 offset:swizzle(SWAP,8)
	s_waitcnt lgkmcnt(0)
	v_cndmask_b32_e64 v236, v236, v12, s[98:99]
	v_cndmask_b32_e64 v237, v237, v13, s[98:99]
	v_cndmask_b32_e64 v238, v238, v14, s[98:99]
	v_cndmask_b32_e64 v239, v239, v15, s[98:99]
	v_cndmask_b32_e64 v240, v8, v240, s[98:99]
	v_cndmask_b32_e64 v241, v9, v241, s[98:99]
	v_cndmask_b32_e64 v242, v10, v242, s[98:99]
	v_cndmask_b32_e64 v243, v11, v243, s[98:99]
	global_store_dwordx4 v[228:229], v[236:239], off
	global_store_dwordx4 v[232:233], v[240:243], off
	global_store_dwordx4 v[26:27], v[18:21], off
	v_lshl_add_u64 v[228:229], v[28:29], 0, v[230:231]
	v_lshl_add_u64 v[232:233], v[28:29], 0, v[244:245]
	global_load_dwordx4 v[246:249], v[228:229], off offset:512
	global_load_dwordx4 v[236:239], v[232:233], off offset:512
	s_nop 0
	v_mul_f32_e32 v13, v13, v13
	v_mul_f32_e32 v15, v15, v15
	v_mul_f32_e32 v9, v9, v9
	v_mul_f32_e32 v11, v11, v11
	v_fmac_f32_e32 v13, v12, v12
	v_fmac_f32_e32 v15, v14, v14
	v_fmac_f32_e32 v9, v8, v8
	v_fmac_f32_e32 v11, v10, v10
	v_add_f32_e32 v8, v13, v15
	v_add_f32_e32 v9, v9, v11
	v_add_f32_e32 v12, v8, v9
	s_waitcnt vmcnt(0)
	ds_swizzle_b32 v22, v246 offset:swizzle(SWAP,8)
	ds_swizzle_b32 v23, v247 offset:swizzle(SWAP,8)
	ds_swizzle_b32 v24, v248 offset:swizzle(SWAP,8)
	ds_swizzle_b32 v25, v249 offset:swizzle(SWAP,8)
	ds_swizzle_b32 v18, v236 offset:swizzle(SWAP,8)
	ds_swizzle_b32 v19, v237 offset:swizzle(SWAP,8)
	ds_swizzle_b32 v20, v238 offset:swizzle(SWAP,8)
	ds_swizzle_b32 v21, v239 offset:swizzle(SWAP,8)
	s_waitcnt lgkmcnt(0)
	v_cndmask_b32_e64 v18, v18, v246, s[98:99]
	v_cndmask_b32_e64 v19, v19, v247, s[98:99]
	v_cndmask_b32_e64 v20, v20, v248, s[98:99]
	v_cndmask_b32_e64 v21, v21, v249, s[98:99]
	v_cndmask_b32_e64 v22, v236, v22, s[98:99]
	v_cndmask_b32_e64 v23, v237, v23, s[98:99]
	v_cndmask_b32_e64 v24, v238, v24, s[98:99]
	v_cndmask_b32_e64 v25, v239, v25, s[98:99]
	v_pk_add_f32 v[6:7], v[6:7], v[20:21]
	v_pk_add_f32 v[4:5], v[4:5], v[18:19]
	s_waitcnt vmcnt(0)
	v_pk_add_f32 v[10:11], v[2:3], v[24:25]
	v_pk_add_f32 v[8:9], v[0:1], v[22:23]
	v_mul_f32_e32 v0, v5, v5
	v_mul_f32_e32 v1, v7, v7
	v_mul_f32_e32 v2, v9, v9
	v_mul_f32_e32 v3, v11, v11
	v_fmac_f32_e32 v0, v4, v4
	v_fmac_f32_e32 v1, v6, v6
	v_fmac_f32_e32 v2, v8, v8
	v_fmac_f32_e32 v3, v10, v10
	v_add_f32_e32 v0, v0, v1
	v_add_f32_e32 v1, v2, v3
	v_add_f32_e32 v0, v0, v1
	v_add_f32_e32 v0, v12, v0
	ds_bpermute_b32 v1, v120, v0
	v_lshl_add_u64 v[228:229], v[28:29], 0, v[230:231]
	v_lshl_add_u64 v[232:233], v[28:29], 0, v[244:245]
	ds_swizzle_b32 v236, v8 offset:swizzle(SWAP,8)
	ds_swizzle_b32 v237, v9 offset:swizzle(SWAP,8)
	ds_swizzle_b32 v238, v10 offset:swizzle(SWAP,8)
	ds_swizzle_b32 v239, v11 offset:swizzle(SWAP,8)
	ds_swizzle_b32 v240, v4 offset:swizzle(SWAP,8)
	ds_swizzle_b32 v241, v5 offset:swizzle(SWAP,8)
	ds_swizzle_b32 v242, v6 offset:swizzle(SWAP,8)
	ds_swizzle_b32 v243, v7 offset:swizzle(SWAP,8)
	s_waitcnt lgkmcnt(0)
	v_cndmask_b32_e64 v236, v236, v4, s[98:99]
	v_cndmask_b32_e64 v237, v237, v5, s[98:99]
	v_cndmask_b32_e64 v238, v238, v6, s[98:99]
	v_cndmask_b32_e64 v239, v239, v7, s[98:99]
	v_cndmask_b32_e64 v240, v8, v240, s[98:99]
	v_cndmask_b32_e64 v241, v9, v241, s[98:99]
	v_cndmask_b32_e64 v242, v10, v242, s[98:99]
	v_cndmask_b32_e64 v243, v11, v243, s[98:99]
	global_store_dwordx4 v[228:229], v[236:239], off offset:512
	global_store_dwordx4 v[232:233], v[240:243], off offset:512
	v_cvt_pk_bf16_f32 v2, v4, v5
	v_cvt_pk_bf16_f32 v3, v6, v7
	v_cvt_pk_bf16_f32 v4, v8, v9
	s_waitcnt lgkmcnt(0)
	v_add_f32_e32 v0, v0, v1
	ds_bpermute_b32 v1, v114, v0
	v_cvt_pk_bf16_f32 v5, v10, v11
	global_store_dwordx4 v[26:27], v[2:5], off offset:256
	s_and_saveexec_b64 s[24:25], s[2:3]
	s_cbranch_execz .LBB0_861
	v_readlane_b32 s26, v254, 41
	s_waitcnt lgkmcnt(0)
	v_add_f32_e32 v2, v0, v1
	v_lshlrev_b64 v[0:1], 6, v[16:17]
	v_readlane_b32 s27, v254, 42
	s_lshl_b32 s6, s38, 2
	s_nop 0
	v_lshl_add_u64 v[0:1], s[26:27], 0, v[0:1]
	v_lshl_add_u64 v[0:1], s[22:23], 2, v[0:1]
	v_lshl_add_u64 v[0:1], v[0:1], 0, s[6:7]
	global_store_dword v[0:1], v2, off

;     __device__ __forceinline__ void operator()(const f32x4 (&acc)[2][2][4][2], const Unit& u, int wr, int wc, int fr, int fq, const PG8_LAS float*) const {
;     ...
;             for (int m = 0; m < 4; ++m) { const int row = row0 + ai * HALF + m * 16; const size_t off = (size_t)row * ldc + col0; float ss = 0.f;
; #pragma unroll
;                 for (int bj = 0; bj < 2; ++bj) {
;                     const f32x4 b0 = *(const f32x4*)(base + off + bj * HALF), b1 = *(const f32x4*)(base + off + bj * HALF + 4);
;                     const f32x4 v0 = b0 + acc[ai][bj][m][0], v1 = b1 + acc[ai][bj][m][1];
;                     *(f32x4*)(out + off + bj * HALF) = v0; *(f32x4*)(out + off + bj * HALF + 4) = v1;
.LBB0_1644:
	v_lshl_add_u32 v146, s26, 8, v150
	v_lshl_or_b32 v144, s27, 8, v152
	v_ashrrev_i32_e32 v147, 31, v146
	v_ashrrev_i32_e32 v145, 31, v144
	v_lshlrev_b64 v[148:149], 12, v[146:147]
	v_lshl_add_u64 v[156:157], s[68:69], 0, v[148:149]
	v_lshlrev_b64 v[148:149], 2, v[144:145]
	v_lshl_add_u64 v[144:145], v[156:157], 0, v[148:149]
	v_lshl_add_u64 v[228:229], v[144:145], 0, v[230:231]
	v_lshl_add_u64 v[232:233], v[144:145], 0, v[244:245]
	global_load_dwordx4 v[246:249], v[228:229], off
	global_load_dwordx4 v[236:239], v[232:233], off
	s_mov_b64 s[26:27], -1
	s_waitcnt vmcnt(0)
	ds_swizzle_b32 v156, v246 offset:swizzle(SWAP,8)
	ds_swizzle_b32 v157, v247 offset:swizzle(SWAP,8)
	ds_swizzle_b32 v158, v248 offset:swizzle(SWAP,8)
	ds_swizzle_b32 v159, v249 offset:swizzle(SWAP,8)
	ds_swizzle_b32 v160, v236 offset:swizzle(SWAP,8)
	ds_swizzle_b32 v161, v237 offset:swizzle(SWAP,8)
	ds_swizzle_b32 v162, v238 offset:swizzle(SWAP,8)
	ds_swizzle_b32 v163, v239 offset:swizzle(SWAP,8)
	s_waitcnt lgkmcnt(0)
	v_cndmask_b32_e64 v160, v160, v246, s[98:99]
	v_cndmask_b32_e64 v161, v161, v247, s[98:99]
	v_cndmask_b32_e64 v162, v162, v248, s[98:99]
	v_cndmask_b32_e64 v163, v163, v249, s[98:99]
	v_cndmask_b32_e64 v156, v236, v156, s[98:99]
	v_cndmask_b32_e64 v157, v237, v157, s[98:99]
	v_cndmask_b32_e64 v158, v238, v158, s[98:99]
	v_cndmask_b32_e64 v159, v239, v159, s[98:99]
	v_pk_add_f32 v[122:123], v[122:123], v[158:159]
	v_pk_add_f32 v[126:127], v[126:127], v[162:163]
	v_pk_add_f32 v[124:125], v[124:125], v[160:161]
	v_pk_add_f32 v[120:121], v[120:121], v[156:157]
	v_lshl_add_u64 v[228:229], v[144:145], 0, v[230:231]
	v_lshl_add_u64 v[232:233], v[144:145], 0, v[244:245]
	ds_swizzle_b32 v236, v120 offset:swizzle(SWAP,8)
	ds_swizzle_b32 v237, v121 offset:swizzle(SWAP,8)
	ds_swizzle_b32 v238, v122 offset:swizzle(SWAP,8)
	ds_swizzle_b32 v239, v123 offset:swizzle(SWAP,8)
	ds_swizzle_b32 v240, v124 offset:swizzle(SWAP,8)
	ds_swizzle_b32 v241, v125 offset:swizzle(SWAP,8)
	ds_swizzle_b32 v242, v126 offset:swizzle(SWAP,8)
	ds_swizzle_b32 v243, v127 offset:swizzle(SWAP,8)
	s_waitcnt lgkmcnt(0)
	v_cndmask_b32_e64 v236, v236, v124, s[98:99]
	v_cndmask_b32_e64 v237, v237, v125, s[98:99]
	v_cndmask_b32_e64 v238, v238, v126, s[98:99]
	v_cndmask_b32_e64 v239, v239, v127, s[98:99]
	v_cndmask_b32_e64 v240, v120, v240, s[98:99]
	v_cndmask_b32_e64 v241, v121, v241, s[98:99]
	v_cndmask_b32_e64 v242, v122, v242, s[98:99]
	v_cndmask_b32_e64 v243, v123, v243, s[98:99]
	global_store_dwordx4 v[228:229], v[236:239], off
	global_store_dwordx4 v[232:233], v[240:243], off
	v_lshl_add_u64 v[228:229], v[144:145], 0, v[230:231]
	v_lshl_add_u64 v[232:233], v[144:145], 0, v[244:245]
	global_load_dwordx4 v[246:249], v[228:229], off offset:512
	global_load_dwordx4 v[236:239], v[232:233], off offset:512
	s_nop 0
	s_waitcnt vmcnt(0)
	ds_swizzle_b32 v120, v246 offset:swizzle(SWAP,8)
	ds_swizzle_b32 v121, v247 offset:swizzle(SWAP,8)
	ds_swizzle_b32 v122, v248 offset:swizzle(SWAP,8)
	ds_swizzle_b32 v123, v249 offset:swizzle(SWAP,8)
	ds_swizzle_b32 v124, v236 offset:swizzle(SWAP,8)
	ds_swizzle_b32 v125, v237 offset:swizzle(SWAP,8)
	ds_swizzle_b32 v126, v238 offset:swizzle(SWAP,8)
	ds_swizzle_b32 v127, v239 offset:swizzle(SWAP,8)
	s_waitcnt lgkmcnt(0)
	v_cndmask_b32_e64 v124, v124, v246, s[98:99]
	v_cndmask_b32_e64 v125, v125, v247, s[98:99]
	v_cndmask_b32_e64 v126, v126, v248, s[98:99]
	v_cndmask_b32_e64 v127, v127, v249, s[98:99]
	v_cndmask_b32_e64 v120, v236, v120, s[98:99]
	v_cndmask_b32_e64 v121, v237, v121, s[98:99]
	v_cndmask_b32_e64 v122, v238, v122, s[98:99]
	v_cndmask_b32_e64 v123, v239, v123, s[98:99]
	v_pk_add_f32 v[112:113], v[112:113], v[120:121]
	s_waitcnt vmcnt(0)
	v_pk_add_f32 v[118:119], v[118:119], v[126:127]
	v_pk_add_f32 v[116:117], v[116:117], v[124:125]
	v_pk_add_f32 v[114:115], v[114:115], v[122:123]
	v_lshl_add_u64 v[228:229], v[144:145], 0, v[230:231]
	v_lshl_add_u64 v[232:233], v[144:145], 0, v[244:245]
	ds_swizzle_b32 v236, v112 offset:swizzle(SWAP,8)
	ds_swizzle_b32 v237, v113 offset:swizzle(SWAP,8)
	ds_swizzle_b32 v238, v114 offset:swizzle(SWAP,8)
	ds_swizzle_b32 v239, v115 offset:swizzle(SWAP,8)
	ds_swizzle_b32 v240, v116 offset:swizzle(SWAP,8)
	ds_swizzle_b32 v241, v117 offset:swizzle(SWAP,8)
	ds_swizzle_b32 v242, v118 offset:swizzle(SWAP,8)
	ds_swizzle_b32 v243, v119 offset:swizzle(SWAP,8)
	s_waitcnt lgkmcnt(0)
	v_cndmask_b32_e64 v236, v236, v116, s[98:99]
	v_cndmask_b32_e64 v237, v237, v117, s[98:99]
	v_cndmask_b32_e64 v238, v238, v118, s[98:99]
	v_cndmask_b32_e64 v239, v239, v119, s[98:99]
	v_cndmask_b32_e64 v240, v112, v240, s[98:99]
	v_cndmask_b32_e64 v241, v113, v241, s[98:99]
	v_cndmask_b32_e64 v242, v114, v242, s[98:99]
	v_cndmask_b32_e64 v243, v115, v243, s[98:99]
	global_store_dwordx4 v[228:229], v[236:239], off offset:512
	global_store_dwordx4 v[232:233], v[240:243], off offset:512
	s_nop 1
	v_or_b32_e32 v112, 16, v146
	v_ashrrev_i32_e32 v113, 31, v112
	v_lshlrev_b64 v[112:113], 12, v[112:113]
	v_lshl_add_u64 v[112:113], s[68:69], 0, v[112:113]
	v_lshl_add_u64 v[120:121], v[112:113], 0, v[148:149]
	v_lshl_add_u64 v[228:229], v[120:121], 0, v[230:231]
	v_lshl_add_u64 v[232:233], v[120:121], 0, v[244:245]
	global_load_dwordx4 v[246:249], v[228:229], off
	global_load_dwordx4 v[236:239], v[232:233], off
	s_waitcnt vmcnt(0)
	ds_swizzle_b32 v112, v246 offset:swizzle(SWAP,8)
	ds_swizzle_b32 v113, v247 offset:swizzle(SWAP,8)
	ds_swizzle_b32 v114, v248 offset:swizzle(SWAP,8)
	ds_swizzle_b32 v115, v249 offset:swizzle(SWAP,8)
	ds_swizzle_b32 v116, v236 offset:swizzle(SWAP,8)
	ds_swizzle_b32 v117, v237 offset:swizzle(SWAP,8)
	ds_swizzle_b32 v118, v238 offset:swizzle(SWAP,8)
	ds_swizzle_b32 v119, v239 offset:swizzle(SWAP,8)
	s_waitcnt lgkmcnt(0)
;     __device__ __forceinline__ void operator()(const f32x4 (&acc)[2][2][4][2], const Unit& u, int wr, int wc, int fr, int fq, const PG8_LAS float*) const {
;     ...
;             for (int m = 0; m < 4; ++m) { const int row = row0 + ai * HALF + m * 16; const size_t off = (size_t)row * ldc + col0; float ss = 0.f;
; #pragma unroll
;                 for (int bj = 0; bj < 2; ++bj) {
;                     const f32x4 b0 = *(const f32x4*)(base + off + bj * HALF), b1 = *(const f32x4*)(base + off + bj * HALF + 4);
;                     const f32x4 v0 = b0 + acc[ai][bj][m][0], v1 = b1 + acc[ai][bj][m][1];
;                     *(f32x4*)(out + off + bj * HALF) = v0; *(f32x4*)(out + off + bj * HALF + 4) = v1;
	v_cndmask_b32_e64 v116, v116, v246, s[98:99]
	v_cndmask_b32_e64 v117, v117, v247, s[98:99]
	v_cndmask_b32_e64 v118, v118, v248, s[98:99]
	v_cndmask_b32_e64 v119, v119, v249, s[98:99]
	v_cndmask_b32_e64 v112, v236, v112, s[98:99]
	v_cndmask_b32_e64 v113, v237, v113, s[98:99]
	v_cndmask_b32_e64 v114, v238, v114, s[98:99]
	v_cndmask_b32_e64 v115, v239, v115, s[98:99]
	v_pk_add_f32 v[106:107], v[106:107], v[114:115]
	s_waitcnt vmcnt(0)
	v_pk_add_f32 v[110:111], v[110:111], v[118:119]
	v_pk_add_f32 v[108:109], v[108:109], v[116:117]
	v_pk_add_f32 v[104:105], v[104:105], v[112:113]
	v_lshl_add_u64 v[228:229], v[120:121], 0, v[230:231]
	v_lshl_add_u64 v[232:233], v[120:121], 0, v[244:245]
	ds_swizzle_b32 v236, v104 offset:swizzle(SWAP,8)
	ds_swizzle_b32 v237, v105 offset:swizzle(SWAP,8)
	ds_swizzle_b32 v238, v106 offset:swizzle(SWAP,8)
	ds_swizzle_b32 v239, v107 offset:swizzle(SWAP,8)
	ds_swizzle_b32 v240, v108 offset:swizzle(SWAP,8)
	ds_swizzle_b32 v241, v109 offset:swizzle(SWAP,8)
	ds_swizzle_b32 v242, v110 offset:swizzle(SWAP,8)
	ds_swizzle_b32 v243, v111 offset:swizzle(SWAP,8)
	s_waitcnt lgkmcnt(0)
	v_cndmask_b32_e64 v236, v236, v108, s[98:99]
	v_cndmask_b32_e64 v237, v237, v109, s[98:99]
	v_cndmask_b32_e64 v238, v238, v110, s[98:99]
	v_cndmask_b32_e64 v239, v239, v111, s[98:99]
	v_cndmask_b32_e64 v240, v104, v240, s[98:99]
	v_cndmask_b32_e64 v241, v105, v241, s[98:99]
	v_cndmask_b32_e64 v242, v106, v242, s[98:99]
	v_cndmask_b32_e64 v243, v107, v243, s[98:99]
	global_store_dwordx4 v[228:229], v[236:239], off
	global_store_dwordx4 v[232:233], v[240:243], off
	v_lshl_add_u64 v[228:229], v[120:121], 0, v[230:231]
	v_lshl_add_u64 v[232:233], v[120:121], 0, v[244:245]
	global_load_dwordx4 v[246:249], v[228:229], off offset:512
	global_load_dwordx4 v[236:239], v[232:233], off offset:512
	s_nop 0
	s_waitcnt vmcnt(0)
	ds_swizzle_b32 v104, v246 offset:swizzle(SWAP,8)
	ds_swizzle_b32 v105, v247 offset:swizzle(SWAP,8)
	ds_swizzle_b32 v106, v248 offset:swizzle(SWAP,8)
	ds_swizzle_b32 v107, v249 offset:swizzle(SWAP,8)
	ds_swizzle_b32 v108, v236 offset:swizzle(SWAP,8)
	ds_swizzle_b32 v109, v237 offset:swizzle(SWAP,8)
	ds_swizzle_b32 v110, v238 offset:swizzle(SWAP,8)
	ds_swizzle_b32 v111, v239 offset:swizzle(SWAP,8)
	s_waitcnt lgkmcnt(0)
	v_cndmask_b32_e64 v108, v108, v246, s[98:99]
	v_cndmask_b32_e64 v109, v109, v247, s[98:99]
	v_cndmask_b32_e64 v110, v110, v248, s[98:99]
	v_cndmask_b32_e64 v111, v111, v249, s[98:99]
	v_cndmask_b32_e64 v104, v236, v104, s[98:99]
	v_cndmask_b32_e64 v105, v237, v105, s[98:99]
	v_cndmask_b32_e64 v106, v238, v106, s[98:99]
	v_cndmask_b32_e64 v107, v239, v107, s[98:99]
	v_pk_add_f32 v[96:97], v[96:97], v[104:105]
	s_waitcnt vmcnt(0)
	v_pk_add_f32 v[102:103], v[102:103], v[110:111]
	v_pk_add_f32 v[100:101], v[100:101], v[108:109]
	v_pk_add_f32 v[98:99], v[98:99], v[106:107]
	v_lshl_add_u64 v[228:229], v[120:121], 0, v[230:231]
	v_lshl_add_u64 v[232:233], v[120:121], 0, v[244:245]
	ds_swizzle_b32 v236, v96 offset:swizzle(SWAP,8)
	ds_swizzle_b32 v237, v97 offset:swizzle(SWAP,8)
	ds_swizzle_b32 v238, v98 offset:swizzle(SWAP,8)
	ds_swizzle_b32 v239, v99 offset:swizzle(SWAP,8)
	ds_swizzle_b32 v240, v100 offset:swizzle(SWAP,8)
	ds_swizzle_b32 v241, v101 offset:swizzle(SWAP,8)
	ds_swizzle_b32 v242, v102 offset:swizzle(SWAP,8)
	ds_swizzle_b32 v243, v103 offset:swizzle(SWAP,8)
	s_waitcnt lgkmcnt(0)
	v_cndmask_b32_e64 v236, v236, v100, s[98:99]
	v_cndmask_b32_e64 v237, v237, v101, s[98:99]
	v_cndmask_b32_e64 v238, v238, v102, s[98:99]
	v_cndmask_b32_e64 v239, v239, v103, s[98:99]
	v_cndmask_b32_e64 v240, v96, v240, s[98:99]
	v_cndmask_b32_e64 v241, v97, v241, s[98:99]
	v_cndmask_b32_e64 v242, v98, v242, s[98:99]
	v_cndmask_b32_e64 v243, v99, v243, s[98:99]
	global_store_dwordx4 v[228:229], v[236:239], off offset:512
	global_store_dwordx4 v[232:233], v[240:243], off offset:512
	s_nop 1
	v_or_b32_e32 v96, 32, v146
	v_ashrrev_i32_e32 v97, 31, v96
	v_lshlrev_b64 v[96:97], 12, v[96:97]
	v_lshl_add_u64 v[96:97], s[68:69], 0, v[96:97]
	v_lshl_add_u64 v[104:105], v[96:97], 0, v[148:149]
	v_lshl_add_u64 v[228:229], v[104:105], 0, v[230:231]
	v_lshl_add_u64 v[232:233], v[104:105], 0, v[244:245]
	global_load_dwordx4 v[246:249], v[228:229], off
	global_load_dwordx4 v[236:239], v[232:233], off
	s_waitcnt vmcnt(0)
	ds_swizzle_b32 v96, v246 offset:swizzle(SWAP,8)
	ds_swizzle_b32 v97, v247 offset:swizzle(SWAP,8)
	ds_swizzle_b32 v98, v248 offset:swizzle(SWAP,8)
	ds_swizzle_b32 v99, v249 offset:swizzle(SWAP,8)
	ds_swizzle_b32 v100, v236 offset:swizzle(SWAP,8)
	ds_swizzle_b32 v101, v237 offset:swizzle(SWAP,8)
	ds_swizzle_b32 v102, v238 offset:swizzle(SWAP,8)
	ds_swizzle_b32 v103, v239 offset:swizzle(SWAP,8)
	s_waitcnt lgkmcnt(0)
	v_cndmask_b32_e64 v100, v100, v246, s[98:99]
	v_cndmask_b32_e64 v101, v101, v247, s[98:99]
	v_cndmask_b32_e64 v102, v102, v248, s[98:99]
	v_cndmask_b32_e64 v103, v103, v249, s[98:99]
	v_cndmask_b32_e64 v96, v236, v96, s[98:99]
	v_cndmask_b32_e64 v97, v237, v97, s[98:99]
	v_cndmask_b32_e64 v98, v238, v98, s[98:99]
	v_cndmask_b32_e64 v99, v239, v99, s[98:99]
	v_pk_add_f32 v[90:91], v[90:91], v[98:99]
	s_waitcnt vmcnt(0)
	v_pk_add_f32 v[94:95], v[94:95], v[102:103]
	v_pk_add_f32 v[92:93], v[92:93], v[100:101]
	v_pk_add_f32 v[88:89], v[88:89], v[96:97]
	v_lshl_add_u64 v[228:229], v[104:105], 0, v[230:231]
	v_lshl_add_u64 v[232:233], v[104:105], 0, v[244:245]
	ds_swizzle_b32 v236, v88 offset:swizzle(SWAP,8)
	ds_swizzle_b32 v237, v89 offset:swizzle(SWAP,8)
	ds_swizzle_b32 v238, v90 offset:swizzle(SWAP,8)
	ds_swizzle_b32 v239, v91 offset:swizzle(SWAP,8)
	ds_swizzle_b32 v240, v92 offset:swizzle(SWAP,8)
	ds_swizzle_b32 v241, v93 offset:swizzle(SWAP,8)
	ds_swizzle_b32 v242, v94 offset:swizzle(SWAP,8)
	ds_swizzle_b32 v243, v95 offset:swizzle(SWAP,8)
	s_waitcnt lgkmcnt(0)
;     __device__ __forceinline__ void operator()(const f32x4 (&acc)[2][2][4][2], const Unit& u, int wr, int wc, int fr, int fq, const PG8_LAS float*) const {
;     ...
;             for (int m = 0; m < 4; ++m) { const int row = row0 + ai * HALF + m * 16; const size_t off = (size_t)row * ldc + col0; float ss = 0.f;
; #pragma unroll
;                 for (int bj = 0; bj < 2; ++bj) {
;                     const f32x4 b0 = *(const f32x4*)(base + off + bj * HALF), b1 = *(const f32x4*)(base + off + bj * HALF + 4);
;                     const f32x4 v0 = b0 + acc[ai][bj][m][0], v1 = b1 + acc[ai][bj][m][1];
;                     *(f32x4*)(out + off + bj * HALF) = v0; *(f32x4*)(out + off + bj * HALF + 4) = v1;
	v_cndmask_b32_e64 v236, v236, v92, s[98:99]
	v_cndmask_b32_e64 v237, v237, v93, s[98:99]
	v_cndmask_b32_e64 v238, v238, v94, s[98:99]
	v_cndmask_b32_e64 v239, v239, v95, s[98:99]
	v_cndmask_b32_e64 v240, v88, v240, s[98:99]
	v_cndmask_b32_e64 v241, v89, v241, s[98:99]
	v_cndmask_b32_e64 v242, v90, v242, s[98:99]
	v_cndmask_b32_e64 v243, v91, v243, s[98:99]
	global_store_dwordx4 v[228:229], v[236:239], off
	global_store_dwordx4 v[232:233], v[240:243], off
	v_lshl_add_u64 v[228:229], v[104:105], 0, v[230:231]
	v_lshl_add_u64 v[232:233], v[104:105], 0, v[244:245]
	global_load_dwordx4 v[246:249], v[228:229], off offset:512
	global_load_dwordx4 v[236:239], v[232:233], off offset:512
	s_nop 0
	s_waitcnt vmcnt(0)
	ds_swizzle_b32 v88, v246 offset:swizzle(SWAP,8)
	ds_swizzle_b32 v89, v247 offset:swizzle(SWAP,8)
	ds_swizzle_b32 v90, v248 offset:swizzle(SWAP,8)
	ds_swizzle_b32 v91, v249 offset:swizzle(SWAP,8)
	ds_swizzle_b32 v92, v236 offset:swizzle(SWAP,8)
	ds_swizzle_b32 v93, v237 offset:swizzle(SWAP,8)
	ds_swizzle_b32 v94, v238 offset:swizzle(SWAP,8)
	ds_swizzle_b32 v95, v239 offset:swizzle(SWAP,8)
	s_waitcnt lgkmcnt(0)
	v_cndmask_b32_e64 v92, v92, v246, s[98:99]
	v_cndmask_b32_e64 v93, v93, v247, s[98:99]
	v_cndmask_b32_e64 v94, v94, v248, s[98:99]
	v_cndmask_b32_e64 v95, v95, v249, s[98:99]
	v_cndmask_b32_e64 v88, v236, v88, s[98:99]
	v_cndmask_b32_e64 v89, v237, v89, s[98:99]
	v_cndmask_b32_e64 v90, v238, v90, s[98:99]
	v_cndmask_b32_e64 v91, v239, v91, s[98:99]
	v_pk_add_f32 v[80:81], v[80:81], v[88:89]
	s_waitcnt vmcnt(0)
	v_pk_add_f32 v[86:87], v[86:87], v[94:95]
	v_pk_add_f32 v[84:85], v[84:85], v[92:93]
	v_pk_add_f32 v[82:83], v[82:83], v[90:91]
	v_lshl_add_u64 v[228:229], v[104:105], 0, v[230:231]
	v_lshl_add_u64 v[232:233], v[104:105], 0, v[244:245]
	ds_swizzle_b32 v236, v80 offset:swizzle(SWAP,8)
	ds_swizzle_b32 v237, v81 offset:swizzle(SWAP,8)
	ds_swizzle_b32 v238, v82 offset:swizzle(SWAP,8)
	ds_swizzle_b32 v239, v83 offset:swizzle(SWAP,8)
	ds_swizzle_b32 v240, v84 offset:swizzle(SWAP,8)
	ds_swizzle_b32 v241, v85 offset:swizzle(SWAP,8)
	ds_swizzle_b32 v242, v86 offset:swizzle(SWAP,8)
	ds_swizzle_b32 v243, v87 offset:swizzle(SWAP,8)
	s_waitcnt lgkmcnt(0)
	v_cndmask_b32_e64 v236, v236, v84, s[98:99]
	v_cndmask_b32_e64 v237, v237, v85, s[98:99]
	v_cndmask_b32_e64 v238, v238, v86, s[98:99]
	v_cndmask_b32_e64 v239, v239, v87, s[98:99]
	v_cndmask_b32_e64 v240, v80, v240, s[98:99]
	v_cndmask_b32_e64 v241, v81, v241, s[98:99]
	v_cndmask_b32_e64 v242, v82, v242, s[98:99]
	v_cndmask_b32_e64 v243, v83, v243, s[98:99]
	global_store_dwordx4 v[228:229], v[236:239], off offset:512
	global_store_dwordx4 v[232:233], v[240:243], off offset:512
	s_nop 1
	v_or_b32_e32 v80, 48, v146
	v_ashrrev_i32_e32 v81, 31, v80
	v_lshlrev_b64 v[80:81], 12, v[80:81]
	v_lshl_add_u64 v[80:81], s[68:69], 0, v[80:81]
	v_lshl_add_u64 v[88:89], v[80:81], 0, v[148:149]
	v_lshl_add_u64 v[228:229], v[88:89], 0, v[230:231]
	v_lshl_add_u64 v[232:233], v[88:89], 0, v[244:245]
	global_load_dwordx4 v[246:249], v[228:229], off
	global_load_dwordx4 v[236:239], v[232:233], off
	s_waitcnt vmcnt(0)
	ds_swizzle_b32 v80, v246 offset:swizzle(SWAP,8)
	ds_swizzle_b32 v81, v247 offset:swizzle(SWAP,8)
	ds_swizzle_b32 v82, v248 offset:swizzle(SWAP,8)
	ds_swizzle_b32 v83, v249 offset:swizzle(SWAP,8)
	ds_swizzle_b32 v84, v236 offset:swizzle(SWAP,8)
	ds_swizzle_b32 v85, v237 offset:swizzle(SWAP,8)
	ds_swizzle_b32 v86, v238 offset:swizzle(SWAP,8)
	ds_swizzle_b32 v87, v239 offset:swizzle(SWAP,8)
	s_waitcnt lgkmcnt(0)
	v_cndmask_b32_e64 v84, v84, v246, s[98:99]
	v_cndmask_b32_e64 v85, v85, v247, s[98:99]
	v_cndmask_b32_e64 v86, v86, v248, s[98:99]
	v_cndmask_b32_e64 v87, v87, v249, s[98:99]
	v_cndmask_b32_e64 v80, v236, v80, s[98:99]
	v_cndmask_b32_e64 v81, v237, v81, s[98:99]
	v_cndmask_b32_e64 v82, v238, v82, s[98:99]
	v_cndmask_b32_e64 v83, v239, v83, s[98:99]
	v_pk_add_f32 v[74:75], v[74:75], v[82:83]
	s_waitcnt vmcnt(0)
	v_pk_add_f32 v[78:79], v[78:79], v[86:87]
	v_pk_add_f32 v[76:77], v[76:77], v[84:85]
	v_pk_add_f32 v[72:73], v[72:73], v[80:81]
	v_lshl_add_u64 v[228:229], v[88:89], 0, v[230:231]
	v_lshl_add_u64 v[232:233], v[88:89], 0, v[244:245]
	ds_swizzle_b32 v236, v72 offset:swizzle(SWAP,8)
	ds_swizzle_b32 v237, v73 offset:swizzle(SWAP,8)
	ds_swizzle_b32 v238, v74 offset:swizzle(SWAP,8)
	ds_swizzle_b32 v239, v75 offset:swizzle(SWAP,8)
	ds_swizzle_b32 v240, v76 offset:swizzle(SWAP,8)
	ds_swizzle_b32 v241, v77 offset:swizzle(SWAP,8)
	ds_swizzle_b32 v242, v78 offset:swizzle(SWAP,8)
	ds_swizzle_b32 v243, v79 offset:swizzle(SWAP,8)
	s_waitcnt lgkmcnt(0)
	v_cndmask_b32_e64 v236, v236, v76, s[98:99]
	v_cndmask_b32_e64 v237, v237, v77, s[98:99]
	v_cndmask_b32_e64 v238, v238, v78, s[98:99]
	v_cndmask_b32_e64 v239, v239, v79, s[98:99]
	v_cndmask_b32_e64 v240, v72, v240, s[98:99]
	v_cndmask_b32_e64 v241, v73, v241, s[98:99]
	v_cndmask_b32_e64 v242, v74, v242, s[98:99]
	v_cndmask_b32_e64 v243, v75, v243, s[98:99]
	global_store_dwordx4 v[228:229], v[236:239], off
	global_store_dwordx4 v[232:233], v[240:243], off
	v_lshl_add_u64 v[228:229], v[88:89], 0, v[230:231]
	v_lshl_add_u64 v[232:233], v[88:89], 0, v[244:245]
	global_load_dwordx4 v[246:249], v[228:229], off offset:512
	global_load_dwordx4 v[236:239], v[232:233], off offset:512
	s_nop 0
	s_waitcnt vmcnt(0)
	ds_swizzle_b32 v72, v246 offset:swizzle(SWAP,8)
	ds_swizzle_b32 v73, v247 offset:swizzle(SWAP,8)
	ds_swizzle_b32 v74, v248 offset:swizzle(SWAP,8)
	ds_swizzle_b32 v75, v249 offset:swizzle(SWAP,8)
	ds_swizzle_b32 v76, v236 offset:swizzle(SWAP,8)
	ds_swizzle_b32 v77, v237 offset:swizzle(SWAP,8)
	ds_swizzle_b32 v78, v238 offset:swizzle(SWAP,8)
	ds_swizzle_b32 v79, v239 offset:swizzle(SWAP,8)
	s_waitcnt lgkmcnt(0)
;     __device__ __forceinline__ void operator()(const f32x4 (&acc)[2][2][4][2], const Unit& u, int wr, int wc, int fr, int fq, const PG8_LAS float*) const {
;     ...
;             for (int m = 0; m < 4; ++m) { const int row = row0 + ai * HALF + m * 16; const size_t off = (size_t)row * ldc + col0; float ss = 0.f;
; #pragma unroll
;                 for (int bj = 0; bj < 2; ++bj) {
;                     const f32x4 b0 = *(const f32x4*)(base + off + bj * HALF), b1 = *(const f32x4*)(base + off + bj * HALF + 4);
;                     const f32x4 v0 = b0 + acc[ai][bj][m][0], v1 = b1 + acc[ai][bj][m][1];
;                     *(f32x4*)(out + off + bj * HALF) = v0; *(f32x4*)(out + off + bj * HALF + 4) = v1;
	v_cndmask_b32_e64 v76, v76, v246, s[98:99]
	v_cndmask_b32_e64 v77, v77, v247, s[98:99]
	v_cndmask_b32_e64 v78, v78, v248, s[98:99]
	v_cndmask_b32_e64 v79, v79, v249, s[98:99]
	v_cndmask_b32_e64 v72, v236, v72, s[98:99]
	v_cndmask_b32_e64 v73, v237, v73, s[98:99]
	v_cndmask_b32_e64 v74, v238, v74, s[98:99]
	v_cndmask_b32_e64 v75, v239, v75, s[98:99]
	v_pk_add_f32 v[66:67], v[66:67], v[74:75]
	s_waitcnt vmcnt(0)
	v_pk_add_f32 v[70:71], v[70:71], v[78:79]
	v_pk_add_f32 v[68:69], v[68:69], v[76:77]
	v_add_co_u32_e32 v74, vcc, s50, v144
	v_pk_add_f32 v[64:65], v[64:65], v[72:73]
	v_lshl_add_u64 v[228:229], v[88:89], 0, v[230:231]
	v_lshl_add_u64 v[232:233], v[88:89], 0, v[244:245]
	ds_swizzle_b32 v236, v64 offset:swizzle(SWAP,8)
	ds_swizzle_b32 v237, v65 offset:swizzle(SWAP,8)
	ds_swizzle_b32 v238, v66 offset:swizzle(SWAP,8)
	ds_swizzle_b32 v239, v67 offset:swizzle(SWAP,8)
	ds_swizzle_b32 v240, v68 offset:swizzle(SWAP,8)
	ds_swizzle_b32 v241, v69 offset:swizzle(SWAP,8)
	ds_swizzle_b32 v242, v70 offset:swizzle(SWAP,8)
	ds_swizzle_b32 v243, v71 offset:swizzle(SWAP,8)
	s_waitcnt lgkmcnt(0)
	v_cndmask_b32_e64 v236, v236, v68, s[98:99]
	v_cndmask_b32_e64 v237, v237, v69, s[98:99]
	v_cndmask_b32_e64 v238, v238, v70, s[98:99]
	v_cndmask_b32_e64 v239, v239, v71, s[98:99]
	v_cndmask_b32_e64 v240, v64, v240, s[98:99]
	v_cndmask_b32_e64 v241, v65, v241, s[98:99]
	v_cndmask_b32_e64 v242, v66, v242, s[98:99]
	v_cndmask_b32_e64 v243, v67, v243, s[98:99]
	global_store_dwordx4 v[228:229], v[236:239], off offset:512
	global_store_dwordx4 v[232:233], v[240:243], off offset:512
	v_addc_co_u32_e32 v75, vcc, 0, v145, vcc
	v_lshl_add_u64 v[72:73], v[144:145], 0, s[10:11]
	v_lshl_add_u64 v[228:229], v[74:75], 0, v[230:231]
	v_lshl_add_u64 v[232:233], v[72:73], 0, v[244:245]
	global_load_dwordx4 v[246:249], v[228:229], off
	global_load_dwordx4 v[236:239], v[232:233], off
	s_waitcnt vmcnt(0)
	ds_swizzle_b32 v68, v246 offset:swizzle(SWAP,8)
	ds_swizzle_b32 v69, v247 offset:swizzle(SWAP,8)
	ds_swizzle_b32 v70, v248 offset:swizzle(SWAP,8)
	ds_swizzle_b32 v71, v249 offset:swizzle(SWAP,8)
	ds_swizzle_b32 v64, v236 offset:swizzle(SWAP,8)
	ds_swizzle_b32 v65, v237 offset:swizzle(SWAP,8)
	ds_swizzle_b32 v66, v238 offset:swizzle(SWAP,8)
	ds_swizzle_b32 v67, v239 offset:swizzle(SWAP,8)
	s_waitcnt lgkmcnt(0)
	v_cndmask_b32_e64 v64, v64, v246, s[98:99]
	v_cndmask_b32_e64 v65, v65, v247, s[98:99]
	v_cndmask_b32_e64 v66, v66, v248, s[98:99]
	v_cndmask_b32_e64 v67, v67, v249, s[98:99]
	v_cndmask_b32_e64 v68, v236, v68, s[98:99]
	v_cndmask_b32_e64 v69, v237, v69, s[98:99]
	v_cndmask_b32_e64 v70, v238, v70, s[98:99]
	v_cndmask_b32_e64 v71, v239, v71, s[98:99]
	v_pk_add_f32 v[62:63], v[62:63], v[66:67]
	v_pk_add_f32 v[60:61], v[60:61], v[64:65]
	s_waitcnt vmcnt(0)
	v_pk_add_f32 v[58:59], v[58:59], v[70:71]
	v_pk_add_f32 v[56:57], v[56:57], v[68:69]
	v_lshl_add_u64 v[228:229], v[74:75], 0, v[230:231]
	v_lshl_add_u64 v[232:233], v[72:73], 0, v[244:245]
	ds_swizzle_b32 v236, v56 offset:swizzle(SWAP,8)
	ds_swizzle_b32 v237, v57 offset:swizzle(SWAP,8)
	ds_swizzle_b32 v238, v58 offset:swizzle(SWAP,8)
	ds_swizzle_b32 v239, v59 offset:swizzle(SWAP,8)
	ds_swizzle_b32 v240, v60 offset:swizzle(SWAP,8)
	ds_swizzle_b32 v241, v61 offset:swizzle(SWAP,8)
	ds_swizzle_b32 v242, v62 offset:swizzle(SWAP,8)
	ds_swizzle_b32 v243, v63 offset:swizzle(SWAP,8)
	s_waitcnt lgkmcnt(0)
	v_cndmask_b32_e64 v236, v236, v60, s[98:99]
	v_cndmask_b32_e64 v237, v237, v61, s[98:99]
	v_cndmask_b32_e64 v238, v238, v62, s[98:99]
	v_cndmask_b32_e64 v239, v239, v63, s[98:99]
	v_cndmask_b32_e64 v240, v56, v240, s[98:99]
	v_cndmask_b32_e64 v241, v57, v241, s[98:99]
	v_cndmask_b32_e64 v242, v58, v242, s[98:99]
	v_cndmask_b32_e64 v243, v59, v243, s[98:99]
	global_store_dwordx4 v[228:229], v[236:239], off
	global_store_dwordx4 v[232:233], v[240:243], off
	v_lshl_add_u64 v[228:229], v[72:73], 0, v[230:231]
	v_lshl_add_u64 v[232:233], v[72:73], 0, v[244:245]
	global_load_dwordx4 v[246:249], v[228:229], off offset:512
	global_load_dwordx4 v[236:239], v[232:233], off offset:512
	s_nop 0
	s_waitcnt vmcnt(0)
	ds_swizzle_b32 v56, v246 offset:swizzle(SWAP,8)
	ds_swizzle_b32 v57, v247 offset:swizzle(SWAP,8)
	ds_swizzle_b32 v58, v248 offset:swizzle(SWAP,8)
	ds_swizzle_b32 v59, v249 offset:swizzle(SWAP,8)
	ds_swizzle_b32 v60, v236 offset:swizzle(SWAP,8)
	ds_swizzle_b32 v61, v237 offset:swizzle(SWAP,8)
	ds_swizzle_b32 v62, v238 offset:swizzle(SWAP,8)
	ds_swizzle_b32 v63, v239 offset:swizzle(SWAP,8)
	s_waitcnt lgkmcnt(0)
	v_cndmask_b32_e64 v60, v60, v246, s[98:99]
	v_cndmask_b32_e64 v61, v61, v247, s[98:99]
	v_cndmask_b32_e64 v62, v62, v248, s[98:99]
	v_cndmask_b32_e64 v63, v63, v249, s[98:99]
	v_cndmask_b32_e64 v56, v236, v56, s[98:99]
	v_cndmask_b32_e64 v57, v237, v57, s[98:99]
	v_cndmask_b32_e64 v58, v238, v58, s[98:99]
	v_cndmask_b32_e64 v59, v239, v59, s[98:99]
	v_pk_add_f32 v[50:51], v[50:51], v[58:59]
	s_waitcnt vmcnt(0)
	v_pk_add_f32 v[54:55], v[54:55], v[62:63]
	v_pk_add_f32 v[52:53], v[52:53], v[60:61]
	v_add_co_u32_e32 v58, vcc, s51, v144
	v_pk_add_f32 v[48:49], v[48:49], v[56:57]
	v_lshl_add_u64 v[228:229], v[72:73], 0, v[230:231]
	v_lshl_add_u64 v[232:233], v[72:73], 0, v[244:245]
	ds_swizzle_b32 v236, v48 offset:swizzle(SWAP,8)
	ds_swizzle_b32 v237, v49 offset:swizzle(SWAP,8)
	ds_swizzle_b32 v238, v50 offset:swizzle(SWAP,8)
	ds_swizzle_b32 v239, v51 offset:swizzle(SWAP,8)
	ds_swizzle_b32 v240, v52 offset:swizzle(SWAP,8)
	ds_swizzle_b32 v241, v53 offset:swizzle(SWAP,8)
	ds_swizzle_b32 v242, v54 offset:swizzle(SWAP,8)
	ds_swizzle_b32 v243, v55 offset:swizzle(SWAP,8)
	s_waitcnt lgkmcnt(0)
;     __device__ __forceinline__ void operator()(const f32x4 (&acc)[2][2][4][2], const Unit& u, int wr, int wc, int fr, int fq, const PG8_LAS float*) const {
;     ...
;             for (int m = 0; m < 4; ++m) { const int row = row0 + ai * HALF + m * 16; const size_t off = (size_t)row * ldc + col0; float ss = 0.f;
; #pragma unroll
;                 for (int bj = 0; bj < 2; ++bj) {
;                     const f32x4 b0 = *(const f32x4*)(base + off + bj * HALF), b1 = *(const f32x4*)(base + off + bj * HALF + 4);
;                     const f32x4 v0 = b0 + acc[ai][bj][m][0], v1 = b1 + acc[ai][bj][m][1];
;                     *(f32x4*)(out + off + bj * HALF) = v0; *(f32x4*)(out + off + bj * HALF + 4) = v1;
	v_cndmask_b32_e64 v236, v236, v52, s[98:99]
	v_cndmask_b32_e64 v237, v237, v53, s[98:99]
	v_cndmask_b32_e64 v238, v238, v54, s[98:99]
	v_cndmask_b32_e64 v239, v239, v55, s[98:99]
	v_cndmask_b32_e64 v240, v48, v240, s[98:99]
	v_cndmask_b32_e64 v241, v49, v241, s[98:99]
	v_cndmask_b32_e64 v242, v50, v242, s[98:99]
	v_cndmask_b32_e64 v243, v51, v243, s[98:99]
	global_store_dwordx4 v[228:229], v[236:239], off offset:512
	global_store_dwordx4 v[232:233], v[240:243], off offset:512
	v_addc_co_u32_e32 v59, vcc, 0, v145, vcc
	v_lshl_add_u64 v[56:57], v[144:145], 0, s[12:13]
	v_lshl_add_u64 v[228:229], v[58:59], 0, v[230:231]
	v_lshl_add_u64 v[232:233], v[56:57], 0, v[244:245]
	global_load_dwordx4 v[246:249], v[228:229], off
	global_load_dwordx4 v[236:239], v[232:233], off
	s_waitcnt vmcnt(0)
	ds_swizzle_b32 v52, v246 offset:swizzle(SWAP,8)
	ds_swizzle_b32 v53, v247 offset:swizzle(SWAP,8)
	ds_swizzle_b32 v54, v248 offset:swizzle(SWAP,8)
	ds_swizzle_b32 v55, v249 offset:swizzle(SWAP,8)
	ds_swizzle_b32 v48, v236 offset:swizzle(SWAP,8)
	ds_swizzle_b32 v49, v237 offset:swizzle(SWAP,8)
	ds_swizzle_b32 v50, v238 offset:swizzle(SWAP,8)
	ds_swizzle_b32 v51, v239 offset:swizzle(SWAP,8)
	s_waitcnt lgkmcnt(0)
	v_cndmask_b32_e64 v48, v48, v246, s[98:99]
	v_cndmask_b32_e64 v49, v49, v247, s[98:99]
	v_cndmask_b32_e64 v50, v50, v248, s[98:99]
	v_cndmask_b32_e64 v51, v51, v249, s[98:99]
	v_cndmask_b32_e64 v52, v236, v52, s[98:99]
	v_cndmask_b32_e64 v53, v237, v53, s[98:99]
	v_cndmask_b32_e64 v54, v238, v54, s[98:99]
	v_cndmask_b32_e64 v55, v239, v55, s[98:99]
	v_pk_add_f32 v[46:47], v[46:47], v[50:51]
	v_pk_add_f32 v[44:45], v[44:45], v[48:49]
	s_waitcnt vmcnt(0)
	v_pk_add_f32 v[42:43], v[42:43], v[54:55]
	v_pk_add_f32 v[40:41], v[40:41], v[52:53]
	v_lshl_add_u64 v[228:229], v[58:59], 0, v[230:231]
	v_lshl_add_u64 v[232:233], v[56:57], 0, v[244:245]
	ds_swizzle_b32 v236, v40 offset:swizzle(SWAP,8)
	ds_swizzle_b32 v237, v41 offset:swizzle(SWAP,8)
	ds_swizzle_b32 v238, v42 offset:swizzle(SWAP,8)
	ds_swizzle_b32 v239, v43 offset:swizzle(SWAP,8)
	ds_swizzle_b32 v240, v44 offset:swizzle(SWAP,8)
	ds_swizzle_b32 v241, v45 offset:swizzle(SWAP,8)
	ds_swizzle_b32 v242, v46 offset:swizzle(SWAP,8)
	ds_swizzle_b32 v243, v47 offset:swizzle(SWAP,8)
	s_waitcnt lgkmcnt(0)
	v_cndmask_b32_e64 v236, v236, v44, s[98:99]
	v_cndmask_b32_e64 v237, v237, v45, s[98:99]
	v_cndmask_b32_e64 v238, v238, v46, s[98:99]
	v_cndmask_b32_e64 v239, v239, v47, s[98:99]
	v_cndmask_b32_e64 v240, v40, v240, s[98:99]
	v_cndmask_b32_e64 v241, v41, v241, s[98:99]
	v_cndmask_b32_e64 v242, v42, v242, s[98:99]
	v_cndmask_b32_e64 v243, v43, v243, s[98:99]
	global_store_dwordx4 v[228:229], v[236:239], off
	global_store_dwordx4 v[232:233], v[240:243], off
	v_lshl_add_u64 v[228:229], v[56:57], 0, v[230:231]
	v_lshl_add_u64 v[232:233], v[56:57], 0, v[244:245]
	global_load_dwordx4 v[246:249], v[228:229], off offset:512
	global_load_dwordx4 v[236:239], v[232:233], off offset:512
	s_nop 0
	s_waitcnt vmcnt(0)
	ds_swizzle_b32 v40, v246 offset:swizzle(SWAP,8)
	ds_swizzle_b32 v41, v247 offset:swizzle(SWAP,8)
	ds_swizzle_b32 v42, v248 offset:swizzle(SWAP,8)
	ds_swizzle_b32 v43, v249 offset:swizzle(SWAP,8)
	ds_swizzle_b32 v44, v236 offset:swizzle(SWAP,8)
	ds_swizzle_b32 v45, v237 offset:swizzle(SWAP,8)
	ds_swizzle_b32 v46, v238 offset:swizzle(SWAP,8)
	ds_swizzle_b32 v47, v239 offset:swizzle(SWAP,8)
	s_waitcnt lgkmcnt(0)
	v_cndmask_b32_e64 v44, v44, v246, s[98:99]
	v_cndmask_b32_e64 v45, v45, v247, s[98:99]
	v_cndmask_b32_e64 v46, v46, v248, s[98:99]
	v_cndmask_b32_e64 v47, v47, v249, s[98:99]
	v_cndmask_b32_e64 v40, v236, v40, s[98:99]
	v_cndmask_b32_e64 v41, v237, v41, s[98:99]
	v_cndmask_b32_e64 v42, v238, v42, s[98:99]
	v_cndmask_b32_e64 v43, v239, v43, s[98:99]
	v_pk_add_f32 v[34:35], v[34:35], v[42:43]
	s_waitcnt vmcnt(0)
	v_pk_add_f32 v[38:39], v[38:39], v[46:47]
	v_pk_add_f32 v[36:37], v[36:37], v[44:45]
	v_add_co_u32_e32 v42, vcc, s52, v144
	v_pk_add_f32 v[32:33], v[32:33], v[40:41]
	v_lshl_add_u64 v[228:229], v[56:57], 0, v[230:231]
	v_lshl_add_u64 v[232:233], v[56:57], 0, v[244:245]
	ds_swizzle_b32 v236, v32 offset:swizzle(SWAP,8)
	ds_swizzle_b32 v237, v33 offset:swizzle(SWAP,8)
	ds_swizzle_b32 v238, v34 offset:swizzle(SWAP,8)
	ds_swizzle_b32 v239, v35 offset:swizzle(SWAP,8)
	ds_swizzle_b32 v240, v36 offset:swizzle(SWAP,8)
	ds_swizzle_b32 v241, v37 offset:swizzle(SWAP,8)
	ds_swizzle_b32 v242, v38 offset:swizzle(SWAP,8)
	ds_swizzle_b32 v243, v39 offset:swizzle(SWAP,8)
	s_waitcnt lgkmcnt(0)
	v_cndmask_b32_e64 v236, v236, v36, s[98:99]
	v_cndmask_b32_e64 v237, v237, v37, s[98:99]
	v_cndmask_b32_e64 v238, v238, v38, s[98:99]
	v_cndmask_b32_e64 v239, v239, v39, s[98:99]
	v_cndmask_b32_e64 v240, v32, v240, s[98:99]
	v_cndmask_b32_e64 v241, v33, v241, s[98:99]
	v_cndmask_b32_e64 v242, v34, v242, s[98:99]
	v_cndmask_b32_e64 v243, v35, v243, s[98:99]
	global_store_dwordx4 v[228:229], v[236:239], off offset:512
	global_store_dwordx4 v[232:233], v[240:243], off offset:512
	v_addc_co_u32_e32 v43, vcc, 0, v145, vcc
	v_lshl_add_u64 v[40:41], v[144:145], 0, s[14:15]
	v_lshl_add_u64 v[228:229], v[42:43], 0, v[230:231]
	v_lshl_add_u64 v[232:233], v[40:41], 0, v[244:245]
	global_load_dwordx4 v[246:249], v[228:229], off
	global_load_dwordx4 v[236:239], v[232:233], off
	s_waitcnt vmcnt(0)
	ds_swizzle_b32 v36, v246 offset:swizzle(SWAP,8)
	ds_swizzle_b32 v37, v247 offset:swizzle(SWAP,8)
	ds_swizzle_b32 v38, v248 offset:swizzle(SWAP,8)
	ds_swizzle_b32 v39, v249 offset:swizzle(SWAP,8)
	ds_swizzle_b32 v32, v236 offset:swizzle(SWAP,8)
	ds_swizzle_b32 v33, v237 offset:swizzle(SWAP,8)
	ds_swizzle_b32 v34, v238 offset:swizzle(SWAP,8)
	ds_swizzle_b32 v35, v239 offset:swizzle(SWAP,8)
	s_waitcnt lgkmcnt(0)
;     __device__ __forceinline__ void operator()(const f32x4 (&acc)[2][2][4][2], const Unit& u, int wr, int wc, int fr, int fq, const PG8_LAS float*) const {
;     ...
;             for (int m = 0; m < 4; ++m) { const int row = row0 + ai * HALF + m * 16; const size_t off = (size_t)row * ldc + col0; float ss = 0.f;
; #pragma unroll
;                 for (int bj = 0; bj < 2; ++bj) {
;                     const f32x4 b0 = *(const f32x4*)(base + off + bj * HALF), b1 = *(const f32x4*)(base + off + bj * HALF + 4);
;                     const f32x4 v0 = b0 + acc[ai][bj][m][0], v1 = b1 + acc[ai][bj][m][1];
;                     *(f32x4*)(out + off + bj * HALF) = v0; *(f32x4*)(out + off + bj * HALF + 4) = v1;
	v_cndmask_b32_e64 v32, v32, v246, s[98:99]
	v_cndmask_b32_e64 v33, v33, v247, s[98:99]
	v_cndmask_b32_e64 v34, v34, v248, s[98:99]
	v_cndmask_b32_e64 v35, v35, v249, s[98:99]
	v_cndmask_b32_e64 v36, v236, v36, s[98:99]
	v_cndmask_b32_e64 v37, v237, v37, s[98:99]
	v_cndmask_b32_e64 v38, v238, v38, s[98:99]
	v_cndmask_b32_e64 v39, v239, v39, s[98:99]
	v_pk_add_f32 v[30:31], v[30:31], v[34:35]
	v_pk_add_f32 v[28:29], v[28:29], v[32:33]
	s_waitcnt vmcnt(0)
	v_pk_add_f32 v[26:27], v[26:27], v[38:39]
	v_pk_add_f32 v[24:25], v[24:25], v[36:37]
	v_lshl_add_u64 v[228:229], v[42:43], 0, v[230:231]
	v_lshl_add_u64 v[232:233], v[40:41], 0, v[244:245]
	ds_swizzle_b32 v236, v24 offset:swizzle(SWAP,8)
	ds_swizzle_b32 v237, v25 offset:swizzle(SWAP,8)
	ds_swizzle_b32 v238, v26 offset:swizzle(SWAP,8)
	ds_swizzle_b32 v239, v27 offset:swizzle(SWAP,8)
	ds_swizzle_b32 v240, v28 offset:swizzle(SWAP,8)
	ds_swizzle_b32 v241, v29 offset:swizzle(SWAP,8)
	ds_swizzle_b32 v242, v30 offset:swizzle(SWAP,8)
	ds_swizzle_b32 v243, v31 offset:swizzle(SWAP,8)
	s_waitcnt lgkmcnt(0)
	v_cndmask_b32_e64 v236, v236, v28, s[98:99]
	v_cndmask_b32_e64 v237, v237, v29, s[98:99]
	v_cndmask_b32_e64 v238, v238, v30, s[98:99]
	v_cndmask_b32_e64 v239, v239, v31, s[98:99]
	v_cndmask_b32_e64 v240, v24, v240, s[98:99]
	v_cndmask_b32_e64 v241, v25, v241, s[98:99]
	v_cndmask_b32_e64 v242, v26, v242, s[98:99]
	v_cndmask_b32_e64 v243, v27, v243, s[98:99]
	global_store_dwordx4 v[228:229], v[236:239], off
	global_store_dwordx4 v[232:233], v[240:243], off
	v_lshl_add_u64 v[228:229], v[40:41], 0, v[230:231]
	v_lshl_add_u64 v[232:233], v[40:41], 0, v[244:245]
	global_load_dwordx4 v[246:249], v[228:229], off offset:512
	global_load_dwordx4 v[236:239], v[232:233], off offset:512
	s_nop 0
	s_waitcnt vmcnt(0)
	ds_swizzle_b32 v24, v246 offset:swizzle(SWAP,8)
	ds_swizzle_b32 v25, v247 offset:swizzle(SWAP,8)
	ds_swizzle_b32 v26, v248 offset:swizzle(SWAP,8)
	ds_swizzle_b32 v27, v249 offset:swizzle(SWAP,8)
	ds_swizzle_b32 v28, v236 offset:swizzle(SWAP,8)
	ds_swizzle_b32 v29, v237 offset:swizzle(SWAP,8)
	ds_swizzle_b32 v30, v238 offset:swizzle(SWAP,8)
	ds_swizzle_b32 v31, v239 offset:swizzle(SWAP,8)
	s_waitcnt lgkmcnt(0)
	v_cndmask_b32_e64 v28, v28, v246, s[98:99]
	v_cndmask_b32_e64 v29, v29, v247, s[98:99]
	v_cndmask_b32_e64 v30, v30, v248, s[98:99]
	v_cndmask_b32_e64 v31, v31, v249, s[98:99]
	v_cndmask_b32_e64 v24, v236, v24, s[98:99]
	v_cndmask_b32_e64 v25, v237, v25, s[98:99]
	v_cndmask_b32_e64 v26, v238, v26, s[98:99]
	v_cndmask_b32_e64 v27, v239, v27, s[98:99]
	v_pk_add_f32 v[18:19], v[18:19], v[26:27]
	s_waitcnt vmcnt(0)
	v_pk_add_f32 v[22:23], v[22:23], v[30:31]
	v_pk_add_f32 v[20:21], v[20:21], v[28:29]
	v_add_co_u32_e32 v26, vcc, s53, v144
	v_pk_add_f32 v[16:17], v[16:17], v[24:25]
	v_lshl_add_u64 v[228:229], v[40:41], 0, v[230:231]
	v_lshl_add_u64 v[232:233], v[40:41], 0, v[244:245]
	ds_swizzle_b32 v236, v16 offset:swizzle(SWAP,8)
	ds_swizzle_b32 v237, v17 offset:swizzle(SWAP,8)
	ds_swizzle_b32 v238, v18 offset:swizzle(SWAP,8)
	ds_swizzle_b32 v239, v19 offset:swizzle(SWAP,8)
	ds_swizzle_b32 v240, v20 offset:swizzle(SWAP,8)
	ds_swizzle_b32 v241, v21 offset:swizzle(SWAP,8)
	ds_swizzle_b32 v242, v22 offset:swizzle(SWAP,8)
	ds_swizzle_b32 v243, v23 offset:swizzle(SWAP,8)
	s_waitcnt lgkmcnt(0)
	v_cndmask_b32_e64 v236, v236, v20, s[98:99]
	v_cndmask_b32_e64 v237, v237, v21, s[98:99]
	v_cndmask_b32_e64 v238, v238, v22, s[98:99]
	v_cndmask_b32_e64 v239, v239, v23, s[98:99]
	v_cndmask_b32_e64 v240, v16, v240, s[98:99]
	v_cndmask_b32_e64 v241, v17, v241, s[98:99]
	v_cndmask_b32_e64 v242, v18, v242, s[98:99]
	v_cndmask_b32_e64 v243, v19, v243, s[98:99]
	global_store_dwordx4 v[228:229], v[236:239], off offset:512
	global_store_dwordx4 v[232:233], v[240:243], off offset:512
	v_addc_co_u32_e32 v27, vcc, 0, v145, vcc
	s_nop 0
	v_lshl_add_u64 v[16:17], v[144:145], 0, s[16:17]
	v_lshl_add_u64 v[228:229], v[26:27], 0, v[230:231]
	v_lshl_add_u64 v[232:233], v[16:17], 0, v[244:245]
	global_load_dwordx4 v[246:249], v[228:229], off
	global_load_dwordx4 v[236:239], v[232:233], off
	s_andn2_b64 vcc, exec, s[2:3]
	s_waitcnt vmcnt(0)
; #define PG8_BAR __builtin_amdgcn_s_barrier()
;     __device__ __forceinline__ void operator()(const f32x4 (&acc)[2][2][4][2], const Unit& u, int wr, int wc, int fr, int fq, const PG8_LAS float*) const {
;     ...
;             for (int m = 0; m < 4; ++m) { const int row = row0 + ai * HALF + m * 16; const size_t off = (size_t)row * ldc + col0; float ss = 0.f;
; #pragma unroll
;                 for (int bj = 0; bj < 2; ++bj) {
;                     const f32x4 b0 = *(const f32x4*)(base + off + bj * HALF), b1 = *(const f32x4*)(base + off + bj * HALF + 4);
;                     const f32x4 v0 = b0 + acc[ai][bj][m][0], v1 = b1 + acc[ai][bj][m][1];
;                     *(f32x4*)(out + off + bj * HALF) = v0; *(f32x4*)(out + off + bj * HALF + 4) = v1;
; template <class Epi, class Sched, bool ALIGN_EPI = false, bool SP2 = false>
; __device__ __forceinline__ void gemm_phase(PG8_LAS unsigned char* lds, const Gemm g, const Sched& S, const Epi& E) {
;     ...
;         if (!has_next) break;
; #pragma unroll
;         for (int a = 0; a < 2; ++a)
; #pragma unroll
;             for (int b = 0; b < 2; ++b)
; #pragma unroll
;                 for (int m = 0; m < 4; ++m)
; #pragma unroll
;                     for (int n = 0; n < 2; ++n) acc[a][b][m][n] = (f32x4){0.f, 0.f, 0.f, 0.f};
;         cur = nxt; cA = nA; cB = nB; ++ui;
;         if constexpr (ALIGN_EPI) { if (wr == 1) PG8_BAR; }
	ds_swizzle_b32 v22, v246 offset:swizzle(SWAP,8)
	ds_swizzle_b32 v23, v247 offset:swizzle(SWAP,8)
	ds_swizzle_b32 v24, v248 offset:swizzle(SWAP,8)
	ds_swizzle_b32 v25, v249 offset:swizzle(SWAP,8)
	ds_swizzle_b32 v18, v236 offset:swizzle(SWAP,8)
	ds_swizzle_b32 v19, v237 offset:swizzle(SWAP,8)
	ds_swizzle_b32 v20, v238 offset:swizzle(SWAP,8)
	ds_swizzle_b32 v21, v239 offset:swizzle(SWAP,8)
	s_waitcnt lgkmcnt(0)
	v_cndmask_b32_e64 v18, v18, v246, s[98:99]
	v_cndmask_b32_e64 v19, v19, v247, s[98:99]
	v_cndmask_b32_e64 v20, v20, v248, s[98:99]
	v_cndmask_b32_e64 v21, v21, v249, s[98:99]
	v_cndmask_b32_e64 v22, v236, v22, s[98:99]
	v_cndmask_b32_e64 v23, v237, v23, s[98:99]
	v_cndmask_b32_e64 v24, v238, v24, s[98:99]
	v_cndmask_b32_e64 v25, v239, v25, s[98:99]
	v_pk_add_f32 v[14:15], v[14:15], v[20:21]
	v_pk_add_f32 v[12:13], v[12:13], v[18:19]
	s_waitcnt vmcnt(0)
	v_pk_add_f32 v[10:11], v[10:11], v[24:25]
	v_pk_add_f32 v[8:9], v[8:9], v[22:23]
	v_lshl_add_u64 v[228:229], v[26:27], 0, v[230:231]
	v_lshl_add_u64 v[232:233], v[16:17], 0, v[244:245]
	ds_swizzle_b32 v236, v8 offset:swizzle(SWAP,8)
	ds_swizzle_b32 v237, v9 offset:swizzle(SWAP,8)
	ds_swizzle_b32 v238, v10 offset:swizzle(SWAP,8)
	ds_swizzle_b32 v239, v11 offset:swizzle(SWAP,8)
	ds_swizzle_b32 v240, v12 offset:swizzle(SWAP,8)
	ds_swizzle_b32 v241, v13 offset:swizzle(SWAP,8)
	ds_swizzle_b32 v242, v14 offset:swizzle(SWAP,8)
	ds_swizzle_b32 v243, v15 offset:swizzle(SWAP,8)
	s_waitcnt lgkmcnt(0)
	v_cndmask_b32_e64 v236, v236, v12, s[98:99]
	v_cndmask_b32_e64 v237, v237, v13, s[98:99]
	v_cndmask_b32_e64 v238, v238, v14, s[98:99]
	v_cndmask_b32_e64 v239, v239, v15, s[98:99]
	v_cndmask_b32_e64 v240, v8, v240, s[98:99]
	v_cndmask_b32_e64 v241, v9, v241, s[98:99]
	v_cndmask_b32_e64 v242, v10, v242, s[98:99]
	v_cndmask_b32_e64 v243, v11, v243, s[98:99]
	global_store_dwordx4 v[228:229], v[236:239], off
	global_store_dwordx4 v[232:233], v[240:243], off
	v_lshl_add_u64 v[228:229], v[16:17], 0, v[230:231]
	v_lshl_add_u64 v[232:233], v[16:17], 0, v[244:245]
	global_load_dwordx4 v[246:249], v[228:229], off offset:512
	global_load_dwordx4 v[236:239], v[232:233], off offset:512
	s_nop 0
	s_waitcnt vmcnt(0)
	ds_swizzle_b32 v8, v246 offset:swizzle(SWAP,8)
	ds_swizzle_b32 v9, v247 offset:swizzle(SWAP,8)
	ds_swizzle_b32 v10, v248 offset:swizzle(SWAP,8)
	ds_swizzle_b32 v11, v249 offset:swizzle(SWAP,8)
	ds_swizzle_b32 v12, v236 offset:swizzle(SWAP,8)
	ds_swizzle_b32 v13, v237 offset:swizzle(SWAP,8)
	ds_swizzle_b32 v14, v238 offset:swizzle(SWAP,8)
	ds_swizzle_b32 v15, v239 offset:swizzle(SWAP,8)
	s_waitcnt lgkmcnt(0)
	v_cndmask_b32_e64 v12, v12, v246, s[98:99]
	v_cndmask_b32_e64 v13, v13, v247, s[98:99]
	v_cndmask_b32_e64 v14, v14, v248, s[98:99]
	v_cndmask_b32_e64 v15, v15, v249, s[98:99]
	v_cndmask_b32_e64 v8, v236, v8, s[98:99]
	v_cndmask_b32_e64 v9, v237, v9, s[98:99]
	v_cndmask_b32_e64 v10, v238, v10, s[98:99]
	v_cndmask_b32_e64 v11, v239, v11, s[98:99]
	v_pk_add_f32 v[2:3], v[2:3], v[10:11]
	s_waitcnt vmcnt(0)
	v_pk_add_f32 v[6:7], v[6:7], v[14:15]
	v_pk_add_f32 v[4:5], v[4:5], v[12:13]
	v_pk_add_f32 v[0:1], v[0:1], v[8:9]
	v_lshl_add_u64 v[228:229], v[16:17], 0, v[230:231]
	v_lshl_add_u64 v[232:233], v[16:17], 0, v[244:245]
	ds_swizzle_b32 v236, v0 offset:swizzle(SWAP,8)
	ds_swizzle_b32 v237, v1 offset:swizzle(SWAP,8)
	ds_swizzle_b32 v238, v2 offset:swizzle(SWAP,8)
	ds_swizzle_b32 v239, v3 offset:swizzle(SWAP,8)
	ds_swizzle_b32 v240, v4 offset:swizzle(SWAP,8)
	ds_swizzle_b32 v241, v5 offset:swizzle(SWAP,8)
	ds_swizzle_b32 v242, v6 offset:swizzle(SWAP,8)
	ds_swizzle_b32 v243, v7 offset:swizzle(SWAP,8)
	s_waitcnt lgkmcnt(0)
	v_cndmask_b32_e64 v236, v236, v4, s[98:99]
	v_cndmask_b32_e64 v237, v237, v5, s[98:99]
	v_cndmask_b32_e64 v238, v238, v6, s[98:99]
	v_cndmask_b32_e64 v239, v239, v7, s[98:99]
	v_cndmask_b32_e64 v240, v0, v240, s[98:99]
	v_cndmask_b32_e64 v241, v1, v241, s[98:99]
	v_cndmask_b32_e64 v242, v2, v242, s[98:99]
	v_cndmask_b32_e64 v243, v3, v243, s[98:99]
	global_store_dwordx4 v[228:229], v[236:239], off offset:512
	global_store_dwordx4 v[232:233], v[240:243], off offset:512
	s_cbranch_vccnz .LBB0_1633
	s_andn2_b64 vcc, exec, s[4:5]
	s_cbranch_vccnz .LBB0_1632
	s_barrier
	s_branch .LBB0_1632
